# hoisted loop-invariant LDS/global address math out of 10 GEMM K-loops into spare VGPRs (tool-generated), DCE of dead VALU
# speedup vs baseline: 1.0839x; 1.0839x over previous
.LBB0_281:
	v_mov_b32_e32 v255, 0x8000
	v_bfe_u32 v1, v0, 1, 3
	v_lshlrev_b32_e32 v1, 8, v1
	v_add_u32_e32 v255, v255, v1
	v_bfe_u32 v1, v0, 6, 2
	v_mul_u32_u24_e32 v1, 0x1800, v1
	v_add_u32_e32 v255, v255, v1
	v_mov_b32_e32 v2, 0x0
	v_bfe_u32 v1, v0, 0, 1
	v_lshlrev_b32_e32 v1, 7, v1
	v_xor_b32_e32 v2, v2, v1
	v_bfe_u32 v1, v0, 1, 3
	v_lshlrev_b32_e32 v1, 4, v1
	v_xor_b32_e32 v2, v2, v1
	v_bfe_u32 v1, v0, 4, 2
	v_lshlrev_b32_e32 v1, 4, v1
	v_xor_b32_e32 v2, v2, v1
	v_bfe_u32 v1, v0, 6, 1
	v_lshlrev_b32_e32 v1, 7, v1
	v_xor_b32_e32 v2, v2, v1
	v_add_u32_e32 v255, v255, v2
	v_mov_b32_e32 v254, 0x8800
	v_bfe_u32 v1, v0, 1, 3
	v_lshlrev_b32_e32 v1, 8, v1
	v_add_u32_e32 v254, v254, v1
	v_bfe_u32 v1, v0, 6, 2
	v_mul_u32_u24_e32 v1, 0x1800, v1
	v_add_u32_e32 v254, v254, v1
	v_mov_b32_e32 v2, 0x80
	v_bfe_u32 v1, v0, 0, 1
	v_lshlrev_b32_e32 v1, 7, v1
	v_xor_b32_e32 v2, v2, v1
	v_bfe_u32 v1, v0, 1, 3
	v_lshlrev_b32_e32 v1, 4, v1
	v_xor_b32_e32 v2, v2, v1
	v_bfe_u32 v1, v0, 4, 2
	v_lshlrev_b32_e32 v1, 4, v1
	v_xor_b32_e32 v2, v2, v1
	v_bfe_u32 v1, v0, 6, 1
	v_lshlrev_b32_e32 v1, 7, v1
	v_xor_b32_e32 v2, v2, v1
	v_add_u32_e32 v254, v254, v2
	v_mov_b32_e32 v253, 0x0
	v_bfe_u32 v1, v0, 0, 1
	v_lshlrev_b32_e32 v1, 7, v1
	v_xor_b32_e32 v253, v253, v1
	v_bfe_u32 v1, v0, 1, 3
	v_mul_u32_u24_e32 v1, 0x110, v1
	v_xor_b32_e32 v253, v253, v1
	v_bfe_u32 v1, v0, 4, 2
	v_lshlrev_b32_e32 v1, 4, v1
	v_xor_b32_e32 v253, v253, v1
	v_bfe_u32 v1, v0, 8, 1
	v_lshlrev_b32_e32 v1, 14, v1
	v_xor_b32_e32 v253, v253, v1
	v_mov_b32_e32 v252, 0x880
	v_bfe_u32 v1, v0, 0, 1
	v_lshlrev_b32_e32 v1, 7, v1
	v_xor_b32_e32 v252, v252, v1
	v_bfe_u32 v1, v0, 1, 3
	v_mul_u32_u24_e32 v1, 0x110, v1
	v_xor_b32_e32 v252, v252, v1
	v_bfe_u32 v1, v0, 4, 2
	v_lshlrev_b32_e32 v1, 4, v1
	v_xor_b32_e32 v252, v252, v1
	v_bfe_u32 v1, v0, 8, 1
	v_lshlrev_b32_e32 v1, 14, v1
	v_xor_b32_e32 v252, v252, v1
	v_mov_b32_e32 v251, 0x0
	v_bfe_u32 v1, v0, 0, 4
	v_lshlrev_b32_e32 v1, 4, v1
	v_xor_b32_e32 v251, v251, v1
	v_bfe_u32 v1, v0, 4, 4
	v_mul_u32_u24_e32 v1, 0x110, v1
	v_xor_b32_e32 v251, v251, v1
	v_bfe_u32 v1, v0, 8, 1
	v_lshlrev_b32_e32 v1, 12, v1
	v_xor_b32_e32 v251, v251, v1
	v_mov_b32_e32 v250, 0x8800
	v_bfe_u32 v1, v0, 1, 3
	v_lshlrev_b32_e32 v1, 8, v1
	v_add_u32_e32 v250, v250, v1
	v_bfe_u32 v1, v0, 6, 2
	v_mul_u32_u24_e32 v1, 0x1800, v1
	v_add_u32_e32 v250, v250, v1
	v_mov_b32_e32 v2, 0xc0
	v_bfe_u32 v1, v0, 0, 1
	v_lshlrev_b32_e32 v1, 7, v1
	v_xor_b32_e32 v2, v2, v1
	v_bfe_u32 v1, v0, 1, 3
	v_lshlrev_b32_e32 v1, 4, v1
	v_xor_b32_e32 v2, v2, v1
	v_bfe_u32 v1, v0, 4, 2
	v_lshlrev_b32_e32 v1, 4, v1
	v_xor_b32_e32 v2, v2, v1
	v_bfe_u32 v1, v0, 6, 1
	v_lshlrev_b32_e32 v1, 7, v1
	v_xor_b32_e32 v2, v2, v1
	v_add_u32_e32 v250, v250, v2
	v_mov_b32_e32 v249, 0x8000
	v_bfe_u32 v1, v0, 1, 3
	v_lshlrev_b32_e32 v1, 8, v1
	v_add_u32_e32 v249, v249, v1
	v_bfe_u32 v1, v0, 6, 2
	v_mul_u32_u24_e32 v1, 0x1800, v1
	v_add_u32_e32 v249, v249, v1
	v_mov_b32_e32 v2, 0x40
	v_bfe_u32 v1, v0, 0, 1
	v_lshlrev_b32_e32 v1, 7, v1
	v_xor_b32_e32 v2, v2, v1
	v_bfe_u32 v1, v0, 1, 3
	v_lshlrev_b32_e32 v1, 4, v1
	v_xor_b32_e32 v2, v2, v1
	v_bfe_u32 v1, v0, 4, 2
	v_lshlrev_b32_e32 v1, 4, v1
	v_xor_b32_e32 v2, v2, v1
	v_bfe_u32 v1, v0, 6, 1
	v_lshlrev_b32_e32 v1, 7, v1
	v_xor_b32_e32 v2, v2, v1
	v_add_u32_e32 v249, v249, v2
	v_mov_b32_e32 v248, 0x8c0
	v_bfe_u32 v1, v0, 0, 1
	v_lshlrev_b32_e32 v1, 7, v1
	v_xor_b32_e32 v248, v248, v1
	v_bfe_u32 v1, v0, 1, 3
	v_mul_u32_u24_e32 v1, 0x110, v1
	v_xor_b32_e32 v248, v248, v1
	v_bfe_u32 v1, v0, 4, 2
	v_lshlrev_b32_e32 v1, 4, v1
	v_xor_b32_e32 v248, v248, v1
	v_bfe_u32 v1, v0, 8, 1
	v_lshlrev_b32_e32 v1, 14, v1
	v_xor_b32_e32 v248, v248, v1
	v_mov_b32_e32 v247, 0x40
	v_bfe_u32 v1, v0, 0, 1
	v_lshlrev_b32_e32 v1, 7, v1
	v_xor_b32_e32 v247, v247, v1
	v_bfe_u32 v1, v0, 1, 3
	v_mul_u32_u24_e32 v1, 0x110, v1
	v_xor_b32_e32 v247, v247, v1
	v_bfe_u32 v1, v0, 4, 2
	v_lshlrev_b32_e32 v1, 4, v1
	v_xor_b32_e32 v247, v247, v1
	v_bfe_u32 v1, v0, 8, 1
	v_lshlrev_b32_e32 v1, 14, v1
	v_xor_b32_e32 v247, v247, v1
	v_mov_b32_e32 v246, 0x0
	v_bfe_u32 v1, v0, 0, 3
	v_lshlrev_b32_e32 v1, 4, v1
	v_add_u32_e32 v246, v246, v1
	v_bfe_u32 v1, v0, 3, 6
	v_lshlrev_b32_e32 v1, 11, v1
	v_add_u32_e32 v246, v246, v1
	v_mov_b32_e32 v245, 0x10000
	v_bfe_u32 v1, v0, 0, 4
	v_lshlrev_b32_e32 v1, 4, v1
	v_xor_b32_e32 v245, v245, v1
	v_bfe_u32 v1, v0, 4, 4
	v_mul_u32_u24_e32 v1, 0x110, v1
	v_xor_b32_e32 v245, v245, v1
	v_bfe_u32 v1, v0, 8, 1
	v_lshlrev_b32_e32 v1, 12, v1
	v_xor_b32_e32 v245, v245, v1
	v_mov_b32_e32 v244, 0x20000
	v_bfe_u32 v1, v0, 0, 3
	v_lshlrev_b32_e32 v1, 4, v1
	v_add_u32_e32 v244, v244, v1
	v_bfe_u32 v1, v0, 3, 6
	v_lshlrev_b32_e32 v1, 11, v1
	v_add_u32_e32 v244, v244, v1
	v_mov_b32_e32 v243, 0x40000
	v_bfe_u32 v1, v0, 0, 3
	v_lshlrev_b32_e32 v1, 4, v1
	v_add_u32_e32 v243, v243, v1
	v_bfe_u32 v1, v0, 3, 6
	v_lshlrev_b32_e32 v1, 11, v1
	v_add_u32_e32 v243, v243, v1
	v_mov_b32_e32 v242, 0x18000
	v_bfe_u32 v1, v0, 1, 3
	v_lshlrev_b32_e32 v1, 8, v1
	v_add_u32_e32 v242, v242, v1
	v_bfe_u32 v1, v0, 6, 2
	v_mul_u32_u24_e32 v1, 0x1800, v1
	v_add_u32_e32 v242, v242, v1
	v_mov_b32_e32 v2, 0x0
	v_bfe_u32 v1, v0, 0, 1
	v_lshlrev_b32_e32 v1, 7, v1
	v_xor_b32_e32 v2, v2, v1
	v_bfe_u32 v1, v0, 1, 3
	v_lshlrev_b32_e32 v1, 4, v1
	v_xor_b32_e32 v2, v2, v1
	v_bfe_u32 v1, v0, 4, 2
	v_lshlrev_b32_e32 v1, 4, v1
	v_xor_b32_e32 v2, v2, v1
	v_bfe_u32 v1, v0, 6, 1
	v_lshlrev_b32_e32 v1, 7, v1
	v_xor_b32_e32 v2, v2, v1
	v_add_u32_e32 v242, v242, v2
	v_mov_b32_e32 v241, 0x18000
	v_bfe_u32 v1, v0, 1, 3
	v_lshlrev_b32_e32 v1, 8, v1
	v_add_u32_e32 v241, v241, v1
	v_bfe_u32 v1, v0, 6, 2
	v_mul_u32_u24_e32 v1, 0x1800, v1
	v_add_u32_e32 v241, v241, v1
	v_mov_b32_e32 v2, 0x40
	v_bfe_u32 v1, v0, 0, 1
	v_lshlrev_b32_e32 v1, 7, v1
	v_xor_b32_e32 v2, v2, v1
	v_bfe_u32 v1, v0, 1, 3
	v_lshlrev_b32_e32 v1, 4, v1
	v_xor_b32_e32 v2, v2, v1
	v_bfe_u32 v1, v0, 4, 2
	v_lshlrev_b32_e32 v1, 4, v1
	v_xor_b32_e32 v2, v2, v1
	v_bfe_u32 v1, v0, 6, 1
	v_lshlrev_b32_e32 v1, 7, v1
	v_xor_b32_e32 v2, v2, v1
	v_add_u32_e32 v241, v241, v2
	v_mov_b32_e32 v240, 0x10040
	v_bfe_u32 v1, v0, 0, 1
	v_lshlrev_b32_e32 v1, 7, v1
	v_xor_b32_e32 v240, v240, v1
	v_bfe_u32 v1, v0, 1, 3
	v_mul_u32_u24_e32 v1, 0x110, v1
	v_xor_b32_e32 v240, v240, v1
	v_bfe_u32 v1, v0, 4, 2
	v_lshlrev_b32_e32 v1, 4, v1
	v_xor_b32_e32 v240, v240, v1
	v_bfe_u32 v1, v0, 8, 1
	v_lshlrev_b32_e32 v1, 14, v1
	v_xor_b32_e32 v240, v240, v1
	v_mov_b32_e32 v239, 0x60000
	v_bfe_u32 v1, v0, 0, 3
	v_lshlrev_b32_e32 v1, 4, v1
	v_add_u32_e32 v239, v239, v1
	v_bfe_u32 v1, v0, 3, 6
	v_lshlrev_b32_e32 v1, 11, v1
	v_add_u32_e32 v239, v239, v1
	v_mov_b32_e32 v238, 0x18800
	v_bfe_u32 v1, v0, 1, 3
	v_lshlrev_b32_e32 v1, 8, v1
	v_add_u32_e32 v238, v238, v1
	v_bfe_u32 v1, v0, 6, 2
	v_mul_u32_u24_e32 v1, 0x1800, v1
	v_add_u32_e32 v238, v238, v1
	v_mov_b32_e32 v2, 0x80
	v_bfe_u32 v1, v0, 0, 1
	v_lshlrev_b32_e32 v1, 7, v1
	v_xor_b32_e32 v2, v2, v1
	v_bfe_u32 v1, v0, 1, 3
	v_lshlrev_b32_e32 v1, 4, v1
	v_xor_b32_e32 v2, v2, v1
	v_bfe_u32 v1, v0, 4, 2
	v_lshlrev_b32_e32 v1, 4, v1
	v_xor_b32_e32 v2, v2, v1
	v_bfe_u32 v1, v0, 6, 1
	v_lshlrev_b32_e32 v1, 7, v1
	v_xor_b32_e32 v2, v2, v1
	v_add_u32_e32 v238, v238, v2
	v_mov_b32_e32 v237, 0x10000
	v_bfe_u32 v1, v0, 0, 1
	v_lshlrev_b32_e32 v1, 7, v1
	v_xor_b32_e32 v237, v237, v1
	v_bfe_u32 v1, v0, 1, 3
	v_mul_u32_u24_e32 v1, 0x110, v1
	v_xor_b32_e32 v237, v237, v1
	v_bfe_u32 v1, v0, 4, 2
	v_lshlrev_b32_e32 v1, 4, v1
	v_xor_b32_e32 v237, v237, v1
	v_bfe_u32 v1, v0, 8, 1
	v_lshlrev_b32_e32 v1, 14, v1
	v_xor_b32_e32 v237, v237, v1
	v_mov_b32_e32 v236, 0x10880
	v_bfe_u32 v1, v0, 0, 1
	v_lshlrev_b32_e32 v1, 7, v1
	v_xor_b32_e32 v236, v236, v1
	v_bfe_u32 v1, v0, 1, 3
	v_mul_u32_u24_e32 v1, 0x110, v1
	v_xor_b32_e32 v236, v236, v1
	v_bfe_u32 v1, v0, 4, 2
	v_lshlrev_b32_e32 v1, 4, v1
	v_xor_b32_e32 v236, v236, v1
	v_bfe_u32 v1, v0, 8, 1
	v_lshlrev_b32_e32 v1, 14, v1
	v_xor_b32_e32 v236, v236, v1
	v_mov_b32_e32 v235, 0x18800
	v_bfe_u32 v1, v0, 1, 3
	v_lshlrev_b32_e32 v1, 8, v1
	v_add_u32_e32 v235, v235, v1
	v_bfe_u32 v1, v0, 6, 2
	v_mul_u32_u24_e32 v1, 0x1800, v1
	v_add_u32_e32 v235, v235, v1
	v_mov_b32_e32 v2, 0xc0
	v_bfe_u32 v1, v0, 0, 1
	v_lshlrev_b32_e32 v1, 7, v1
	v_xor_b32_e32 v2, v2, v1
	v_bfe_u32 v1, v0, 1, 3
	v_lshlrev_b32_e32 v1, 4, v1
	v_xor_b32_e32 v2, v2, v1
	v_bfe_u32 v1, v0, 4, 2
	v_lshlrev_b32_e32 v1, 4, v1
	v_xor_b32_e32 v2, v2, v1
	v_bfe_u32 v1, v0, 6, 1
	v_lshlrev_b32_e32 v1, 7, v1
	v_xor_b32_e32 v2, v2, v1
	v_add_u32_e32 v235, v235, v2
	v_mov_b32_e32 v234, 0x108c0
	v_bfe_u32 v1, v0, 0, 1
	v_lshlrev_b32_e32 v1, 7, v1
	v_xor_b32_e32 v234, v234, v1
	v_bfe_u32 v1, v0, 1, 3
	v_mul_u32_u24_e32 v1, 0x110, v1
	v_xor_b32_e32 v234, v234, v1
	v_bfe_u32 v1, v0, 4, 2
	v_lshlrev_b32_e32 v1, 4, v1
	v_xor_b32_e32 v234, v234, v1
	v_bfe_u32 v1, v0, 8, 1
	v_lshlrev_b32_e32 v1, 14, v1
	v_xor_b32_e32 v234, v234, v1
	v_mov_b32_e32 v1, v0
	s_load_dword s2, s[0:1], 0xe0
	s_mov_b32 s3, s10
	v_mov_b32_e32 v1, v0
	s_waitcnt lgkmcnt(0)
	s_lshr_b32 s11, s2, 3
	v_cvt_f32_u32_e32 v2, s11
	s_mov_b32 s2, s10
	s_ashr_i32 s3, s2, 3
	v_rcp_iflag_f32_e32 v2, v2
	s_ashr_i32 s4, s2, 31
	s_sub_i32 s2, 0, s11
	s_abs_i32 s3, s3
	v_mul_f32_e32 v1, 0x4f7ffffe, v2
	v_cvt_u32_f32_e32 v1, v1
	s_mov_b32 s45, 0
	v_readfirstlane_b32 s5, v1
	s_mul_i32 s2, s2, s5
	s_mul_hi_u32 s2, s5, s2
	s_add_i32 s2, s5, s2
	s_mul_hi_u32 s5, s3, s2
	s_mul_i32 s5, s5, s11
	s_sub_i32 s3, s3, s5
	s_sub_i32 s5, s3, s11
	s_cmp_ge_u32 s3, s11
	s_cselect_b32 s3, s5, s3
	s_sub_i32 s5, s3, s11
	s_cmp_ge_u32 s3, s11
	s_cselect_b32 s3, s5, s3
	s_xor_b32 s3, s3, s4
	s_sub_i32 s24, s3, s4
	s_mov_b32 s3, s10
	s_cmpk_gt_i32 s24, 0x5f
	s_cbranch_scc1 .LBB0_361
	s_load_dwordx2 s[4:5], s[16:17], 0xd0
	s_mov_b32 s3, s10
	v_mov_b32_e32 v54, 0
	v_mov_b32_e32 v1, v0
	s_waitcnt lgkmcnt(0)
	s_add_u32 s25, s4, 0x17f0000
	s_addc_u32 s26, s5, 0
	s_add_u32 s8, s4, 0x37f0000
	s_addc_u32 s9, s5, 0
	s_add_u32 s27, s4, 0x50000
	s_addc_u32 s28, s5, 0
	s_ashr_i32 s4, s24, 31
	s_lshr_b32 s4, s4, 27
	s_add_i32 s4, s24, s4
	s_ashr_i32 s4, s4, 5
	s_lshl_b32 s5, s24, 1
	s_lshl_b32 s12, s4, 6
	s_sub_i32 s5, s5, s12
	s_lshl_b32 s4, s4, 2
	s_and_b32 s12, s24, 3
	s_or_b32 s29, s4, s12
	s_sub_i32 s4, s11, s24
	s_addk_i32 s4, 0x5f
	s_mul_hi_u32 s2, s4, s2
	s_mul_i32 s12, s2, s11
	s_sub_i32 s4, s4, s12
	s_add_i32 s12, s2, 1
	s_sub_i32 s13, s4, s11
	s_cmp_ge_u32 s4, s11
	s_cselect_b32 s2, s12, s2
	s_cselect_b32 s4, s13, s4
	s_add_i32 s12, s2, 1
	s_cmp_ge_u32 s4, s11
	s_cselect_b32 s2, s12, s2
	s_and_b32 s3, s3, 7
	s_and_b32 s4, s5, -8
	s_lshl_b32 s30, s2, 4
	s_mul_i32 s2, s29, 0xc0
	s_or_b32 s31, s3, s4
	s_ashr_i32 s3, s2, 31
	s_lshl_b64 s[2:3], s[2:3], 11
	v_lshlrev_b32_e32 v2, 8, v1
	v_lshlrev_b32_e32 v1, 4, v1
	s_add_u32 s2, s27, s2
	v_and_b32_e32 v1, 0x70, v1
	s_movk_i32 s33, 0xf800
	v_mov_b32_e32 v175, 0
	s_addc_u32 s3, s28, s3
	v_and_or_b32 v174, v2, s33, v1
	s_lshl_b32 s4, s31, 8
	v_lshl_add_u64 v[2:3], s[2:3], 0, v[174:175]
	s_mov_b32 s12, 0x40000
	s_ashr_i32 s5, s4, 31
	v_add_co_u32_e32 v14, vcc, s12, v2
	s_lshl_b64 s[4:5], s[4:5], 11
	s_nop 0
	v_addc_co_u32_e32 v15, vcc, 0, v3, vcc
	s_mov_b32 s34, 0x20000
	s_add_u32 s4, s25, s4
	v_add_co_u32_e32 v16, vcc, s34, v2
	s_addc_u32 s5, s26, s5
	s_nop 0
	v_addc_co_u32_e32 v17, vcc, 0, v3, vcc
	global_load_dwordx4 v[2:5], v[14:15], off
	global_load_dwordx4 v[6:9], v[16:17], off
	global_load_dwordx4 v[10:13], v174, s[2:3]
	v_lshl_add_u64 v[14:15], s[4:5], 0, v[174:175]
	s_mov_b32 s13, 0x60000
	v_add_co_u32_e32 v30, vcc, s13, v14
	v_mov_b32_e32 v1, v0
	s_nop 0
	v_addc_co_u32_e32 v31, vcc, 0, v15, vcc
	v_add_co_u32_e32 v32, vcc, s12, v14
	s_movk_i32 s36, 0xf0
	s_nop 0
	v_addc_co_u32_e32 v33, vcc, 0, v15, vcc
	v_add_co_u32_e32 v34, vcc, s34, v14
	s_mov_b32 s35, 2
	s_nop 0
	v_addc_co_u32_e32 v35, vcc, 0, v15, vcc
	global_load_dwordx4 v[14:17], v174, s[4:5]
	global_load_dwordx4 v[18:21], v[34:35], off
	global_load_dwordx4 v[22:25], v[32:33], off
	global_load_dwordx4 v[26:29], v[30:31], off
	v_mov_b32_e32 v30, v0
	v_ashrrev_i32_e32 v31, 4, v1
	v_xor_b32_e32 v1, v31, v1
	v_lshlrev_b32_e32 v31, 8, v31
	v_lshlrev_b32_e32 v1, 4, v1
	v_and_or_b32 v1, v1, s36, v31
	s_movk_i32 s37, 0xff80
	s_mov_b32 s38, 0x10000
	s_mov_b32 s39, 0x18000
	s_movk_i32 s40, 0x8a0
	s_movk_i32 s41, 0x1140
	v_mov_b32_e32 v176, 0x18000
	s_mov_b32 s22, 2
	s_mov_b32 s42, s24
	s_mov_b32 s43, s29
	s_mov_b32 s44, s31
	v_mov_b32_e32 v55, v54
	v_mov_b32_e32 v56, v54
	v_mov_b32_e32 v57, v54
	v_mov_b32_e32 v82, v54
	v_mov_b32_e32 v83, v54
	v_mov_b32_e32 v84, v54
	v_mov_b32_e32 v85, v54
	v_mov_b32_e32 v86, v54
	v_mov_b32_e32 v87, v54
	v_mov_b32_e32 v88, v54
	v_mov_b32_e32 v89, v54
	v_mov_b32_e32 v90, v54
	v_mov_b32_e32 v91, v54
	v_mov_b32_e32 v92, v54
	v_mov_b32_e32 v93, v54
	v_mov_b32_e32 v94, v54
	v_mov_b32_e32 v95, v54
	v_mov_b32_e32 v96, v54
	v_mov_b32_e32 v97, v54
	s_waitcnt vmcnt(4)
	ds_write_b128 v1, v[10:13] offset:32768
	ds_write_b128 v1, v[6:9] offset:40960
	ds_write_b128 v1, v[2:5] offset:49152
	s_waitcnt vmcnt(3)
	ds_write_b128 v1, v[14:17]
	s_waitcnt vmcnt(2)
	ds_write_b128 v1, v[18:21] offset:8192
	s_waitcnt vmcnt(1)
	ds_write_b128 v1, v[22:25] offset:16384
	s_waitcnt vmcnt(0)
	ds_write_b128 v1, v[26:29] offset:24576
	v_mov_b32_e32 v98, v54
	v_lshlrev_b32_e32 v2, 4, v30
	v_lshlrev_b32_e32 v1, 8, v30
	v_and_b32_e32 v2, 0x70, v2
	v_and_or_b32 v174, v1, s33, v2
	v_lshl_add_u64 v[2:3], s[2:3], 0, v[174:175]
	v_add_co_u32_e32 v10, vcc, s12, v2
	v_mov_b32_e32 v1, 0x10000
	s_nop 0
	v_addc_co_u32_e32 v11, vcc, 0, v3, vcc
	v_add_co_u32_e32 v12, vcc, s34, v2
	v_mov_b32_e32 v99, v54
	s_nop 0
	v_addc_co_u32_e32 v13, vcc, 0, v3, vcc
	global_load_dwordx4 v[2:5], v[10:11], off offset:128
	global_load_dwordx4 v[6:9], v[12:13], off offset:128
	v_lshl_add_u64 v[10:11], s[4:5], 0, v[174:175]
	v_add_co_u32_e32 v12, vcc, s13, v10
	v_mov_b32_e32 v100, v54
	s_nop 0
	v_addc_co_u32_e32 v13, vcc, 0, v11, vcc
	v_add_co_u32_e32 v22, vcc, s12, v10
	v_mov_b32_e32 v101, v54
	s_nop 0
	v_addc_co_u32_e32 v23, vcc, 0, v11, vcc
	v_add_co_u32_e32 v30, vcc, s34, v10
	global_load_dwordx4 v[14:17], v[12:13], off offset:128
	global_load_dwordx4 v[18:21], v[22:23], off offset:128
	v_addc_co_u32_e32 v31, vcc, 0, v11, vcc
	global_load_dwordx4 v[10:13], v174, s[2:3] offset:128
	global_load_dwordx4 v[22:25], v[30:31], off offset:128
	global_load_dwordx4 v[26:29], v174, s[4:5] offset:128
	v_mov_b32_e32 v102, v54
	v_mov_b32_e32 v103, v54
	v_mov_b32_e32 v104, v54
	v_mov_b32_e32 v105, v54
	v_mov_b32_e32 v106, v54
	v_mov_b32_e32 v107, v54
	v_mov_b32_e32 v108, v54
	v_mov_b32_e32 v109, v54
	v_mov_b32_e32 v110, v54
	v_mov_b32_e32 v111, v54
	v_mov_b32_e32 v112, v54
	v_mov_b32_e32 v113, v54
	v_mov_b32_e32 v114, v54
	v_mov_b32_e32 v115, v54
	v_mov_b32_e32 v116, v54
	v_mov_b32_e32 v117, v54
	v_mov_b32_e32 v118, v54
	v_mov_b32_e32 v119, v54
	v_mov_b32_e32 v120, v54
	v_mov_b32_e32 v121, v54
	v_mov_b32_e32 v122, v54
	v_mov_b32_e32 v123, v54
	v_mov_b32_e32 v124, v54
	v_mov_b32_e32 v125, v54
	v_mov_b32_e32 v78, v54
	v_mov_b32_e32 v79, v54
	v_mov_b32_e32 v80, v54
	v_mov_b32_e32 v81, v54
	v_mov_b32_e32 v74, v54
	v_mov_b32_e32 v75, v54
	v_mov_b32_e32 v76, v54
	v_mov_b32_e32 v77, v54
	v_mov_b32_e32 v70, v54
	v_mov_b32_e32 v71, v54
	v_mov_b32_e32 v72, v54
	v_mov_b32_e32 v73, v54
	v_mov_b32_e32 v66, v54
	v_mov_b32_e32 v67, v54
	v_mov_b32_e32 v68, v54
	v_mov_b32_e32 v69, v54
	v_mov_b32_e32 v62, v54
	v_mov_b32_e32 v63, v54
	v_mov_b32_e32 v64, v54
	v_mov_b32_e32 v65, v54
	v_mov_b32_e32 v58, v54
	v_mov_b32_e32 v59, v54
	v_mov_b32_e32 v60, v54
	v_mov_b32_e32 v61, v54
	v_mov_b32_e32 v50, v54
	v_mov_b32_e32 v51, v54
	v_mov_b32_e32 v52, v54
	v_mov_b32_e32 v53, v54
	v_mov_b32_e32 v46, v54
	v_mov_b32_e32 v47, v54
	v_mov_b32_e32 v48, v54
	v_mov_b32_e32 v49, v54
	v_mov_b32_e32 v42, v54
	v_mov_b32_e32 v43, v54
	v_mov_b32_e32 v44, v54
	v_mov_b32_e32 v45, v54
	v_mov_b32_e32 v38, v54
	v_mov_b32_e32 v39, v54
	v_mov_b32_e32 v40, v54
	v_mov_b32_e32 v41, v54
	v_mov_b32_e32 v34, v54
	v_mov_b32_e32 v35, v54
	v_mov_b32_e32 v36, v54
	v_mov_b32_e32 v37, v54
	v_mov_b32_e32 v30, v54
	v_mov_b32_e32 v31, v54
	v_mov_b32_e32 v32, v54
	v_mov_b32_e32 v33, v54
	s_waitcnt lgkmcnt(0)
	s_barrier
	s_branch .LBB0_285

.LBB0_285:
	s_add_i32 s2, s35, -1
	ds_read_b128 v[130:133], v255
	ds_read_b128 v[126:129], v254
	ds_read_b128 v[134:137], v255 offset:4096
	ds_read_b128 v[142:145], v253
	ds_read_b128 v[146:149], v252
	ds_read_b128 v[138:141], v253 offset:4096
	s_setprio 1
	s_waitcnt lgkmcnt(2)
	v_mfma_f32_16x16x32_bf16 v[122:125], v[130:133], v[142:145], v[122:125]
	s_cmp_lt_i32 s2, s30
	s_cselect_b64 s[14:15], -1, 0
	s_cmp_ge_i32 s2, s30
	v_mfma_f32_16x16x32_bf16 v[118:121], v[126:129], v[142:145], v[118:121]
	v_mfma_f32_16x16x32_bf16 v[114:117], v[134:137], v[142:145], v[114:117]
	ds_read_b128 v[142:145], v252 offset:4096
	ds_read_b128 v[150:153], v253 offset:8192
	s_waitcnt lgkmcnt(3)
	v_mfma_f32_16x16x32_bf16 v[110:113], v[130:133], v[146:149], v[110:113]
	v_mfma_f32_16x16x32_bf16 v[106:109], v[126:129], v[146:149], v[106:109]
	v_mfma_f32_16x16x32_bf16 v[102:105], v[134:137], v[146:149], v[102:105]
	s_cbranch_scc1 .LBB0_287
	s_waitcnt vmcnt(0)
	ds_write_b128 v245, v[26:29]
	ds_write_b128 v245, v[22:25] offset:8192
.LBB0_287:
	s_lshl_b32 s2, s44, 8
	s_ashr_i32 s3, s2, 31
	s_lshl_b64 s[4:5], s[2:3], 11
	s_lshl_b32 s2, s22, 6
	s_ashr_i32 s3, s2, 31
	s_add_u32 s20, s25, s4
	s_addc_u32 s21, s26, s5
	s_lshl_b64 s[12:13], s[2:3], 1
	s_waitcnt vmcnt(1)
	s_add_u32 s20, s20, s12
	s_addc_u32 s21, s21, s13
	s_waitcnt vmcnt(0)
	s_nop 0
	s_waitcnt lgkmcnt(2)
	v_mfma_f32_16x16x32_bf16 v[98:101], v[130:133], v[138:141], v[98:101]
	global_load_dwordx4 v[22:25], v246, s[20:21]
	v_mfma_f32_16x16x32_bf16 v[94:97], v[126:129], v[138:141], v[94:97]
	v_mfma_f32_16x16x32_bf16 v[90:93], v[134:137], v[138:141], v[90:93]
	s_waitcnt lgkmcnt(1)
	v_mfma_f32_16x16x32_bf16 v[138:141], v[134:137], v[142:145], v[54:57]
	s_waitcnt lgkmcnt(0)
	v_mfma_f32_16x16x32_bf16 v[146:149], v[126:129], v[150:153], v[74:77]
	s_nop 0
	ds_read_b128 v[54:57], v252 offset:12288
	s_nop 0
	ds_read_b128 v[74:77], v252 offset:8192
	global_load_dwordx4 v[26:29], v244, s[20:21]
	s_waitcnt lgkmcnt(0)
	v_mfma_f32_16x16x32_bf16 v[158:161], v[126:129], v[74:77], v[62:65]
	s_nop 2
	ds_read_b128 v[62:65], v253 offset:12288
	v_mfma_f32_16x16x32_bf16 v[86:89], v[130:133], v[142:145], v[86:89]
	v_mfma_f32_16x16x32_bf16 v[82:85], v[126:129], v[142:145], v[82:85]
	v_mfma_f32_16x16x32_bf16 v[142:145], v[130:133], v[150:153], v[78:81]
	v_mfma_f32_16x16x32_bf16 v[150:153], v[134:137], v[150:153], v[70:73]
	v_mfma_f32_16x16x32_bf16 v[154:157], v[130:133], v[74:77], v[66:69]
	v_mfma_f32_16x16x32_bf16 v[162:165], v[134:137], v[74:77], v[58:61]
	s_nop 2
	v_cndmask_b32_e64 v59, 0, 1, s[14:15]
	v_cmp_ne_u32_e64 s[2:3], 1, v59
	s_andn2_b64 vcc, exec, s[14:15]
	s_cbranch_vccnz .LBB0_289
	ds_write_b128 v245, v[18:21] offset:16384
	ds_write_b128 v245, v[14:17] offset:24576
.LBB0_289:
	s_waitcnt lgkmcnt(0)
	v_mfma_f32_16x16x32_bf16 v[50:53], v[130:133], v[62:65], v[50:53]
	v_mfma_f32_16x16x32_bf16 v[46:49], v[126:129], v[62:65], v[46:49]
	s_nop 0
	global_load_dwordx4 v[14:17], v243, s[20:21]
	s_nop 0
	global_load_dwordx4 v[18:21], v239, s[20:21]
	v_mfma_f32_16x16x32_bf16 v[42:45], v[134:137], v[62:65], v[42:45]
	v_mfma_f32_16x16x32_bf16 v[38:41], v[130:133], v[54:57], v[38:41]
	v_mfma_f32_16x16x32_bf16 v[126:129], v[126:129], v[54:57], v[34:37]
	v_mfma_f32_16x16x32_bf16 v[30:33], v[134:137], v[54:57], v[30:33]
	s_setprio 0
	s_nop 0
	s_nop 0
	ds_read_b128 v[134:137], v250
	ds_read_b128 v[130:133], v249 offset:4096
	ds_read_b128 v[166:169], v249
	ds_read_b128 v[54:57], v248
	ds_read_b128 v[34:37], v247
	ds_read_b128 v[70:73], v247 offset:4096
	s_setprio 1
	s_waitcnt lgkmcnt(1)
	v_mfma_f32_16x16x32_bf16 v[122:125], v[166:169], v[34:37], v[122:125]
	v_mfma_f32_16x16x32_bf16 v[118:121], v[134:137], v[34:37], v[118:121]
	v_mfma_f32_16x16x32_bf16 v[114:117], v[130:133], v[34:37], v[114:117]
	v_mfma_f32_16x16x32_bf16 v[58:61], v[134:137], v[54:57], v[106:109]
	s_nop 2
	ds_read_b128 v[106:109], v248 offset:4096
	ds_read_b128 v[34:37], v247 offset:8192
	v_mfma_f32_16x16x32_bf16 v[110:113], v[166:169], v[54:57], v[110:113]
	v_mfma_f32_16x16x32_bf16 v[54:57], v[130:133], v[54:57], v[102:105]
	s_nop 2
	s_and_b64 vcc, exec, s[2:3]
	s_cbranch_vccnz .LBB0_291
	ds_write_b128 v245, v[10:13] offset:32768
	ds_write_b128 v245, v[6:9] offset:40960
.LBB0_291:
	s_mul_i32 s14, s43, 0xc0
	s_ashr_i32 s15, s14, 31
	s_lshl_b64 s[14:15], s[14:15], 11
	s_add_u32 s20, s27, s14
	s_addc_u32 s21, s28, s15
	s_add_u32 s12, s20, s12
	s_addc_u32 s13, s21, s13
	s_waitcnt lgkmcnt(1)
	v_mfma_f32_16x16x32_bf16 v[74:77], v[166:169], v[106:109], v[86:89]
	v_mfma_f32_16x16x32_bf16 v[78:81], v[134:137], v[106:109], v[82:85]
	v_mfma_f32_16x16x32_bf16 v[82:85], v[130:133], v[106:109], v[138:141]
	ds_read_b128 v[106:109], v248 offset:8192
	s_nop 1
	ds_read_b128 v[138:141], v247 offset:12288
	global_load_dwordx4 v[6:9], v246, s[12:13]
	s_nop 0
	global_load_dwordx4 v[10:13], v244, s[12:13]
	s_waitcnt lgkmcnt(2)
	v_mfma_f32_16x16x32_bf16 v[86:89], v[166:169], v[34:37], v[142:145]
	s_nop 2
	ds_read_b128 v[142:145], v248 offset:12288
	v_mfma_f32_16x16x32_bf16 v[62:65], v[166:169], v[70:73], v[98:101]
	v_mfma_f32_16x16x32_bf16 v[66:69], v[134:137], v[70:73], v[94:97]
	v_mfma_f32_16x16x32_bf16 v[70:73], v[130:133], v[70:73], v[90:93]
	v_mfma_f32_16x16x32_bf16 v[90:93], v[134:137], v[34:37], v[146:149]
	v_mfma_f32_16x16x32_bf16 v[94:97], v[130:133], v[34:37], v[150:153]
	s_waitcnt lgkmcnt(2)
	v_mfma_f32_16x16x32_bf16 v[98:101], v[166:169], v[106:109], v[154:157]
	v_mfma_f32_16x16x32_bf16 v[102:105], v[134:137], v[106:109], v[158:161]
	v_mfma_f32_16x16x32_bf16 v[106:109], v[130:133], v[106:109], v[162:165]
	s_and_b64 vcc, exec, s[2:3]
	s_cbranch_vccnz .LBB0_293
	ds_write_b128 v245, v[2:5] offset:49152
.LBB0_293:
	s_waitcnt lgkmcnt(1)
	v_mfma_f32_16x16x32_bf16 v[50:53], v[166:169], v[138:141], v[50:53]
	global_load_dwordx4 v[2:5], v243, s[12:13]
	v_mfma_f32_16x16x32_bf16 v[34:37], v[134:137], v[138:141], v[46:49]
	v_mfma_f32_16x16x32_bf16 v[46:49], v[130:133], v[138:141], v[42:45]
	s_waitcnt lgkmcnt(0)
	v_mfma_f32_16x16x32_bf16 v[38:41], v[166:169], v[142:145], v[38:41]
	v_mfma_f32_16x16x32_bf16 v[42:45], v[134:137], v[142:145], v[126:129]
	v_mfma_f32_16x16x32_bf16 v[30:33], v[130:133], v[142:145], v[30:33]
	s_setprio 0
	s_add_i32 s46, s22, 1
	s_cmp_lg_u32 s46, 16
	s_cbranch_scc1 .LBB0_297
	s_add_i32 s24, s24, s11
	s_cmpk_gt_i32 s24, 0x5f
	s_cbranch_scc1 .LBB0_296
	s_ashr_i32 s3, s24, 31
	s_lshr_b32 s3, s3, 27
	s_add_i32 s3, s24, s3
	s_ashr_i32 s3, s3, 5
	s_mov_b32 s2, s10
	s_lshl_b32 s4, s3, 6
	s_lshl_b32 s5, s24, 1
	s_sub_i32 s4, s5, s4
	s_and_b32 s2, s2, 7
	s_and_b32 s4, s4, -8
	s_or_b32 s44, s2, s4
	s_lshl_b32 s3, s3, 2
	s_and_b32 s5, s24, 3
	s_lshl_b32 s2, s44, 8
	s_or_b32 s43, s3, s5
	s_ashr_i32 s3, s2, 31
	s_lshl_b64 s[4:5], s[2:3], 11
	s_mul_i32 s2, s43, 0xc0
	s_ashr_i32 s3, s2, 31
	s_lshl_b64 s[14:15], s[2:3], 11

.LBB0_297:
	s_barrier
	s_nop 0
	ds_read_b128 v[162:165], v242
	ds_read_b128 v[158:161], v238
	ds_read_b128 v[166:169], v242 offset:4096
	ds_read_b128 v[130:133], v237
	ds_read_b128 v[138:141], v236
	ds_read_b128 v[126:129], v237 offset:4096
	s_setprio 1
	s_waitcnt lgkmcnt(2)
	v_mfma_f32_16x16x32_bf16 v[122:125], v[162:165], v[130:133], v[122:125]
	s_cmp_lt_i32 s35, s30
	s_cselect_b64 s[20:21], -1, 0
	s_cmp_ge_i32 s35, s30
	v_mfma_f32_16x16x32_bf16 v[118:121], v[158:161], v[130:133], v[118:121]
	s_cselect_b64 s[12:13], -1, 0
	v_mfma_f32_16x16x32_bf16 v[114:117], v[166:169], v[130:133], v[114:117]
	ds_read_b128 v[130:133], v236 offset:4096
	ds_read_b128 v[134:137], v237 offset:8192
	s_waitcnt lgkmcnt(3)
	v_mfma_f32_16x16x32_bf16 v[110:113], v[162:165], v[138:141], v[110:113]
	v_mfma_f32_16x16x32_bf16 v[58:61], v[158:161], v[138:141], v[58:61]
	v_mfma_f32_16x16x32_bf16 v[54:57], v[166:169], v[138:141], v[54:57]
	s_and_b64 vcc, exec, s[12:13]
	s_cbranch_vccnz .LBB0_299
	s_waitcnt vmcnt(6)
	ds_write_b128 v251, v[22:25]
	s_waitcnt vmcnt(5)
	ds_write_b128 v251, v[26:29] offset:8192
.LBB0_299:
	s_lshl_b32 s2, s46, 6
	s_ashr_i32 s3, s2, 31
	s_add_u32 s22, s25, s4
	s_addc_u32 s23, s26, s5
	s_lshl_b64 s[4:5], s[2:3], 1
	s_waitcnt vmcnt(6)
	s_add_u32 s22, s22, s4
	s_addc_u32 s23, s23, s5
	s_waitcnt lgkmcnt(2)
	v_mfma_f32_16x16x32_bf16 v[62:65], v[162:165], v[126:129], v[62:65]
	v_mfma_f32_16x16x32_bf16 v[66:69], v[158:161], v[126:129], v[66:69]
	v_mfma_f32_16x16x32_bf16 v[70:73], v[166:169], v[126:129], v[70:73]
	s_waitcnt lgkmcnt(1)
	v_mfma_f32_16x16x32_bf16 v[74:77], v[162:165], v[130:133], v[74:77]
	v_mfma_f32_16x16x32_bf16 v[78:81], v[158:161], v[130:133], v[78:81]
	v_mfma_f32_16x16x32_bf16 v[138:141], v[166:169], v[130:133], v[82:85]
	s_waitcnt lgkmcnt(0)
	v_mfma_f32_16x16x32_bf16 v[126:129], v[162:165], v[134:137], v[86:89]
	v_mfma_f32_16x16x32_bf16 v[130:133], v[158:161], v[134:137], v[90:93]
	s_nop 1
	ds_read_b128 v[86:89], v237 offset:12288
	ds_read_b128 v[90:93], v236 offset:8192
	global_load_dwordx4 v[26:29], v246, s[22:23]
	s_nop 0
	global_load_dwordx4 v[22:25], v244, s[22:23]
	ds_read_b128 v[82:85], v236 offset:12288
	v_mfma_f32_16x16x32_bf16 v[134:137], v[166:169], v[134:137], v[94:97]
	s_waitcnt lgkmcnt(1)
	v_mfma_f32_16x16x32_bf16 v[142:145], v[162:165], v[90:93], v[98:101]
	v_mfma_f32_16x16x32_bf16 v[146:149], v[158:161], v[90:93], v[102:105]
	v_mfma_f32_16x16x32_bf16 v[150:153], v[166:169], v[90:93], v[106:109]
	v_cndmask_b32_e64 v91, 0, 1, s[20:21]
	v_cmp_ne_u32_e64 s[2:3], 1, v91
	s_andn2_b64 vcc, exec, s[20:21]
	s_cbranch_vccnz .LBB0_301
	s_waitcnt vmcnt(6)
	ds_write_b128 v251, v[14:17] offset:16384
	s_waitcnt vmcnt(5)
	ds_write_b128 v251, v[18:21] offset:24576
.LBB0_301:
	s_waitcnt vmcnt(6)
	v_mfma_f32_16x16x32_bf16 v[50:53], v[162:165], v[86:89], v[50:53]
	s_nop 0
	v_mfma_f32_16x16x32_bf16 v[154:157], v[158:161], v[86:89], v[34:37]
	s_nop 0
	global_load_dwordx4 v[18:21], v243, s[22:23]
	s_nop 0
	global_load_dwordx4 v[14:17], v239, s[22:23]
	v_mfma_f32_16x16x32_bf16 v[34:37], v[166:169], v[86:89], v[46:49]
	s_waitcnt lgkmcnt(0)
	v_mfma_f32_16x16x32_bf16 v[38:41], v[162:165], v[82:85], v[38:41]
	v_mfma_f32_16x16x32_bf16 v[158:161], v[158:161], v[82:85], v[42:45]
	v_mfma_f32_16x16x32_bf16 v[30:33], v[166:169], v[82:85], v[30:33]
	s_setprio 0
	s_nop 0
	s_nop 0
	ds_read_b128 v[166:169], v241
	ds_read_b128 v[162:165], v235
	ds_read_b128 v[170:173], v241 offset:4096
	ds_read_b128 v[42:45], v240
	ds_read_b128 v[82:85], v234
	ds_read_b128 v[46:49], v240 offset:4096
	s_setprio 1
	s_waitcnt lgkmcnt(2)
	v_mfma_f32_16x16x32_bf16 v[122:125], v[166:169], v[42:45], v[122:125]
	v_mfma_f32_16x16x32_bf16 v[118:121], v[162:165], v[42:45], v[118:121]
	v_mfma_f32_16x16x32_bf16 v[114:117], v[170:173], v[42:45], v[114:117]
	s_waitcnt lgkmcnt(1)
	v_mfma_f32_16x16x32_bf16 v[106:109], v[162:165], v[82:85], v[58:61]
	s_nop 2
	ds_read_b128 v[58:61], v234 offset:4096
	ds_read_b128 v[42:45], v240 offset:8192
	v_mfma_f32_16x16x32_bf16 v[110:113], v[166:169], v[82:85], v[110:113]
	v_mfma_f32_16x16x32_bf16 v[102:105], v[170:173], v[82:85], v[54:57]
	s_and_b64 vcc, exec, s[2:3]
	s_cbranch_vccnz .LBB0_303
	s_waitcnt vmcnt(6)
	ds_write_b128 v251, v[6:9] offset:32768
	s_waitcnt vmcnt(5)
	ds_write_b128 v251, v[10:13] offset:40960
.LBB0_303:
	s_add_u32 s14, s27, s14
	s_addc_u32 s15, s28, s15
	s_waitcnt vmcnt(6)
	s_add_u32 s4, s14, s4
	s_addc_u32 s5, s15, s5
	global_load_dwordx4 v[10:13], v246, s[4:5]
	s_nop 0
	global_load_dwordx4 v[6:9], v244, s[4:5]
	s_waitcnt lgkmcnt(2)
	v_mfma_f32_16x16x32_bf16 v[98:101], v[166:169], v[46:49], v[62:65]
	v_mfma_f32_16x16x32_bf16 v[94:97], v[162:165], v[46:49], v[66:69]
	v_mfma_f32_16x16x32_bf16 v[90:93], v[170:173], v[46:49], v[70:73]
	ds_read_b128 v[46:49], v234 offset:8192
	s_waitcnt lgkmcnt(2)
	v_mfma_f32_16x16x32_bf16 v[86:89], v[166:169], v[58:61], v[74:77]
	v_mfma_f32_16x16x32_bf16 v[82:85], v[162:165], v[58:61], v[78:81]
	s_waitcnt lgkmcnt(1)
	v_mfma_f32_16x16x32_bf16 v[78:81], v[166:169], v[42:45], v[126:129]
	v_mfma_f32_16x16x32_bf16 v[74:77], v[162:165], v[42:45], v[130:133]
	s_nop 1
	ds_read_b128 v[126:129], v234 offset:12288
	v_mfma_f32_16x16x32_bf16 v[70:73], v[170:173], v[42:45], v[134:137]
	ds_read_b128 v[42:45], v240 offset:12288
	v_mfma_f32_16x16x32_bf16 v[54:57], v[170:173], v[58:61], v[138:141]
	s_waitcnt lgkmcnt(2)
	v_mfma_f32_16x16x32_bf16 v[66:69], v[166:169], v[46:49], v[142:145]
	v_mfma_f32_16x16x32_bf16 v[62:65], v[162:165], v[46:49], v[146:149]
	v_mfma_f32_16x16x32_bf16 v[58:61], v[170:173], v[46:49], v[150:153]
	s_and_b64 vcc, exec, s[2:3]
	s_cbranch_vccnz .LBB0_305
	s_waitcnt vmcnt(6)
	ds_write_b128 v251, v[2:5] offset:49152
.LBB0_305:
	s_waitcnt vmcnt(6)
	s_waitcnt lgkmcnt(0)
	v_mfma_f32_16x16x32_bf16 v[50:53], v[166:169], v[42:45], v[50:53]
	global_load_dwordx4 v[2:5], v243, s[4:5]
	v_mfma_f32_16x16x32_bf16 v[46:49], v[162:165], v[42:45], v[154:157]
	v_mfma_f32_16x16x32_bf16 v[42:45], v[170:173], v[42:45], v[34:37]
	v_mfma_f32_16x16x32_bf16 v[38:41], v[166:169], v[126:129], v[38:41]
	v_mfma_f32_16x16x32_bf16 v[34:37], v[162:165], v[126:129], v[158:161]
	v_mfma_f32_16x16x32_bf16 v[30:33], v[170:173], v[126:129], v[30:33]
	s_setprio 0
	s_add_i32 s22, s46, 1
	s_cmp_lg_u32 s22, 16
	s_cbranch_scc1 .LBB0_309
	s_add_i32 s24, s24, s11
	s_cmpk_gt_i32 s24, 0x5f
	s_cbranch_scc1 .LBB0_308
	s_ashr_i32 s3, s24, 31
	s_lshr_b32 s3, s3, 27
	s_add_i32 s3, s24, s3
	s_ashr_i32 s3, s3, 5
	s_mov_b32 s2, s10
	s_lshl_b32 s4, s3, 6
	s_lshl_b32 s5, s24, 1
	s_sub_i32 s4, s5, s4
	s_and_b32 s2, s2, 7
	s_and_b32 s4, s4, -8
	s_lshl_b32 s3, s3, 2
	s_and_b32 s5, s24, 3
	s_or_b32 s43, s3, s5
	s_or_b32 s44, s2, s4

.LBB0_956:
	v_mov_b32_e32 v255, 0x8000
	v_bfe_u32 v1, v0, 0, 1
	v_lshlrev_b32_e32 v1, 7, v1
	v_xor_b32_e32 v255, v255, v1
	v_bfe_u32 v1, v0, 1, 3
	v_mul_u32_u24_e32 v1, 0x110, v1
	v_xor_b32_e32 v255, v255, v1
	v_bfe_u32 v1, v0, 4, 2
	v_lshlrev_b32_e32 v1, 4, v1
	v_xor_b32_e32 v255, v255, v1
	v_bfe_u32 v1, v0, 6, 2
	v_lshlrev_b32_e32 v1, 13, v1
	v_xor_b32_e32 v255, v255, v1
	v_mov_b32_e32 v254, 0x8880
	v_bfe_u32 v1, v0, 0, 1
	v_lshlrev_b32_e32 v1, 7, v1
	v_xor_b32_e32 v254, v254, v1
	v_bfe_u32 v1, v0, 1, 3
	v_mul_u32_u24_e32 v1, 0x110, v1
	v_xor_b32_e32 v254, v254, v1
	v_bfe_u32 v1, v0, 4, 2
	v_lshlrev_b32_e32 v1, 4, v1
	v_xor_b32_e32 v254, v254, v1
	v_bfe_u32 v1, v0, 6, 2
	v_lshlrev_b32_e32 v1, 13, v1
	v_xor_b32_e32 v254, v254, v1
	v_mov_b32_e32 v253, 0x880
	v_bfe_u32 v1, v0, 0, 1
	v_lshlrev_b32_e32 v1, 7, v1
	v_xor_b32_e32 v253, v253, v1
	v_bfe_u32 v1, v0, 1, 3
	v_mul_u32_u24_e32 v1, 0x110, v1
	v_xor_b32_e32 v253, v253, v1
	v_bfe_u32 v1, v0, 4, 2
	v_lshlrev_b32_e32 v1, 4, v1
	v_xor_b32_e32 v253, v253, v1
	v_bfe_u32 v1, v0, 8, 1
	v_lshlrev_b32_e32 v1, 14, v1
	v_xor_b32_e32 v253, v253, v1
	v_mov_b32_e32 v252, 0x0
	v_bfe_u32 v1, v0, 0, 1
	v_lshlrev_b32_e32 v1, 7, v1
	v_xor_b32_e32 v252, v252, v1
	v_bfe_u32 v1, v0, 1, 3
	v_mul_u32_u24_e32 v1, 0x110, v1
	v_xor_b32_e32 v252, v252, v1
	v_bfe_u32 v1, v0, 4, 2
	v_lshlrev_b32_e32 v1, 4, v1
	v_xor_b32_e32 v252, v252, v1
	v_bfe_u32 v1, v0, 8, 1
	v_lshlrev_b32_e32 v1, 14, v1
	v_xor_b32_e32 v252, v252, v1
	v_mov_b32_e32 v251, 0x0
	v_bfe_u32 v1, v0, 0, 4
	v_lshlrev_b32_e32 v1, 4, v1
	v_xor_b32_e32 v251, v251, v1
	v_bfe_u32 v1, v0, 4, 4
	v_mul_u32_u24_e32 v1, 0x110, v1
	v_xor_b32_e32 v251, v251, v1
	v_bfe_u32 v1, v0, 8, 1
	v_lshlrev_b32_e32 v1, 12, v1
	v_xor_b32_e32 v251, v251, v1
	v_mov_b32_e32 v250, 0x88c0
	v_bfe_u32 v1, v0, 0, 1
	v_lshlrev_b32_e32 v1, 7, v1
	v_xor_b32_e32 v250, v250, v1
	v_bfe_u32 v1, v0, 1, 3
	v_mul_u32_u24_e32 v1, 0x110, v1
	v_xor_b32_e32 v250, v250, v1
	v_bfe_u32 v1, v0, 4, 2
	v_lshlrev_b32_e32 v1, 4, v1
	v_xor_b32_e32 v250, v250, v1
	v_bfe_u32 v1, v0, 6, 2
	v_lshlrev_b32_e32 v1, 13, v1
	v_xor_b32_e32 v250, v250, v1
	v_mov_b32_e32 v249, 0x8040
	v_bfe_u32 v1, v0, 0, 1
	v_lshlrev_b32_e32 v1, 7, v1
	v_xor_b32_e32 v249, v249, v1
	v_bfe_u32 v1, v0, 1, 3
	v_mul_u32_u24_e32 v1, 0x110, v1
	v_xor_b32_e32 v249, v249, v1
	v_bfe_u32 v1, v0, 4, 2
	v_lshlrev_b32_e32 v1, 4, v1
	v_xor_b32_e32 v249, v249, v1
	v_bfe_u32 v1, v0, 6, 2
	v_lshlrev_b32_e32 v1, 13, v1
	v_xor_b32_e32 v249, v249, v1
	v_mov_b32_e32 v248, 0x8c0
	v_bfe_u32 v1, v0, 0, 1
	v_lshlrev_b32_e32 v1, 7, v1
	v_xor_b32_e32 v248, v248, v1
	v_bfe_u32 v1, v0, 1, 3
	v_mul_u32_u24_e32 v1, 0x110, v1
	v_xor_b32_e32 v248, v248, v1
	v_bfe_u32 v1, v0, 4, 2
	v_lshlrev_b32_e32 v1, 4, v1
	v_xor_b32_e32 v248, v248, v1
	v_bfe_u32 v1, v0, 8, 1
	v_lshlrev_b32_e32 v1, 14, v1
	v_xor_b32_e32 v248, v248, v1
	v_mov_b32_e32 v247, 0x40
	v_bfe_u32 v1, v0, 0, 1
	v_lshlrev_b32_e32 v1, 7, v1
	v_xor_b32_e32 v247, v247, v1
	v_bfe_u32 v1, v0, 1, 3
	v_mul_u32_u24_e32 v1, 0x110, v1
	v_xor_b32_e32 v247, v247, v1
	v_bfe_u32 v1, v0, 4, 2
	v_lshlrev_b32_e32 v1, 4, v1
	v_xor_b32_e32 v247, v247, v1
	v_bfe_u32 v1, v0, 8, 1
	v_lshlrev_b32_e32 v1, 14, v1
	v_xor_b32_e32 v247, v247, v1
	v_mov_b32_e32 v246, 0x0
	v_bfe_u32 v1, v0, 0, 3
	v_lshlrev_b32_e32 v1, 4, v1
	v_add_u32_e32 v246, v246, v1
	v_bfe_u32 v1, v0, 3, 6
	v_lshlrev_b32_e32 v1, 11, v1
	v_add_u32_e32 v246, v246, v1
	v_mov_b32_e32 v245, 0x10000
	v_bfe_u32 v1, v0, 0, 4
	v_lshlrev_b32_e32 v1, 4, v1
	v_xor_b32_e32 v245, v245, v1
	v_bfe_u32 v1, v0, 4, 4
	v_mul_u32_u24_e32 v1, 0x110, v1
	v_xor_b32_e32 v245, v245, v1
	v_bfe_u32 v1, v0, 8, 1
	v_lshlrev_b32_e32 v1, 12, v1
	v_xor_b32_e32 v245, v245, v1
	v_mov_b32_e32 v244, 0x20000
	v_bfe_u32 v1, v0, 0, 3
	v_lshlrev_b32_e32 v1, 4, v1
	v_add_u32_e32 v244, v244, v1
	v_bfe_u32 v1, v0, 3, 6
	v_lshlrev_b32_e32 v1, 11, v1
	v_add_u32_e32 v244, v244, v1
	v_mov_b32_e32 v243, 0x40000
	v_bfe_u32 v1, v0, 0, 3
	v_lshlrev_b32_e32 v1, 4, v1
	v_add_u32_e32 v243, v243, v1
	v_bfe_u32 v1, v0, 3, 6
	v_lshlrev_b32_e32 v1, 11, v1
	v_add_u32_e32 v243, v243, v1
	v_mov_b32_e32 v1, v0
	s_load_dword s2, s[0:1], 0xe0
	s_mov_b32 s3, s10
	v_mov_b32_e32 v1, v0
	s_waitcnt lgkmcnt(0)
	s_lshr_b32 s11, s2, 3
	s_waitcnt vmcnt(0)
	v_cvt_f32_u32_e32 v2, s11
	s_mov_b32 s2, s10
	s_ashr_i32 s3, s2, 3
	v_rcp_iflag_f32_e32 v2, v2
	s_ashr_i32 s4, s2, 31
	s_sub_i32 s2, 0, s11
	s_abs_i32 s3, s3
	v_mul_f32_e32 v1, 0x4f7ffffe, v2
	v_cvt_u32_f32_e32 v1, v1
	s_mov_b32 s52, 0
	v_readfirstlane_b32 s5, v1
	s_mul_i32 s2, s2, s5
	s_mul_hi_u32 s2, s5, s2
	s_add_i32 s2, s5, s2
	s_mul_hi_u32 s5, s3, s2
	s_mul_i32 s5, s5, s11
	s_sub_i32 s3, s3, s5
	s_sub_i32 s5, s3, s11
	s_cmp_ge_u32 s3, s11
	s_cselect_b32 s3, s5, s3
	s_sub_i32 s5, s3, s11
	s_cmp_ge_u32 s3, s11
	s_cselect_b32 s3, s5, s3
	s_xor_b32 s3, s3, s4
	s_sub_i32 s30, s3, s4
	s_mov_b32 s3, s10
	s_cmp_gt_i32 s30, 31
	s_cbranch_scc1 .LBB0_1020
	s_load_dwordx4 s[4:7], s[16:17], 0xc8
	s_load_dwordx4 s[12:15], s[16:17], 0x0
	s_mov_b32 s3, s10
	v_mov_b32_e32 v82, 0
	s_waitcnt lgkmcnt(0)
	s_add_u32 s31, s6, 0x17f0000
	s_addc_u32 s33, s7, 0
	s_add_u32 s20, s6, 0x6000
	s_addc_u32 s21, s7, 0
	s_add_u32 s34, s6, 0x570000
	s_addc_u32 s35, s7, 0
	s_ashr_i32 s6, s30, 31
	s_lshr_b32 s6, s6, 27
	s_add_i32 s6, s30, s6
	s_ashr_i32 s6, s6, 5
	s_lshl_b32 s7, s6, 6
	s_lshl_b32 s22, s30, 1
	s_sub_i32 s7, s22, s7
	s_lshl_b32 s6, s6, 2
	s_and_b32 s22, s30, 3
	s_or_b32 s36, s6, s22
	s_sub_i32 s6, s11, s30
	s_add_i32 s6, s6, 31
	s_mul_hi_u32 s2, s6, s2
	s_mul_i32 s22, s2, s11
	s_sub_i32 s6, s6, s22
	s_add_i32 s22, s2, 1
	s_sub_i32 s23, s6, s11
	s_cmp_ge_u32 s6, s11
	s_cselect_b32 s2, s22, s2
	s_cselect_b32 s6, s23, s6
	s_add_i32 s22, s2, 1
	s_cmp_ge_u32 s6, s11
	s_cselect_b32 s2, s22, s2
	s_and_b32 s3, s3, 7
	s_and_b32 s6, s7, -8
	s_lshl_b32 s37, s2, 4
	v_mov_b32_e32 v1, v0
	s_lshl_b32 s2, s36, 8
	s_or_b32 s38, s3, s6
	s_ashr_i32 s3, s2, 31
	s_lshl_b64 s[2:3], s[2:3], 11
	v_lshlrev_b32_e32 v2, 8, v1
	v_lshlrev_b32_e32 v1, 4, v1
	s_add_u32 s2, s34, s2
	v_and_b32_e32 v1, 0x70, v1
	s_movk_i32 s39, 0xf800
	v_mov_b32_e32 v239, 0
	s_addc_u32 s3, s35, s3
	v_and_or_b32 v238, v2, s39, v1
	v_lshl_add_u64 v[10:11], s[2:3], 0, v[238:239]
	s_mov_b32 s40, 0x60000
	v_add_co_u32_e32 v12, vcc, s40, v10
	s_lshl_b32 s6, s38, 8
	s_nop 0
	v_addc_co_u32_e32 v13, vcc, 0, v11, vcc
	s_mov_b32 s22, 0x40000
	s_ashr_i32 s7, s6, 31
	v_add_co_u32_e32 v14, vcc, s22, v10
	s_lshl_b64 s[6:7], s[6:7], 11
	s_nop 0
	v_addc_co_u32_e32 v15, vcc, 0, v11, vcc
	s_mov_b32 s41, 0x20000
	s_add_u32 s6, s31, s6
	v_add_co_u32_e32 v18, vcc, s41, v10
	s_addc_u32 s7, s33, s7
	s_nop 0
	v_addc_co_u32_e32 v19, vcc, 0, v11, vcc
	v_lshl_add_u64 v[30:31], s[6:7], 0, v[238:239]
	v_add_co_u32_e32 v32, vcc, s22, v30
	global_load_dwordx4 v[2:5], v[12:13], off
	global_load_dwordx4 v[6:9], v[14:15], off
	v_addc_co_u32_e32 v33, vcc, 0, v31, vcc
	v_add_co_u32_e32 v34, vcc, s41, v30
	global_load_dwordx4 v[10:13], v[18:19], off
	global_load_dwordx4 v[14:17], v238, s[2:3]
	v_addc_co_u32_e32 v35, vcc, 0, v31, vcc
	global_load_dwordx4 v[18:21], v[32:33], off
	global_load_dwordx4 v[22:25], v[34:35], off
	global_load_dwordx4 v[26:29], v238, s[6:7]
	v_add_co_u32_e32 v30, vcc, s40, v30
	v_mov_b32_e32 v1, v0
	s_nop 0
	v_addc_co_u32_e32 v31, vcc, 0, v31, vcc
	global_load_dwordx4 v[30:33], v[30:31], off
	s_movk_i32 s43, 0xf0
	v_ashrrev_i32_e32 v35, 4, v1
	v_xor_b32_e32 v1, v35, v1
	v_lshlrev_b32_e32 v35, 8, v35
	v_lshlrev_b32_e32 v1, 4, v1
	v_mov_b32_e32 v34, v0
	v_and_or_b32 v1, v1, s43, v35
	s_mov_b32 s42, 2
	s_movk_i32 s44, 0xff80
	s_mov_b32 s45, 0x10000
	s_mov_b32 s46, 0x11000
	s_movk_i32 s47, 0x1800
	s_movk_i32 s48, 0x1fff
	v_mov_b32_e32 v240, 0x8040
	s_mov_b32 s28, 2
	s_mov_b32 s49, s30
	s_mov_b32 s50, s36
	s_mov_b32 s51, s38
	v_mov_b32_e32 v83, v82
	v_mov_b32_e32 v84, v82
	v_mov_b32_e32 v85, v82
	v_mov_b32_e32 v102, v82
	v_mov_b32_e32 v103, v82
	v_mov_b32_e32 v104, v82
	v_mov_b32_e32 v105, v82
	v_mov_b32_e32 v106, v82
	v_mov_b32_e32 v107, v82
	v_mov_b32_e32 v108, v82
	v_mov_b32_e32 v109, v82
	v_mov_b32_e32 v110, v82
	s_waitcnt vmcnt(4)
	ds_write_b128 v1, v[14:17] offset:32768
	ds_write_b128 v1, v[10:13] offset:40960
	ds_write_b128 v1, v[6:9] offset:49152
	ds_write_b128 v1, v[2:5] offset:57344
	s_waitcnt vmcnt(1)
	ds_write_b128 v1, v[26:29]
	ds_write_b128 v1, v[22:25] offset:8192
	ds_write_b128 v1, v[18:21] offset:16384
	s_waitcnt vmcnt(0)
	ds_write_b128 v1, v[30:33] offset:24576
	v_mov_b32_e32 v111, v82
	v_lshlrev_b32_e32 v2, 4, v34
	v_lshlrev_b32_e32 v1, 8, v34
	v_and_b32_e32 v2, 0x70, v2
	v_and_or_b32 v238, v1, s39, v2
	v_lshl_add_u64 v[10:11], s[2:3], 0, v[238:239]
	v_add_co_u32_e32 v12, vcc, s40, v10
	v_lshl_add_u64 v[16:17], s[6:7], 0, v[238:239]
	s_nop 0
	v_addc_co_u32_e32 v13, vcc, 0, v11, vcc
	v_add_co_u32_e32 v14, vcc, s22, v10
	v_mov_b32_e32 v1, 0x10000
	s_nop 0
	v_addc_co_u32_e32 v15, vcc, 0, v11, vcc
	global_load_dwordx4 v[2:5], v[12:13], off offset:128
	global_load_dwordx4 v[6:9], v[14:15], off offset:128
	v_add_co_u32_e32 v14, vcc, s41, v10
	v_mov_b32_e32 v112, v82
	s_nop 0
	v_addc_co_u32_e32 v15, vcc, 0, v11, vcc
	v_add_co_u32_e32 v22, vcc, s40, v16
	v_mov_b32_e32 v113, v82
	s_nop 0
	v_addc_co_u32_e32 v23, vcc, 0, v17, vcc
	v_add_co_u32_e32 v34, vcc, s22, v16
	global_load_dwordx4 v[10:13], v[14:15], off offset:128
	global_load_dwordx4 v[18:21], v[22:23], off offset:128
	v_addc_co_u32_e32 v35, vcc, 0, v17, vcc
	v_add_co_u32_e32 v36, vcc, s41, v16
	v_mov_b32_e32 v114, v82
	s_nop 0
	v_addc_co_u32_e32 v37, vcc, 0, v17, vcc
	global_load_dwordx4 v[22:25], v[34:35], off offset:128
	global_load_dwordx4 v[26:29], v[36:37], off offset:128
	global_load_dwordx4 v[14:17], v238, s[2:3] offset:128
	global_load_dwordx4 v[30:33], v238, s[6:7] offset:128
	v_mov_b32_e32 v115, v82
	v_mov_b32_e32 v116, v82
	v_mov_b32_e32 v117, v82
	v_mov_b32_e32 v118, v82
	v_mov_b32_e32 v119, v82
	v_mov_b32_e32 v120, v82
	v_mov_b32_e32 v121, v82
	v_mov_b32_e32 v122, v82
	v_mov_b32_e32 v123, v82
	v_mov_b32_e32 v124, v82
	v_mov_b32_e32 v125, v82
	v_mov_b32_e32 v126, v82
	v_mov_b32_e32 v127, v82
	v_mov_b32_e32 v128, v82
	v_mov_b32_e32 v129, v82
	v_mov_b32_e32 v130, v82
	v_mov_b32_e32 v131, v82
	v_mov_b32_e32 v132, v82
	v_mov_b32_e32 v133, v82
	v_mov_b32_e32 v134, v82
	v_mov_b32_e32 v135, v82
	v_mov_b32_e32 v136, v82
	v_mov_b32_e32 v137, v82
	v_mov_b32_e32 v138, v82
	v_mov_b32_e32 v139, v82
	v_mov_b32_e32 v140, v82
	v_mov_b32_e32 v141, v82
	v_mov_b32_e32 v142, v82
	v_mov_b32_e32 v143, v82
	v_mov_b32_e32 v144, v82
	v_mov_b32_e32 v145, v82
	v_mov_b32_e32 v146, v82
	v_mov_b32_e32 v147, v82
	v_mov_b32_e32 v148, v82
	v_mov_b32_e32 v149, v82
	v_mov_b32_e32 v150, v82
	v_mov_b32_e32 v151, v82
	v_mov_b32_e32 v152, v82
	v_mov_b32_e32 v153, v82
	v_mov_b32_e32 v154, v82
	v_mov_b32_e32 v155, v82
	v_mov_b32_e32 v156, v82
	v_mov_b32_e32 v157, v82
	v_mov_b32_e32 v158, v82
	v_mov_b32_e32 v159, v82
	v_mov_b32_e32 v160, v82
	v_mov_b32_e32 v161, v82
	v_mov_b32_e32 v98, v82
	v_mov_b32_e32 v99, v82
	v_mov_b32_e32 v100, v82
	v_mov_b32_e32 v101, v82
	v_mov_b32_e32 v94, v82
	v_mov_b32_e32 v95, v82
	v_mov_b32_e32 v96, v82
	v_mov_b32_e32 v97, v82
	v_mov_b32_e32 v90, v82
	v_mov_b32_e32 v91, v82
	v_mov_b32_e32 v92, v82
	v_mov_b32_e32 v93, v82
	v_mov_b32_e32 v86, v82
	v_mov_b32_e32 v87, v82
	v_mov_b32_e32 v88, v82
	v_mov_b32_e32 v89, v82
	v_mov_b32_e32 v78, v82
	v_mov_b32_e32 v79, v82
	v_mov_b32_e32 v80, v82
	v_mov_b32_e32 v81, v82
	v_mov_b32_e32 v74, v82
	v_mov_b32_e32 v75, v82
	v_mov_b32_e32 v76, v82
	v_mov_b32_e32 v77, v82
	v_mov_b32_e32 v70, v82
	v_mov_b32_e32 v71, v82
	v_mov_b32_e32 v72, v82
	v_mov_b32_e32 v73, v82
	v_mov_b32_e32 v66, v82
	v_mov_b32_e32 v67, v82
	v_mov_b32_e32 v68, v82
	v_mov_b32_e32 v69, v82
	v_mov_b32_e32 v62, v82
	v_mov_b32_e32 v63, v82
	v_mov_b32_e32 v64, v82
	v_mov_b32_e32 v65, v82
	v_mov_b32_e32 v58, v82
	v_mov_b32_e32 v59, v82
	v_mov_b32_e32 v60, v82
	v_mov_b32_e32 v61, v82
	v_mov_b32_e32 v54, v82
	v_mov_b32_e32 v55, v82
	v_mov_b32_e32 v56, v82
	v_mov_b32_e32 v57, v82
	v_mov_b32_e32 v50, v82
	v_mov_b32_e32 v51, v82
	v_mov_b32_e32 v52, v82
	v_mov_b32_e32 v53, v82
	v_mov_b32_e32 v46, v82
	v_mov_b32_e32 v47, v82
	v_mov_b32_e32 v48, v82
	v_mov_b32_e32 v49, v82
	v_mov_b32_e32 v42, v82
	v_mov_b32_e32 v43, v82
	v_mov_b32_e32 v44, v82
	v_mov_b32_e32 v45, v82
	v_mov_b32_e32 v38, v82
	v_mov_b32_e32 v39, v82
	v_mov_b32_e32 v40, v82
	v_mov_b32_e32 v41, v82
	v_mov_b32_e32 v34, v82
	v_mov_b32_e32 v35, v82
	v_mov_b32_e32 v36, v82
	v_mov_b32_e32 v37, v82
	s_waitcnt lgkmcnt(0)
	s_barrier
	s_branch .LBB0_960

.LBB0_960:
	s_add_i32 s2, s42, -1
	ds_read_b128 v[174:177], v255
	ds_read_b128 v[166:169], v255 offset:4096
	ds_read_b128 v[170:173], v254
	ds_read_b128 v[162:165], v254 offset:4096
	ds_read_b128 v[194:197], v253
	ds_read_b128 v[182:185], v252
	ds_read_b128 v[178:181], v252 offset:4096
	s_setprio 1
	s_waitcnt lgkmcnt(1)
	v_mfma_f32_16x16x32_bf16 v[158:161], v[174:177], v[182:185], v[158:161]
	s_cmp_lt_i32 s2, s37
	s_cselect_b64 s[24:25], -1, 0
	s_cmp_ge_i32 s2, s37
	v_mfma_f32_16x16x32_bf16 v[154:157], v[170:173], v[182:185], v[154:157]
	v_mfma_f32_16x16x32_bf16 v[150:153], v[166:169], v[182:185], v[150:153]
	v_mfma_f32_16x16x32_bf16 v[146:149], v[162:165], v[182:185], v[146:149]
	ds_read_b128 v[186:189], v253 offset:4096
	ds_read_b128 v[182:185], v252 offset:8192
	v_mfma_f32_16x16x32_bf16 v[142:145], v[174:177], v[194:197], v[142:145]
	v_mfma_f32_16x16x32_bf16 v[138:141], v[170:173], v[194:197], v[138:141]
	v_mfma_f32_16x16x32_bf16 v[134:137], v[166:169], v[194:197], v[134:137]
	v_mfma_f32_16x16x32_bf16 v[130:133], v[162:165], v[194:197], v[130:133]
	s_cbranch_scc1 .LBB0_962
	s_waitcnt vmcnt(0)
	ds_write_b128 v245, v[30:33]
	ds_write_b128 v245, v[26:29] offset:8192
.LBB0_962:
	s_lshl_b32 s6, s51, 8
	s_ashr_i32 s7, s6, 31
	s_lshl_b32 s2, s28, 6
	s_ashr_i32 s3, s2, 31
	s_lshl_b64 s[22:23], s[6:7], 11
	s_add_u32 s26, s31, s22
	s_addc_u32 s27, s33, s23
	s_lshl_b64 s[22:23], s[2:3], 1
	s_waitcnt vmcnt(2)
	s_add_u32 s26, s26, s22
	s_addc_u32 s27, s27, s23
	s_waitcnt vmcnt(0)
	s_nop 0
	s_waitcnt lgkmcnt(2)
	v_mfma_f32_16x16x32_bf16 v[126:129], v[174:177], v[178:181], v[126:129]
	global_load_dwordx4 v[30:33], v244, s[26:27]
	v_mfma_f32_16x16x32_bf16 v[122:125], v[170:173], v[178:181], v[122:125]
	v_mfma_f32_16x16x32_bf16 v[118:121], v[166:169], v[178:181], v[118:121]
	v_mfma_f32_16x16x32_bf16 v[114:117], v[162:165], v[178:181], v[114:117]
	s_waitcnt lgkmcnt(0)
	v_mfma_f32_16x16x32_bf16 v[98:101], v[174:177], v[182:185], v[98:101]
	v_mfma_f32_16x16x32_bf16 v[94:97], v[170:173], v[182:185], v[94:97]
	v_mfma_f32_16x16x32_bf16 v[178:181], v[166:169], v[182:185], v[90:93]
	s_nop 2
	ds_read_b128 v[90:93], v253 offset:8192
	v_mfma_f32_16x16x32_bf16 v[182:185], v[162:165], v[182:185], v[86:89]
	s_nop 2
	ds_read_b128 v[86:89], v253 offset:12288
	global_load_dwordx4 v[26:29], v246, s[26:27]
	v_mfma_f32_16x16x32_bf16 v[110:113], v[174:177], v[186:189], v[110:113]
	v_mfma_f32_16x16x32_bf16 v[106:109], v[170:173], v[186:189], v[106:109]
	v_mfma_f32_16x16x32_bf16 v[102:105], v[166:169], v[186:189], v[102:105]
	v_mfma_f32_16x16x32_bf16 v[82:85], v[162:165], v[186:189], v[82:85]
	s_waitcnt lgkmcnt(1)
	v_mfma_f32_16x16x32_bf16 v[186:189], v[166:169], v[90:93], v[70:73]
	s_nop 2
	ds_read_b128 v[70:73], v252 offset:12288
	v_mfma_f32_16x16x32_bf16 v[78:81], v[174:177], v[90:93], v[78:81]
	v_mfma_f32_16x16x32_bf16 v[74:77], v[170:173], v[90:93], v[74:77]
	v_mfma_f32_16x16x32_bf16 v[190:193], v[162:165], v[90:93], v[66:69]
	s_nop 2
	v_cndmask_b32_e64 v67, 0, 1, s[24:25]
	v_cmp_ne_u32_e64 s[2:3], 1, v67
	s_andn2_b64 vcc, exec, s[24:25]
	s_cbranch_vccnz .LBB0_964
	ds_write_b128 v245, v[22:25] offset:16384
	ds_write_b128 v245, v[18:21] offset:24576
.LBB0_964:
	s_waitcnt lgkmcnt(0)
	v_mfma_f32_16x16x32_bf16 v[194:197], v[174:177], v[70:73], v[62:65]
	v_mfma_f32_16x16x32_bf16 v[198:201], v[170:173], v[70:73], v[58:61]
	s_nop 0
	global_load_dwordx4 v[18:21], v243, s[26:27]
	s_nop 0
	v_add_u32_e32 v22, 0x60000, v246
	global_load_dwordx4 v[22:25], v22, s[26:27]
	v_mfma_f32_16x16x32_bf16 v[202:205], v[166:169], v[70:73], v[54:57]
	v_mfma_f32_16x16x32_bf16 v[206:209], v[162:165], v[70:73], v[50:53]
	v_mfma_f32_16x16x32_bf16 v[174:177], v[174:177], v[86:89], v[46:49]
	v_mfma_f32_16x16x32_bf16 v[170:173], v[170:173], v[86:89], v[42:45]
	v_mfma_f32_16x16x32_bf16 v[166:169], v[166:169], v[86:89], v[38:41]
	v_mfma_f32_16x16x32_bf16 v[162:165], v[162:165], v[86:89], v[34:37]
	s_setprio 0
	s_nop 1
	s_nop 0
	ds_read_b128 v[218:221], v250
	ds_read_b128 v[214:217], v249 offset:4096
	ds_read_b128 v[210:213], v250 offset:4096
	ds_read_b128 v[222:225], v249
	ds_read_b128 v[34:37], v248
	ds_read_b128 v[38:41], v247
	ds_read_b128 v[54:57], v247 offset:4096
	s_setprio 1
	s_waitcnt lgkmcnt(1)
	v_mfma_f32_16x16x32_bf16 v[158:161], v[222:225], v[38:41], v[158:161]
	v_mfma_f32_16x16x32_bf16 v[154:157], v[218:221], v[38:41], v[154:157]
	v_mfma_f32_16x16x32_bf16 v[150:153], v[214:217], v[38:41], v[150:153]
	v_mfma_f32_16x16x32_bf16 v[146:149], v[210:213], v[38:41], v[146:149]
	v_mfma_f32_16x16x32_bf16 v[38:41], v[214:217], v[34:37], v[134:137]
	ds_read_b128 v[70:73], v248 offset:4096
	s_nop 1
	ds_read_b128 v[134:137], v247 offset:8192
	v_mfma_f32_16x16x32_bf16 v[142:145], v[222:225], v[34:37], v[142:145]
	v_mfma_f32_16x16x32_bf16 v[138:141], v[218:221], v[34:37], v[138:141]
	v_mfma_f32_16x16x32_bf16 v[34:37], v[210:213], v[34:37], v[130:133]
	s_nop 2
	s_and_b64 vcc, exec, s[2:3]
	s_cbranch_vccnz .LBB0_966
	ds_write_b128 v245, v[14:17] offset:32768
	ds_write_b128 v245, v[10:13] offset:40960
.LBB0_966:
	s_lshl_b32 s24, s50, 8
	s_ashr_i32 s25, s24, 31
	s_lshl_b64 s[26:27], s[24:25], 11
	s_add_u32 s26, s34, s26
	s_addc_u32 s27, s35, s27
	s_add_u32 s22, s26, s22
	s_addc_u32 s23, s27, s23
	s_waitcnt lgkmcnt(2)
	v_mfma_f32_16x16x32_bf16 v[50:53], v[214:217], v[54:57], v[118:121]
	s_waitcnt lgkmcnt(1)
	v_mfma_f32_16x16x32_bf16 v[58:61], v[222:225], v[70:73], v[110:113]
	ds_read_b128 v[118:121], v247 offset:12288
	v_mfma_f32_16x16x32_bf16 v[62:65], v[218:221], v[70:73], v[106:109]
	v_mfma_f32_16x16x32_bf16 v[66:69], v[214:217], v[70:73], v[102:105]
	v_mfma_f32_16x16x32_bf16 v[70:73], v[210:213], v[70:73], v[82:85]
	s_nop 2
	ds_read_b128 v[82:85], v248 offset:8192
	global_load_dwordx4 v[10:13], v246, s[22:23]
	s_nop 0
	global_load_dwordx4 v[14:17], v244, s[22:23]
	s_waitcnt lgkmcnt(2)
	v_mfma_f32_16x16x32_bf16 v[86:89], v[222:225], v[134:137], v[98:101]
	v_mfma_f32_16x16x32_bf16 v[90:93], v[218:221], v[134:137], v[94:97]
	v_mfma_f32_16x16x32_bf16 v[94:97], v[214:217], v[134:137], v[178:181]
	v_mfma_f32_16x16x32_bf16 v[98:101], v[210:213], v[134:137], v[182:185]
	ds_read_b128 v[134:137], v248 offset:12288
	v_mfma_f32_16x16x32_bf16 v[42:45], v[222:225], v[54:57], v[126:129]
	v_mfma_f32_16x16x32_bf16 v[46:49], v[218:221], v[54:57], v[122:125]
	v_mfma_f32_16x16x32_bf16 v[54:57], v[210:213], v[54:57], v[114:117]
	s_waitcnt lgkmcnt(1)
	v_mfma_f32_16x16x32_bf16 v[102:105], v[222:225], v[82:85], v[78:81]
	v_mfma_f32_16x16x32_bf16 v[74:77], v[218:221], v[82:85], v[74:77]
	v_mfma_f32_16x16x32_bf16 v[78:81], v[214:217], v[82:85], v[186:189]
	v_mfma_f32_16x16x32_bf16 v[82:85], v[210:213], v[82:85], v[190:193]
	s_and_b64 vcc, exec, s[2:3]
	s_cbranch_vccnz .LBB0_968
	ds_write_b128 v245, v[6:9] offset:49152
	ds_write_b128 v245, v[2:5] offset:57344
.LBB0_968:
	v_mfma_f32_16x16x32_bf16 v[106:109], v[222:225], v[118:121], v[194:197]
	s_nop 0
	v_mfma_f32_16x16x32_bf16 v[110:113], v[218:221], v[118:121], v[198:201]
	s_nop 0
	global_load_dwordx4 v[2:5], v243, s[22:23]
	s_nop 0
	v_add_u32_e32 v6, 0x60000, v246
	global_load_dwordx4 v[6:9], v6, s[22:23]
	v_mfma_f32_16x16x32_bf16 v[114:117], v[214:217], v[118:121], v[202:205]
	s_lshl_b64 s[2:3], s[6:7], 10
	s_lshl_b64 s[22:23], s[24:25], 10
	v_mfma_f32_16x16x32_bf16 v[118:121], v[210:213], v[118:121], v[206:209]
	s_waitcnt lgkmcnt(0)
	v_mfma_f32_16x16x32_bf16 v[122:125], v[222:225], v[134:137], v[174:177]
	v_mfma_f32_16x16x32_bf16 v[126:129], v[218:221], v[134:137], v[170:173]
	v_mfma_f32_16x16x32_bf16 v[130:133], v[214:217], v[134:137], v[166:169]
	v_mfma_f32_16x16x32_bf16 v[134:137], v[210:213], v[134:137], v[162:165]
	s_setprio 0
	s_add_i32 s53, s28, 1
	s_cmp_lg_u32 s53, 16
	s_cbranch_scc1 .LBB0_972
	s_add_i32 s30, s30, s11
	s_cmp_gt_i32 s30, 31
	s_cbranch_scc1 .LBB0_971
	s_ashr_i32 s3, s30, 31
	s_lshr_b32 s3, s3, 27
	s_add_i32 s3, s30, s3
	s_ashr_i32 s3, s3, 5
	s_mov_b32 s2, s10
	s_lshl_b32 s6, s3, 6
	s_lshl_b32 s7, s30, 1
	s_sub_i32 s6, s7, s6
	s_and_b32 s2, s2, 7
	s_and_b32 s6, s6, -8
	s_lshl_b32 s3, s3, 2
	s_and_b32 s7, s30, 3
	s_or_b32 s50, s3, s7
	s_or_b32 s51, s2, s6
	s_lshl_b32 s2, s51, 8
	s_lshl_b32 s6, s50, 8
	s_ashr_i32 s3, s2, 31
	s_ashr_i32 s7, s6, 31
	s_lshl_b64 s[2:3], s[2:3], 10
	s_lshl_b64 s[22:23], s[6:7], 10

.LBB0_972:
	s_barrier
	s_nop 0
	v_add_u32_e32 v170, 0x10000, v255
	v_add_u32_e32 v162, 0x11000, v255
	v_add_u32_e32 v171, 0x10000, v254
	ds_read_b128 v[206:209], v170
	ds_read_b128 v[210:213], v171
	v_add_u32_e32 v169, 0x11000, v254
	ds_read_b128 v[214:217], v162
	ds_read_b128 v[218:221], v169
	v_add_u32_e32 v186, 0x10000, v253
	v_add_u32_e32 v187, 0x10000, v252
	ds_read_b128 v[162:165], v186
	ds_read_b128 v[166:169], v187
	ds_read_b128 v[174:177], v187 offset:4096
	s_setprio 1
	ds_read_b128 v[182:185], v186 offset:4096
	ds_read_b128 v[178:181], v187 offset:8192
	s_waitcnt lgkmcnt(3)
	v_mfma_f32_16x16x32_bf16 v[158:161], v[206:209], v[166:169], v[158:161]
	s_cmp_lt_i32 s42, s37
	s_cselect_b64 s[26:27], -1, 0
	s_cmp_ge_i32 s42, s37
	v_mfma_f32_16x16x32_bf16 v[154:157], v[210:213], v[166:169], v[154:157]
	s_cselect_b64 s[6:7], -1, 0
	v_mfma_f32_16x16x32_bf16 v[150:153], v[214:217], v[166:169], v[150:153]
	v_mfma_f32_16x16x32_bf16 v[146:149], v[218:221], v[166:169], v[146:149]
	v_mfma_f32_16x16x32_bf16 v[142:145], v[206:209], v[162:165], v[142:145]
	v_mfma_f32_16x16x32_bf16 v[138:141], v[210:213], v[162:165], v[138:141]
	v_mfma_f32_16x16x32_bf16 v[38:41], v[214:217], v[162:165], v[38:41]
	v_mfma_f32_16x16x32_bf16 v[34:37], v[218:221], v[162:165], v[34:37]
	s_and_b64 vcc, exec, s[6:7]
	s_cbranch_vccnz .LBB0_974
	s_waitcnt vmcnt(6)
	ds_write_b128 v251, v[26:29]
	ds_write_b128 v251, v[30:33] offset:8192
.LBB0_974:
	s_lshl_b32 s24, s53, 6
	s_ashr_i32 s25, s24, 31
	s_lshl_b64 s[2:3], s[2:3], 1
	s_add_u32 s2, s31, s2
	s_addc_u32 s3, s33, s3
	s_lshl_b64 s[24:25], s[24:25], 1
	s_waitcnt vmcnt(6)
	s_add_u32 s28, s2, s24
	s_addc_u32 s29, s3, s25
	s_waitcnt lgkmcnt(2)
	v_mfma_f32_16x16x32_bf16 v[162:165], v[206:209], v[174:177], v[42:45]
	v_mfma_f32_16x16x32_bf16 v[166:169], v[210:213], v[174:177], v[46:49]
	s_waitcnt lgkmcnt(0)
	v_mfma_f32_16x16x32_bf16 v[42:45], v[206:209], v[178:181], v[86:89]
	v_mfma_f32_16x16x32_bf16 v[46:49], v[210:213], v[178:181], v[90:93]
	s_nop 1
	ds_read_b128 v[86:89], v187 offset:12288
	ds_read_b128 v[90:93], v186 offset:8192
	global_load_dwordx4 v[30:33], v246, s[28:29]
	s_nop 0
	global_load_dwordx4 v[26:29], v244, s[28:29]
	v_mfma_f32_16x16x32_bf16 v[58:61], v[206:209], v[182:185], v[58:61]
	v_mfma_f32_16x16x32_bf16 v[62:65], v[210:213], v[182:185], v[62:65]
	v_mfma_f32_16x16x32_bf16 v[66:69], v[214:217], v[182:185], v[66:69]
	v_mfma_f32_16x16x32_bf16 v[70:73], v[218:221], v[182:185], v[70:73]
	s_waitcnt lgkmcnt(0)
	v_mfma_f32_16x16x32_bf16 v[182:185], v[214:217], v[90:93], v[78:81]
	s_nop 2
	ds_read_b128 v[78:81], v186 offset:12288
	v_mfma_f32_16x16x32_bf16 v[170:173], v[214:217], v[174:177], v[50:53]
	v_mfma_f32_16x16x32_bf16 v[174:177], v[218:221], v[174:177], v[54:57]
	v_mfma_f32_16x16x32_bf16 v[50:53], v[214:217], v[178:181], v[94:97]
	v_mfma_f32_16x16x32_bf16 v[54:57], v[218:221], v[178:181], v[98:101]
	v_mfma_f32_16x16x32_bf16 v[178:181], v[206:209], v[90:93], v[102:105]
	v_mfma_f32_16x16x32_bf16 v[74:77], v[210:213], v[90:93], v[74:77]
	v_mfma_f32_16x16x32_bf16 v[186:189], v[218:221], v[90:93], v[82:85]
	s_nop 2
	v_cndmask_b32_e64 v83, 0, 1, s[26:27]
	v_cmp_ne_u32_e64 s[2:3], 1, v83
	s_andn2_b64 vcc, exec, s[26:27]
	s_cbranch_vccnz .LBB0_976
	s_waitcnt vmcnt(7)
	ds_write_b128 v251, v[18:21] offset:16384
	s_waitcnt vmcnt(6)
	ds_write_b128 v251, v[22:25] offset:24576
.LBB0_976:
	s_waitcnt vmcnt(7)
	v_mfma_f32_16x16x32_bf16 v[190:193], v[206:209], v[86:89], v[106:109]
	s_nop 0
	v_mfma_f32_16x16x32_bf16 v[194:197], v[210:213], v[86:89], v[110:113]
	s_nop 0
	global_load_dwordx4 v[22:25], v243, s[28:29]
	s_nop 0
	v_add_u32_e32 v18, 0x60000, v246
	global_load_dwordx4 v[18:21], v18, s[28:29]
	v_mfma_f32_16x16x32_bf16 v[198:201], v[214:217], v[86:89], v[114:117]
	v_mfma_f32_16x16x32_bf16 v[202:205], v[218:221], v[86:89], v[118:121]
	s_waitcnt lgkmcnt(0)
	v_mfma_f32_16x16x32_bf16 v[206:209], v[206:209], v[78:81], v[122:125]
	v_mfma_f32_16x16x32_bf16 v[210:213], v[210:213], v[78:81], v[126:129]
	v_mfma_f32_16x16x32_bf16 v[214:217], v[214:217], v[78:81], v[130:133]
	v_mfma_f32_16x16x32_bf16 v[218:221], v[218:221], v[78:81], v[134:137]
	s_setprio 0
	s_nop 0
	v_add_u32_e32 v81, 0x10000, v249
	v_add_u32_e32 v78, 0x11000, v249
	v_add_u32_e32 v85, 0x10000, v250
	ds_read_b128 v[234:237], v81
	ds_read_b128 v[226:229], v85
	v_add_u32_e32 v80, 0x11000, v250
	ds_read_b128 v[230:233], v78
	ds_read_b128 v[222:225], v80
	v_add_u32_e32 v242, 0x10000, v248
	v_add_u32_e32 v90, 0x10000, v247
	ds_read_b128 v[86:89], v242
	ds_read_b128 v[82:85], v90
	ds_read_b128 v[78:81], v90 offset:4096
	s_setprio 1
	s_waitcnt lgkmcnt(1)
	v_mfma_f32_16x16x32_bf16 v[158:161], v[234:237], v[82:85], v[158:161]
	v_mfma_f32_16x16x32_bf16 v[154:157], v[226:229], v[82:85], v[154:157]
	v_mfma_f32_16x16x32_bf16 v[150:153], v[230:233], v[82:85], v[150:153]
	v_mfma_f32_16x16x32_bf16 v[146:149], v[222:225], v[82:85], v[146:149]
	v_mfma_f32_16x16x32_bf16 v[134:137], v[230:233], v[86:89], v[38:41]
	ds_read_b128 v[82:85], v242 offset:4096
	s_nop 1
	ds_read_b128 v[38:41], v90 offset:8192
	v_mfma_f32_16x16x32_bf16 v[142:145], v[234:237], v[86:89], v[142:145]
	v_mfma_f32_16x16x32_bf16 v[138:141], v[226:229], v[86:89], v[138:141]
	v_mfma_f32_16x16x32_bf16 v[130:133], v[222:225], v[86:89], v[34:37]
	s_nop 2
	s_and_b64 vcc, exec, s[2:3]
	s_cbranch_vccnz .LBB0_978
	s_waitcnt vmcnt(7)
	ds_write_b128 v251, v[10:13] offset:32768
	s_waitcnt vmcnt(6)
	ds_write_b128 v251, v[14:17] offset:40960
.LBB0_978:
	s_lshl_b64 s[22:23], s[22:23], 1
	s_add_u32 s22, s34, s22
	s_addc_u32 s23, s35, s23
	s_waitcnt vmcnt(7)
	s_add_u32 s22, s22, s24
	s_addc_u32 s23, s23, s25
	global_load_dwordx4 v[14:17], v246, s[22:23]
	s_nop 0
	global_load_dwordx4 v[10:13], v244, s[22:23]
	s_waitcnt lgkmcnt(0)
	v_mfma_f32_16x16x32_bf16 v[98:101], v[234:237], v[38:41], v[42:45]
	ds_read_b128 v[34:37], v242 offset:12288
	s_nop 1
	ds_read_b128 v[42:45], v242 offset:8192
	v_mfma_f32_16x16x32_bf16 v[94:97], v[226:229], v[38:41], v[46:49]
	v_mfma_f32_16x16x32_bf16 v[90:93], v[230:233], v[38:41], v[50:53]
	v_mfma_f32_16x16x32_bf16 v[86:89], v[222:225], v[38:41], v[54:57]
	v_add_u32_e32 v38, 0x13000, v247
	ds_read_b128 v[38:41], v38
	v_mfma_f32_16x16x32_bf16 v[126:129], v[234:237], v[78:81], v[162:165]
	v_mfma_f32_16x16x32_bf16 v[122:125], v[226:229], v[78:81], v[166:169]
	v_mfma_f32_16x16x32_bf16 v[118:121], v[230:233], v[78:81], v[170:173]
	v_mfma_f32_16x16x32_bf16 v[114:117], v[222:225], v[78:81], v[174:177]
	v_mfma_f32_16x16x32_bf16 v[110:113], v[234:237], v[82:85], v[58:61]
	v_mfma_f32_16x16x32_bf16 v[106:109], v[226:229], v[82:85], v[62:65]
	v_mfma_f32_16x16x32_bf16 v[102:105], v[230:233], v[82:85], v[66:69]
	v_mfma_f32_16x16x32_bf16 v[82:85], v[222:225], v[82:85], v[70:73]
	s_waitcnt lgkmcnt(1)
	v_mfma_f32_16x16x32_bf16 v[78:81], v[234:237], v[42:45], v[178:181]
	v_mfma_f32_16x16x32_bf16 v[74:77], v[226:229], v[42:45], v[74:77]
	v_mfma_f32_16x16x32_bf16 v[70:73], v[230:233], v[42:45], v[182:185]
	v_mfma_f32_16x16x32_bf16 v[66:69], v[222:225], v[42:45], v[186:189]
	v_mov_b32_e32 v42, v0
	s_and_b64 vcc, exec, s[2:3]
	s_cbranch_vccnz .LBB0_980
	s_waitcnt vmcnt(7)
	ds_write_b128 v251, v[2:5] offset:49152
	s_waitcnt vmcnt(6)
	ds_write_b128 v251, v[6:9] offset:57344
.LBB0_980:
	s_waitcnt vmcnt(7)
	v_lshlrev_b32_e32 v3, 4, v42
	v_lshlrev_b32_e32 v2, 8, v42
	v_and_b32_e32 v3, 0x70, v3
	v_and_or_b32 v238, v2, s39, v3
	s_waitcnt lgkmcnt(0)
	v_mfma_f32_16x16x32_bf16 v[62:65], v[234:237], v[38:41], v[190:193]
	v_mfma_f32_16x16x32_bf16 v[58:61], v[226:229], v[38:41], v[194:197]
	s_nop 0
	global_load_dwordx4 v[6:9], v243, s[22:23]
	s_nop 0
	v_add_u32_e32 v2, 0x60000, v246
	global_load_dwordx4 v[2:5], v2, s[22:23]
	v_mfma_f32_16x16x32_bf16 v[54:57], v[230:233], v[38:41], v[198:201]
	v_mfma_f32_16x16x32_bf16 v[50:53], v[222:225], v[38:41], v[202:205]
	v_mfma_f32_16x16x32_bf16 v[46:49], v[234:237], v[34:37], v[206:209]
	v_mfma_f32_16x16x32_bf16 v[42:45], v[226:229], v[34:37], v[210:213]
	v_mfma_f32_16x16x32_bf16 v[38:41], v[230:233], v[34:37], v[214:217]
	v_mfma_f32_16x16x32_bf16 v[34:37], v[222:225], v[34:37], v[218:221]
	s_setprio 0
	s_add_i32 s28, s53, 1
	s_cmp_lg_u32 s28, 16
	s_cbranch_scc1 .LBB0_984
	s_add_i32 s30, s30, s11
	s_cmp_gt_i32 s30, 31
	s_cbranch_scc1 .LBB0_983
	s_ashr_i32 s3, s30, 31
	s_lshr_b32 s3, s3, 27
	s_add_i32 s3, s30, s3
	s_ashr_i32 s3, s3, 5
	s_mov_b32 s2, s10
	s_lshl_b32 s22, s3, 6
	s_lshl_b32 s23, s30, 1
	s_sub_i32 s22, s23, s22
	s_and_b32 s2, s2, 7
	s_and_b32 s22, s22, -8
	s_lshl_b32 s3, s3, 2
	s_and_b32 s23, s30, 3
	s_or_b32 s50, s3, s23
	s_or_b32 s51, s2, s22

.LBB0_1138:
	v_mov_b32_e32 v255, 0x8000
	v_bfe_u32 v1, v0, 0, 1
	v_lshlrev_b32_e32 v1, 7, v1
	v_xor_b32_e32 v255, v255, v1
	v_bfe_u32 v1, v0, 1, 3
	v_mul_u32_u24_e32 v1, 0x110, v1
	v_xor_b32_e32 v255, v255, v1
	v_bfe_u32 v1, v0, 4, 2
	v_lshlrev_b32_e32 v1, 4, v1
	v_xor_b32_e32 v255, v255, v1
	v_bfe_u32 v1, v0, 6, 2
	v_lshlrev_b32_e32 v1, 13, v1
	v_xor_b32_e32 v255, v255, v1
	v_mov_b32_e32 v254, 0x8880
	v_bfe_u32 v1, v0, 0, 1
	v_lshlrev_b32_e32 v1, 7, v1
	v_xor_b32_e32 v254, v254, v1
	v_bfe_u32 v1, v0, 1, 3
	v_mul_u32_u24_e32 v1, 0x110, v1
	v_xor_b32_e32 v254, v254, v1
	v_bfe_u32 v1, v0, 4, 2
	v_lshlrev_b32_e32 v1, 4, v1
	v_xor_b32_e32 v254, v254, v1
	v_bfe_u32 v1, v0, 6, 2
	v_lshlrev_b32_e32 v1, 13, v1
	v_xor_b32_e32 v254, v254, v1
	v_mov_b32_e32 v253, 0x880
	v_bfe_u32 v1, v0, 0, 1
	v_lshlrev_b32_e32 v1, 7, v1
	v_xor_b32_e32 v253, v253, v1
	v_bfe_u32 v1, v0, 1, 3
	v_mul_u32_u24_e32 v1, 0x110, v1
	v_xor_b32_e32 v253, v253, v1
	v_bfe_u32 v1, v0, 4, 2
	v_lshlrev_b32_e32 v1, 4, v1
	v_xor_b32_e32 v253, v253, v1
	v_bfe_u32 v1, v0, 8, 1
	v_lshlrev_b32_e32 v1, 14, v1
	v_xor_b32_e32 v253, v253, v1
	v_mov_b32_e32 v252, 0x0
	v_bfe_u32 v1, v0, 0, 1
	v_lshlrev_b32_e32 v1, 7, v1
	v_xor_b32_e32 v252, v252, v1
	v_bfe_u32 v1, v0, 1, 3
	v_mul_u32_u24_e32 v1, 0x110, v1
	v_xor_b32_e32 v252, v252, v1
	v_bfe_u32 v1, v0, 4, 2
	v_lshlrev_b32_e32 v1, 4, v1
	v_xor_b32_e32 v252, v252, v1
	v_bfe_u32 v1, v0, 8, 1
	v_lshlrev_b32_e32 v1, 14, v1
	v_xor_b32_e32 v252, v252, v1
	v_mov_b32_e32 v251, 0x0
	v_bfe_u32 v1, v0, 0, 4
	v_lshlrev_b32_e32 v1, 4, v1
	v_xor_b32_e32 v251, v251, v1
	v_bfe_u32 v1, v0, 4, 4
	v_mul_u32_u24_e32 v1, 0x110, v1
	v_xor_b32_e32 v251, v251, v1
	v_bfe_u32 v1, v0, 8, 1
	v_lshlrev_b32_e32 v1, 12, v1
	v_xor_b32_e32 v251, v251, v1
	v_mov_b32_e32 v250, 0x88c0
	v_bfe_u32 v1, v0, 0, 1
	v_lshlrev_b32_e32 v1, 7, v1
	v_xor_b32_e32 v250, v250, v1
	v_bfe_u32 v1, v0, 1, 3
	v_mul_u32_u24_e32 v1, 0x110, v1
	v_xor_b32_e32 v250, v250, v1
	v_bfe_u32 v1, v0, 4, 2
	v_lshlrev_b32_e32 v1, 4, v1
	v_xor_b32_e32 v250, v250, v1
	v_bfe_u32 v1, v0, 6, 2
	v_lshlrev_b32_e32 v1, 13, v1
	v_xor_b32_e32 v250, v250, v1
	v_mov_b32_e32 v249, 0x8040
	v_bfe_u32 v1, v0, 0, 1
	v_lshlrev_b32_e32 v1, 7, v1
	v_xor_b32_e32 v249, v249, v1
	v_bfe_u32 v1, v0, 1, 3
	v_mul_u32_u24_e32 v1, 0x110, v1
	v_xor_b32_e32 v249, v249, v1
	v_bfe_u32 v1, v0, 4, 2
	v_lshlrev_b32_e32 v1, 4, v1
	v_xor_b32_e32 v249, v249, v1
	v_bfe_u32 v1, v0, 6, 2
	v_lshlrev_b32_e32 v1, 13, v1
	v_xor_b32_e32 v249, v249, v1
	v_mov_b32_e32 v248, 0x8c0
	v_bfe_u32 v1, v0, 0, 1
	v_lshlrev_b32_e32 v1, 7, v1
	v_xor_b32_e32 v248, v248, v1
	v_bfe_u32 v1, v0, 1, 3
	v_mul_u32_u24_e32 v1, 0x110, v1
	v_xor_b32_e32 v248, v248, v1
	v_bfe_u32 v1, v0, 4, 2
	v_lshlrev_b32_e32 v1, 4, v1
	v_xor_b32_e32 v248, v248, v1
	v_bfe_u32 v1, v0, 8, 1
	v_lshlrev_b32_e32 v1, 14, v1
	v_xor_b32_e32 v248, v248, v1
	v_mov_b32_e32 v247, 0x40
	v_bfe_u32 v1, v0, 0, 1
	v_lshlrev_b32_e32 v1, 7, v1
	v_xor_b32_e32 v247, v247, v1
	v_bfe_u32 v1, v0, 1, 3
	v_mul_u32_u24_e32 v1, 0x110, v1
	v_xor_b32_e32 v247, v247, v1
	v_bfe_u32 v1, v0, 4, 2
	v_lshlrev_b32_e32 v1, 4, v1
	v_xor_b32_e32 v247, v247, v1
	v_bfe_u32 v1, v0, 8, 1
	v_lshlrev_b32_e32 v1, 14, v1
	v_xor_b32_e32 v247, v247, v1
	v_mov_b32_e32 v246, 0x0
	v_bfe_u32 v1, v0, 0, 3
	v_lshlrev_b32_e32 v1, 4, v1
	v_add_u32_e32 v246, v246, v1
	v_bfe_u32 v1, v0, 3, 6
	v_lshlrev_b32_e32 v1, 11, v1
	v_add_u32_e32 v246, v246, v1
	v_mov_b32_e32 v245, 0x10000
	v_bfe_u32 v1, v0, 0, 4
	v_lshlrev_b32_e32 v1, 4, v1
	v_xor_b32_e32 v245, v245, v1
	v_bfe_u32 v1, v0, 4, 4
	v_mul_u32_u24_e32 v1, 0x110, v1
	v_xor_b32_e32 v245, v245, v1
	v_bfe_u32 v1, v0, 8, 1
	v_lshlrev_b32_e32 v1, 12, v1
	v_xor_b32_e32 v245, v245, v1
	v_mov_b32_e32 v244, 0x20000
	v_bfe_u32 v1, v0, 0, 3
	v_lshlrev_b32_e32 v1, 4, v1
	v_add_u32_e32 v244, v244, v1
	v_bfe_u32 v1, v0, 3, 6
	v_lshlrev_b32_e32 v1, 11, v1
	v_add_u32_e32 v244, v244, v1
	v_mov_b32_e32 v243, 0x40000
	v_bfe_u32 v1, v0, 0, 3
	v_lshlrev_b32_e32 v1, 4, v1
	v_add_u32_e32 v243, v243, v1
	v_bfe_u32 v1, v0, 3, 6
	v_lshlrev_b32_e32 v1, 11, v1
	v_add_u32_e32 v243, v243, v1
	v_mov_b32_e32 v1, v0
	s_mov_b32 s2, s10
	s_load_dword s8, s[0:1], 0xe0
	s_load_dwordx2 s[2:3], s[16:17], 0xd0
	s_waitcnt vmcnt(0)
	v_mov_b32_e32 v2, v0
	s_mov_b32 s27, 0
	s_waitcnt lgkmcnt(0)
	s_add_u32 s11, s2, 0x17f0000
	s_addc_u32 s24, s3, 0
	s_add_u32 s6, s2, 0x37f0000
	s_addc_u32 s7, s3, 0
	s_add_u32 s25, s2, 0x770000
	s_addc_u32 s26, s3, 0
	s_lshr_b32 s28, s8, 3
	v_cvt_f32_u32_e32 v1, s28
	s_sub_i32 s8, 0, s28
	s_mov_b32 s2, s10
	v_rcp_iflag_f32_e32 v1, v1
	s_ashr_i32 s3, s2, 3
	s_abs_i32 s3, s3
	s_ashr_i32 s2, s2, 31
	v_mul_f32_e32 v1, 0x4f7ffffe, v1
	v_cvt_u32_f32_e32 v1, v1
	s_nop 0
	v_readfirstlane_b32 s30, v1
	s_mul_i32 s8, s8, s30
	s_mul_hi_u32 s8, s30, s8
	s_add_i32 s30, s30, s8
	s_mul_hi_u32 s8, s3, s30
	s_mul_i32 s8, s8, s28
	s_sub_i32 s3, s3, s8
	s_sub_i32 s8, s3, s28
	s_cmp_ge_u32 s3, s28
	s_cselect_b32 s3, s8, s3
	s_sub_i32 s8, s3, s28
	s_cmp_ge_u32 s3, s28
	s_cselect_b32 s3, s8, s3
	s_xor_b32 s3, s3, s2
	s_sub_i32 s31, s3, s2
	s_mul_hi_u32 s3, s30, 0xb0
	s_mul_i32 s3, s3, s28
	s_sub_i32 s3, 0xb0, s3
	s_sub_i32 s8, s3, s28
	s_cmp_ge_u32 s3, s28
	s_cselect_b32 s3, s8, s3
	s_sub_i32 s8, s3, s28
	s_cmp_ge_u32 s3, s28
	s_cselect_b32 s29, s8, s3
	s_sub_i32 s33, 0xb0, s29
	s_mov_b32 s2, s10
	s_cmp_ge_i32 s31, s33
	s_cbranch_scc1 .LBB0_1187
	s_mov_b32 s9, s10
	s_cmpk_gt_i32 s31, 0x9f
	s_cbranch_scc0 .LBB0_1141
	s_lshl_b32 s2, s31, 2
	s_add_i32 s2, s2, 0x7ffffd80
	s_and_b32 s8, s2, 0x7ffffff8
	s_and_b32 s2, s31, 1
	s_or_b32 s34, s2, 20
	s_cbranch_execz .LBB0_1142
	s_branch .LBB0_1143

.LBB0_1148:
	s_add_i32 s2, s41, -1
	ds_read_b128 v[182:185], v255
	ds_read_b128 v[174:177], v255 offset:4096
	ds_read_b128 v[178:181], v254
	ds_read_b128 v[170:173], v254 offset:4096
	ds_read_b128 v[190:193], v253
	ds_read_b128 v[162:165], v252
	ds_read_b128 v[186:189], v252 offset:4096
	s_setprio 1
	s_waitcnt lgkmcnt(1)
	v_mfma_f32_16x16x32_bf16 v[158:161], v[182:185], v[162:165], v[158:161]
	s_cmp_lt_i32 s2, s40
	s_cselect_b64 s[14:15], -1, 0
	s_cmp_ge_i32 s2, s40
	v_mfma_f32_16x16x32_bf16 v[150:153], v[178:181], v[162:165], v[150:153]
	v_mfma_f32_16x16x32_bf16 v[154:157], v[174:177], v[162:165], v[154:157]
	v_mfma_f32_16x16x32_bf16 v[162:165], v[170:173], v[162:165], v[146:149]
	v_mfma_f32_16x16x32_bf16 v[166:169], v[174:177], v[190:193], v[138:141]
	s_nop 1
	ds_read_b128 v[146:149], v253 offset:4096
	ds_read_b128 v[138:141], v252 offset:8192
	v_mfma_f32_16x16x32_bf16 v[142:145], v[182:185], v[190:193], v[142:145]
	v_mfma_f32_16x16x32_bf16 v[134:137], v[178:181], v[190:193], v[134:137]
	v_mfma_f32_16x16x32_bf16 v[130:133], v[170:173], v[190:193], v[130:133]
	s_cbranch_scc1 .LBB0_1150
	s_waitcnt vmcnt(0)
	ds_write_b128 v245, v[30:33]
	ds_write_b128 v245, v[26:29] offset:8192
.LBB0_1150:
	s_lshl_b32 s2, s48, 8
	s_ashr_i32 s3, s2, 31
	s_lshl_b64 s[12:13], s[2:3], 11
	s_lshl_b32 s2, s22, 6
	s_ashr_i32 s3, s2, 31
	s_add_u32 s20, s11, s12
	s_addc_u32 s21, s24, s13
	s_lshl_b64 s[8:9], s[2:3], 1
	s_waitcnt vmcnt(2)
	s_add_u32 s20, s20, s8
	s_addc_u32 s21, s21, s9
	s_waitcnt vmcnt(0)
	s_nop 0
	s_waitcnt lgkmcnt(0)
	v_mfma_f32_16x16x32_bf16 v[194:197], v[178:181], v[138:141], v[90:93]
	global_load_dwordx4 v[30:33], v244, s[20:21]
	s_nop 1
	ds_read_b128 v[90:93], v253 offset:8192
	v_mfma_f32_16x16x32_bf16 v[202:205], v[170:173], v[138:141], v[86:89]
	s_nop 2
	ds_read_b128 v[86:89], v253 offset:12288
	global_load_dwordx4 v[26:29], v246, s[20:21]
	s_waitcnt lgkmcnt(1)
	v_mfma_f32_16x16x32_bf16 v[206:209], v[178:181], v[90:93], v[74:77]
	s_nop 2
	ds_read_b128 v[74:77], v252 offset:12288
	v_mfma_f32_16x16x32_bf16 v[126:129], v[182:185], v[186:189], v[126:129]
	v_mfma_f32_16x16x32_bf16 v[118:121], v[178:181], v[186:189], v[118:121]
	v_mfma_f32_16x16x32_bf16 v[122:125], v[174:177], v[186:189], v[122:125]
	v_mfma_f32_16x16x32_bf16 v[114:117], v[170:173], v[186:189], v[114:117]
	v_mfma_f32_16x16x32_bf16 v[110:113], v[182:185], v[146:149], v[110:113]
	v_mfma_f32_16x16x32_bf16 v[102:105], v[178:181], v[146:149], v[102:105]
	v_mfma_f32_16x16x32_bf16 v[106:109], v[174:177], v[146:149], v[106:109]
	v_mfma_f32_16x16x32_bf16 v[66:69], v[170:173], v[146:149], v[66:69]
	v_mfma_f32_16x16x32_bf16 v[190:193], v[182:185], v[138:141], v[98:101]
	v_mfma_f32_16x16x32_bf16 v[198:201], v[174:177], v[138:141], v[94:97]
	v_mfma_f32_16x16x32_bf16 v[186:189], v[182:185], v[90:93], v[82:85]
	v_mfma_f32_16x16x32_bf16 v[210:213], v[174:177], v[90:93], v[78:81]
	v_mfma_f32_16x16x32_bf16 v[214:217], v[170:173], v[90:93], v[70:73]
	s_nop 2
	v_cndmask_b32_e64 v71, 0, 1, s[14:15]
	v_cmp_ne_u32_e64 s[2:3], 1, v71
	s_andn2_b64 vcc, exec, s[14:15]
	s_cbranch_vccnz .LBB0_1152
	ds_write_b128 v245, v[22:25] offset:16384
	ds_write_b128 v245, v[18:21] offset:24576
.LBB0_1152:
	s_waitcnt lgkmcnt(0)
	v_mfma_f32_16x16x32_bf16 v[62:65], v[182:185], v[74:77], v[62:65]
	v_mfma_f32_16x16x32_bf16 v[54:57], v[178:181], v[74:77], v[54:57]
	s_nop 0
	global_load_dwordx4 v[18:21], v243, s[20:21]
	s_nop 0
	v_add_u32_e32 v22, 0x60000, v246
	global_load_dwordx4 v[22:25], v22, s[20:21]
	v_mfma_f32_16x16x32_bf16 v[58:61], v[174:177], v[74:77], v[58:61]
	v_mfma_f32_16x16x32_bf16 v[50:53], v[170:173], v[74:77], v[50:53]
	v_mfma_f32_16x16x32_bf16 v[182:185], v[182:185], v[86:89], v[46:49]
	v_mfma_f32_16x16x32_bf16 v[178:181], v[178:181], v[86:89], v[38:41]
	v_mfma_f32_16x16x32_bf16 v[174:177], v[174:177], v[86:89], v[42:45]
	v_mfma_f32_16x16x32_bf16 v[170:173], v[170:173], v[86:89], v[34:37]
	s_setprio 0
	s_nop 1
	s_nop 0
	ds_read_b128 v[226:229], v250
	ds_read_b128 v[222:225], v249 offset:4096
	ds_read_b128 v[218:221], v250 offset:4096
	ds_read_b128 v[230:233], v249
	ds_read_b128 v[34:37], v248
	ds_read_b128 v[38:41], v247
	ds_read_b128 v[42:45], v247 offset:4096
	s_setprio 1
	s_waitcnt lgkmcnt(1)
	v_mfma_f32_16x16x32_bf16 v[146:149], v[230:233], v[38:41], v[158:161]
	v_mfma_f32_16x16x32_bf16 v[150:153], v[226:229], v[38:41], v[150:153]
	v_mfma_f32_16x16x32_bf16 v[154:157], v[222:225], v[38:41], v[154:157]
	v_mfma_f32_16x16x32_bf16 v[158:161], v[218:221], v[38:41], v[162:165]
	ds_read_b128 v[46:49], v248 offset:4096
	ds_read_b128 v[38:41], v247 offset:8192
	v_mfma_f32_16x16x32_bf16 v[138:141], v[230:233], v[34:37], v[142:145]
	v_mfma_f32_16x16x32_bf16 v[142:145], v[226:229], v[34:37], v[134:137]
	v_mfma_f32_16x16x32_bf16 v[70:73], v[222:225], v[34:37], v[166:169]
	v_mfma_f32_16x16x32_bf16 v[34:37], v[218:221], v[34:37], v[130:133]
	s_nop 2
	s_and_b64 vcc, exec, s[2:3]
	s_cbranch_vccnz .LBB0_1154
	ds_write_b128 v245, v[14:17] offset:32768
	ds_write_b128 v245, v[10:13] offset:40960
.LBB0_1154:
	s_lshl_b32 s14, s47, 8
	s_ashr_i32 s15, s14, 31
	s_lshl_b64 s[14:15], s[14:15], 11
	s_add_u32 s20, s25, s14
	s_addc_u32 s21, s26, s15
	s_add_u32 s8, s20, s8
	s_addc_u32 s9, s21, s9
	s_waitcnt lgkmcnt(2)
	v_mfma_f32_16x16x32_bf16 v[74:77], v[230:233], v[42:45], v[126:129]
	ds_read_b128 v[162:165], v247 offset:12288
	v_mfma_f32_16x16x32_bf16 v[78:81], v[226:229], v[42:45], v[118:121]
	v_mfma_f32_16x16x32_bf16 v[82:85], v[222:225], v[42:45], v[122:125]
	v_mfma_f32_16x16x32_bf16 v[86:89], v[218:221], v[42:45], v[114:117]
	ds_read_b128 v[42:45], v248 offset:8192
	global_load_dwordx4 v[10:13], v246, s[8:9]
	s_nop 0
	global_load_dwordx4 v[14:17], v244, s[8:9]
	s_waitcnt lgkmcnt(3)
	v_mfma_f32_16x16x32_bf16 v[94:97], v[226:229], v[46:49], v[102:105]
	v_mfma_f32_16x16x32_bf16 v[102:105], v[218:221], v[46:49], v[66:69]
	s_nop 2
	ds_read_b128 v[66:69], v248 offset:12288
	v_mfma_f32_16x16x32_bf16 v[90:93], v[230:233], v[46:49], v[110:113]
	v_mfma_f32_16x16x32_bf16 v[98:101], v[222:225], v[46:49], v[106:109]
	s_waitcnt lgkmcnt(3)
	v_mfma_f32_16x16x32_bf16 v[106:109], v[230:233], v[38:41], v[190:193]
	v_mfma_f32_16x16x32_bf16 v[110:113], v[226:229], v[38:41], v[194:197]
	v_mfma_f32_16x16x32_bf16 v[114:117], v[222:225], v[38:41], v[198:201]
	v_mfma_f32_16x16x32_bf16 v[118:121], v[218:221], v[38:41], v[202:205]
	s_waitcnt lgkmcnt(1)
	v_mfma_f32_16x16x32_bf16 v[122:125], v[230:233], v[42:45], v[186:189]
	v_mfma_f32_16x16x32_bf16 v[126:129], v[226:229], v[42:45], v[206:209]
	v_mfma_f32_16x16x32_bf16 v[130:133], v[222:225], v[42:45], v[210:213]
	v_mfma_f32_16x16x32_bf16 v[134:137], v[218:221], v[42:45], v[214:217]
	s_and_b64 vcc, exec, s[2:3]
	s_cbranch_vccnz .LBB0_1156
	ds_write_b128 v245, v[6:9] offset:49152
	ds_write_b128 v245, v[2:5] offset:57344
.LBB0_1156:
	v_mfma_f32_16x16x32_bf16 v[38:41], v[230:233], v[162:165], v[62:65]
	s_nop 0
	v_mfma_f32_16x16x32_bf16 v[42:45], v[226:229], v[162:165], v[54:57]
	s_nop 0
	global_load_dwordx4 v[2:5], v243, s[8:9]
	s_nop 0
	v_add_u32_e32 v6, 0x60000, v246
	global_load_dwordx4 v[6:9], v6, s[8:9]
	v_mfma_f32_16x16x32_bf16 v[46:49], v[222:225], v[162:165], v[58:61]
	v_mfma_f32_16x16x32_bf16 v[50:53], v[218:221], v[162:165], v[50:53]
	s_waitcnt lgkmcnt(0)
	v_mfma_f32_16x16x32_bf16 v[54:57], v[230:233], v[66:69], v[182:185]
	v_mfma_f32_16x16x32_bf16 v[58:61], v[226:229], v[66:69], v[178:181]
	v_mfma_f32_16x16x32_bf16 v[62:65], v[222:225], v[66:69], v[174:177]
	v_mfma_f32_16x16x32_bf16 v[66:69], v[218:221], v[66:69], v[170:173]
	s_setprio 0
	s_add_i32 s50, s22, 1
	s_cmp_lg_u32 s50, 16
	s_cbranch_scc1 .LBB0_1164
	s_add_i32 s31, s31, s28
	s_cmp_ge_i32 s31, s33
	s_cbranch_scc1 .LBB0_1163
	s_mov_b32 s8, s10
	s_cmpk_gt_i32 s31, 0x9f
	s_mov_b64 s[2:3], -1
	s_cbranch_scc0 .LBB0_1160
	s_lshl_b32 s2, s31, 2
	s_add_i32 s2, s2, 0x7ffffd80
	s_and_b32 s9, s2, 0x7ffffff8
	s_and_b32 s2, s31, 1
	s_or_b32 s47, s2, 20
	s_mov_b64 s[2:3], 0

.LBB0_1164:
	s_barrier
	s_nop 0
	v_add_u32_e32 v170, 0x10000, v255
	v_add_u32_e32 v162, 0x11000, v255
	v_add_u32_e32 v171, 0x10000, v254
	ds_read_b128 v[206:209], v170
	ds_read_b128 v[210:213], v171
	v_add_u32_e32 v169, 0x11000, v254
	ds_read_b128 v[214:217], v162
	ds_read_b128 v[218:221], v169
	v_add_u32_e32 v202, 0x10000, v253
	v_add_u32_e32 v190, 0x10000, v252
	ds_read_b128 v[174:177], v202
	ds_read_b128 v[162:165], v190
	ds_read_b128 v[170:173], v190 offset:4096
	s_setprio 1
	s_waitcnt lgkmcnt(1)
	v_mfma_f32_16x16x32_bf16 v[146:149], v[206:209], v[162:165], v[146:149]
	s_cmp_lt_i32 s41, s40
	s_cselect_b64 s[20:21], -1, 0
	s_cmp_ge_i32 s41, s40
	v_mfma_f32_16x16x32_bf16 v[150:153], v[210:213], v[162:165], v[150:153]
	s_cselect_b64 s[8:9], -1, 0
	v_mfma_f32_16x16x32_bf16 v[154:157], v[214:217], v[162:165], v[154:157]
	v_mfma_f32_16x16x32_bf16 v[162:165], v[218:221], v[162:165], v[158:161]
	v_mfma_f32_16x16x32_bf16 v[166:169], v[210:213], v[174:177], v[142:145]
	s_nop 1
	ds_read_b128 v[158:161], v202 offset:4096
	ds_read_b128 v[142:145], v190 offset:8192
	v_mfma_f32_16x16x32_bf16 v[138:141], v[206:209], v[174:177], v[138:141]
	v_mfma_f32_16x16x32_bf16 v[70:73], v[214:217], v[174:177], v[70:73]
	v_mfma_f32_16x16x32_bf16 v[34:37], v[218:221], v[174:177], v[34:37]
	s_and_b64 vcc, exec, s[8:9]
	s_cbranch_vccnz .LBB0_1166
	s_waitcnt vmcnt(6)
	ds_write_b128 v251, v[26:29]
	ds_write_b128 v251, v[30:33] offset:8192
.LBB0_1166:
	s_lshl_b32 s2, s50, 6
	s_ashr_i32 s3, s2, 31
	s_add_u32 s22, s11, s12
	s_addc_u32 s23, s24, s13
	s_lshl_b64 s[12:13], s[2:3], 1
	s_waitcnt vmcnt(6)
	s_add_u32 s22, s22, s12
	s_addc_u32 s23, s23, s13
	s_waitcnt lgkmcnt(0)
	v_mfma_f32_16x16x32_bf16 v[174:177], v[206:209], v[142:145], v[106:109]
	v_mfma_f32_16x16x32_bf16 v[178:181], v[210:213], v[142:145], v[110:113]
	s_nop 0
	ds_read_b128 v[106:109], v190 offset:12288
	s_nop 0
	ds_read_b128 v[110:113], v202 offset:8192
	global_load_dwordx4 v[30:33], v246, s[22:23]
	s_nop 0
	global_load_dwordx4 v[26:29], v244, s[22:23]
	v_mfma_f32_16x16x32_bf16 v[74:77], v[206:209], v[170:173], v[74:77]
	v_mfma_f32_16x16x32_bf16 v[78:81], v[210:213], v[170:173], v[78:81]
	v_mfma_f32_16x16x32_bf16 v[82:85], v[214:217], v[170:173], v[82:85]
	v_mfma_f32_16x16x32_bf16 v[86:89], v[218:221], v[170:173], v[86:89]
	v_mfma_f32_16x16x32_bf16 v[170:173], v[218:221], v[158:161], v[102:105]
	s_nop 2
	ds_read_b128 v[102:105], v202 offset:12288
	v_mfma_f32_16x16x32_bf16 v[90:93], v[206:209], v[158:161], v[90:93]
	v_mfma_f32_16x16x32_bf16 v[94:97], v[210:213], v[158:161], v[94:97]
	v_mfma_f32_16x16x32_bf16 v[98:101], v[214:217], v[158:161], v[98:101]
	v_mfma_f32_16x16x32_bf16 v[182:185], v[214:217], v[142:145], v[114:117]
	v_mfma_f32_16x16x32_bf16 v[186:189], v[218:221], v[142:145], v[118:121]
	s_waitcnt lgkmcnt(1)
	v_mfma_f32_16x16x32_bf16 v[190:193], v[206:209], v[110:113], v[122:125]
	v_mfma_f32_16x16x32_bf16 v[194:197], v[210:213], v[110:113], v[126:129]
	v_mfma_f32_16x16x32_bf16 v[198:201], v[214:217], v[110:113], v[130:133]
	v_mfma_f32_16x16x32_bf16 v[202:205], v[218:221], v[110:113], v[134:137]
	v_cndmask_b32_e64 v111, 0, 1, s[20:21]
	v_cmp_ne_u32_e64 s[2:3], 1, v111
	s_andn2_b64 vcc, exec, s[20:21]
	s_cbranch_vccnz .LBB0_1168
	s_waitcnt vmcnt(7)
	ds_write_b128 v251, v[18:21] offset:16384
	s_waitcnt vmcnt(6)
	ds_write_b128 v251, v[22:25] offset:24576
.LBB0_1168:
	s_waitcnt vmcnt(7)
	v_mfma_f32_16x16x32_bf16 v[38:41], v[206:209], v[106:109], v[38:41]
	s_nop 0
	v_mfma_f32_16x16x32_bf16 v[42:45], v[210:213], v[106:109], v[42:45]
	s_nop 0
	global_load_dwordx4 v[22:25], v243, s[22:23]
	s_nop 0
	v_add_u32_e32 v18, 0x60000, v246
	global_load_dwordx4 v[18:21], v18, s[22:23]
	v_mfma_f32_16x16x32_bf16 v[46:49], v[214:217], v[106:109], v[46:49]
	v_mfma_f32_16x16x32_bf16 v[50:53], v[218:221], v[106:109], v[50:53]
	s_waitcnt lgkmcnt(0)
	v_mfma_f32_16x16x32_bf16 v[206:209], v[206:209], v[102:105], v[54:57]
	v_mfma_f32_16x16x32_bf16 v[210:213], v[210:213], v[102:105], v[58:61]
	v_mfma_f32_16x16x32_bf16 v[214:217], v[214:217], v[102:105], v[62:65]
	v_mfma_f32_16x16x32_bf16 v[218:221], v[218:221], v[102:105], v[66:69]
	s_setprio 0
	s_nop 0
	v_add_u32_e32 v57, 0x10000, v249
	v_add_u32_e32 v54, 0x11000, v249
	v_add_u32_e32 v61, 0x10000, v250
	ds_read_b128 v[234:237], v57
	ds_read_b128 v[226:229], v61
	v_add_u32_e32 v56, 0x11000, v250
	ds_read_b128 v[230:233], v54
	ds_read_b128 v[222:225], v56
	v_add_u32_e32 v242, 0x10000, v248
	v_add_u32_e32 v102, 0x10000, v247
	ds_read_b128 v[66:69], v242
	ds_read_b128 v[54:57], v102
	ds_read_b128 v[58:61], v102 offset:4096
	s_setprio 1
	s_waitcnt lgkmcnt(1)
	v_mfma_f32_16x16x32_bf16 v[158:161], v[234:237], v[54:57], v[146:149]
	v_mfma_f32_16x16x32_bf16 v[150:153], v[226:229], v[54:57], v[150:153]
	v_mfma_f32_16x16x32_bf16 v[154:157], v[230:233], v[54:57], v[154:157]
	v_mfma_f32_16x16x32_bf16 v[146:149], v[222:225], v[54:57], v[162:165]
	ds_read_b128 v[62:65], v242 offset:4096
	ds_read_b128 v[54:57], v102 offset:8192
	v_mfma_f32_16x16x32_bf16 v[142:145], v[234:237], v[66:69], v[138:141]
	v_mfma_f32_16x16x32_bf16 v[134:137], v[226:229], v[66:69], v[166:169]
	v_mfma_f32_16x16x32_bf16 v[138:141], v[230:233], v[66:69], v[70:73]
	v_mfma_f32_16x16x32_bf16 v[130:133], v[222:225], v[66:69], v[34:37]
	s_nop 2
	s_and_b64 vcc, exec, s[2:3]
	s_cbranch_vccnz .LBB0_1170
	s_waitcnt vmcnt(7)
	ds_write_b128 v251, v[10:13] offset:32768
	s_waitcnt vmcnt(6)
	ds_write_b128 v251, v[14:17] offset:40960
.LBB0_1170:
	s_add_u32 s14, s25, s14
	s_addc_u32 s15, s26, s15
	s_waitcnt vmcnt(7)
	s_add_u32 s12, s14, s12
	s_addc_u32 s13, s15, s13
	global_load_dwordx4 v[14:17], v246, s[12:13]
	s_nop 0
	global_load_dwordx4 v[10:13], v244, s[12:13]
	s_waitcnt lgkmcnt(2)
	v_mfma_f32_16x16x32_bf16 v[126:129], v[234:237], v[58:61], v[74:77]
	ds_read_b128 v[34:37], v242 offset:12288
	v_mfma_f32_16x16x32_bf16 v[118:121], v[226:229], v[58:61], v[78:81]
	v_mfma_f32_16x16x32_bf16 v[122:125], v[230:233], v[58:61], v[82:85]
	v_mfma_f32_16x16x32_bf16 v[114:117], v[222:225], v[58:61], v[86:89]
	ds_read_b128 v[58:61], v242 offset:8192
	s_waitcnt lgkmcnt(3)
	v_mfma_f32_16x16x32_bf16 v[110:113], v[234:237], v[62:65], v[90:93]
	v_mfma_f32_16x16x32_bf16 v[102:105], v[226:229], v[62:65], v[94:97]
	v_mfma_f32_16x16x32_bf16 v[106:109], v[230:233], v[62:65], v[98:101]
	s_waitcnt lgkmcnt(2)
	v_mfma_f32_16x16x32_bf16 v[98:101], v[234:237], v[54:57], v[174:177]
	v_mfma_f32_16x16x32_bf16 v[90:93], v[226:229], v[54:57], v[178:181]
	v_mfma_f32_16x16x32_bf16 v[94:97], v[230:233], v[54:57], v[182:185]
	v_mfma_f32_16x16x32_bf16 v[86:89], v[222:225], v[54:57], v[186:189]
	v_add_u32_e32 v54, 0x13000, v247
	ds_read_b128 v[162:165], v54
	v_mfma_f32_16x16x32_bf16 v[66:69], v[222:225], v[62:65], v[170:173]
	s_waitcnt lgkmcnt(1)
	v_mfma_f32_16x16x32_bf16 v[82:85], v[234:237], v[58:61], v[190:193]
	v_mfma_f32_16x16x32_bf16 v[74:77], v[226:229], v[58:61], v[194:197]
	v_mfma_f32_16x16x32_bf16 v[78:81], v[230:233], v[58:61], v[198:201]
	v_mfma_f32_16x16x32_bf16 v[70:73], v[222:225], v[58:61], v[202:205]
	s_and_b64 vcc, exec, s[2:3]
	s_cbranch_vccnz .LBB0_1172
	s_waitcnt vmcnt(7)
	ds_write_b128 v251, v[2:5] offset:49152
	s_waitcnt vmcnt(6)
	ds_write_b128 v251, v[6:9] offset:57344
.LBB0_1172:
	s_waitcnt vmcnt(7)
	s_waitcnt lgkmcnt(0)
	v_mfma_f32_16x16x32_bf16 v[62:65], v[234:237], v[162:165], v[38:41]
	v_mfma_f32_16x16x32_bf16 v[54:57], v[226:229], v[162:165], v[42:45]
	s_nop 0
	global_load_dwordx4 v[6:9], v243, s[12:13]
	s_nop 0
	v_add_u32_e32 v2, 0x60000, v246
	global_load_dwordx4 v[2:5], v2, s[12:13]
	v_mfma_f32_16x16x32_bf16 v[58:61], v[230:233], v[162:165], v[46:49]
	v_mfma_f32_16x16x32_bf16 v[50:53], v[222:225], v[162:165], v[50:53]
	v_mfma_f32_16x16x32_bf16 v[46:49], v[234:237], v[34:37], v[206:209]
	v_mfma_f32_16x16x32_bf16 v[38:41], v[226:229], v[34:37], v[210:213]
	v_mfma_f32_16x16x32_bf16 v[42:45], v[230:233], v[34:37], v[214:217]
	v_mfma_f32_16x16x32_bf16 v[34:37], v[222:225], v[34:37], v[218:221]
	s_setprio 0
	s_add_i32 s22, s50, 1
	s_cmp_lg_u32 s22, 16
	s_cbranch_scc1 .LBB0_1180
	s_add_i32 s31, s31, s28
	s_cmp_ge_i32 s31, s33
	s_cbranch_scc1 .LBB0_1179
	s_mov_b32 s12, s10
	s_cmpk_gt_i32 s31, 0x9f
	s_mov_b64 s[2:3], -1
	s_cbranch_scc0 .LBB0_1176
	s_lshl_b32 s2, s31, 2
	s_add_i32 s2, s2, 0x7ffffd80
	s_and_b32 s13, s2, 0x7ffffff8
	s_and_b32 s2, s31, 1
	s_or_b32 s47, s2, 20
	s_mov_b64 s[2:3], 0

.LBB0_1187:
	v_mov_b32_e32 v255, 0x8000
	v_bfe_u32 v1, v0, 0, 1
	v_lshlrev_b32_e32 v1, 7, v1
	v_xor_b32_e32 v255, v255, v1
	v_bfe_u32 v1, v0, 1, 3
	v_mul_u32_u24_e32 v1, 0x110, v1
	v_xor_b32_e32 v255, v255, v1
	v_bfe_u32 v1, v0, 4, 2
	v_lshlrev_b32_e32 v1, 4, v1
	v_xor_b32_e32 v255, v255, v1
	v_bfe_u32 v1, v0, 6, 2
	v_lshlrev_b32_e32 v1, 13, v1
	v_xor_b32_e32 v255, v255, v1
	v_mov_b32_e32 v254, 0x8880
	v_bfe_u32 v1, v0, 0, 1
	v_lshlrev_b32_e32 v1, 7, v1
	v_xor_b32_e32 v254, v254, v1
	v_bfe_u32 v1, v0, 1, 3
	v_mul_u32_u24_e32 v1, 0x110, v1
	v_xor_b32_e32 v254, v254, v1
	v_bfe_u32 v1, v0, 4, 2
	v_lshlrev_b32_e32 v1, 4, v1
	v_xor_b32_e32 v254, v254, v1
	v_bfe_u32 v1, v0, 6, 2
	v_lshlrev_b32_e32 v1, 13, v1
	v_xor_b32_e32 v254, v254, v1
	v_mov_b32_e32 v253, 0x880
	v_bfe_u32 v1, v0, 0, 1
	v_lshlrev_b32_e32 v1, 7, v1
	v_xor_b32_e32 v253, v253, v1
	v_bfe_u32 v1, v0, 1, 3
	v_mul_u32_u24_e32 v1, 0x110, v1
	v_xor_b32_e32 v253, v253, v1
	v_bfe_u32 v1, v0, 4, 2
	v_lshlrev_b32_e32 v1, 4, v1
	v_xor_b32_e32 v253, v253, v1
	v_bfe_u32 v1, v0, 8, 1
	v_lshlrev_b32_e32 v1, 13, v1
	v_xor_b32_e32 v253, v253, v1
	v_mov_b32_e32 v252, 0x0
	v_bfe_u32 v1, v0, 0, 1
	v_lshlrev_b32_e32 v1, 7, v1
	v_xor_b32_e32 v252, v252, v1
	v_bfe_u32 v1, v0, 1, 3
	v_mul_u32_u24_e32 v1, 0x110, v1
	v_xor_b32_e32 v252, v252, v1
	v_bfe_u32 v1, v0, 4, 2
	v_lshlrev_b32_e32 v1, 4, v1
	v_xor_b32_e32 v252, v252, v1
	v_bfe_u32 v1, v0, 8, 1
	v_lshlrev_b32_e32 v1, 13, v1
	v_xor_b32_e32 v252, v252, v1
	v_mov_b32_e32 v251, 0x0
	v_bfe_u32 v1, v0, 0, 4
	v_lshlrev_b32_e32 v1, 4, v1
	v_xor_b32_e32 v251, v251, v1
	v_bfe_u32 v1, v0, 4, 4
	v_mul_u32_u24_e32 v1, 0x110, v1
	v_xor_b32_e32 v251, v251, v1
	v_bfe_u32 v1, v0, 8, 1
	v_lshlrev_b32_e32 v1, 12, v1
	v_xor_b32_e32 v251, v251, v1
	v_mov_b32_e32 v250, 0x8040
	v_bfe_u32 v1, v0, 0, 1
	v_lshlrev_b32_e32 v1, 7, v1
	v_xor_b32_e32 v250, v250, v1
	v_bfe_u32 v1, v0, 1, 3
	v_mul_u32_u24_e32 v1, 0x110, v1
	v_xor_b32_e32 v250, v250, v1
	v_bfe_u32 v1, v0, 4, 2
	v_lshlrev_b32_e32 v1, 4, v1
	v_xor_b32_e32 v250, v250, v1
	v_bfe_u32 v1, v0, 6, 2
	v_lshlrev_b32_e32 v1, 13, v1
	v_xor_b32_e32 v250, v250, v1
	v_mov_b32_e32 v249, 0x88c0
	v_bfe_u32 v1, v0, 0, 1
	v_lshlrev_b32_e32 v1, 7, v1
	v_xor_b32_e32 v249, v249, v1
	v_bfe_u32 v1, v0, 1, 3
	v_mul_u32_u24_e32 v1, 0x110, v1
	v_xor_b32_e32 v249, v249, v1
	v_bfe_u32 v1, v0, 4, 2
	v_lshlrev_b32_e32 v1, 4, v1
	v_xor_b32_e32 v249, v249, v1
	v_bfe_u32 v1, v0, 6, 2
	v_lshlrev_b32_e32 v1, 13, v1
	v_xor_b32_e32 v249, v249, v1
	v_mov_b32_e32 v248, 0x8c0
	v_bfe_u32 v1, v0, 0, 1
	v_lshlrev_b32_e32 v1, 7, v1
	v_xor_b32_e32 v248, v248, v1
	v_bfe_u32 v1, v0, 1, 3
	v_mul_u32_u24_e32 v1, 0x110, v1
	v_xor_b32_e32 v248, v248, v1
	v_bfe_u32 v1, v0, 4, 2
	v_lshlrev_b32_e32 v1, 4, v1
	v_xor_b32_e32 v248, v248, v1
	v_bfe_u32 v1, v0, 8, 1
	v_lshlrev_b32_e32 v1, 13, v1
	v_xor_b32_e32 v248, v248, v1
	v_mov_b32_e32 v247, 0x40
	v_bfe_u32 v1, v0, 0, 1
	v_lshlrev_b32_e32 v1, 7, v1
	v_xor_b32_e32 v247, v247, v1
	v_bfe_u32 v1, v0, 1, 3
	v_mul_u32_u24_e32 v1, 0x110, v1
	v_xor_b32_e32 v247, v247, v1
	v_bfe_u32 v1, v0, 4, 2
	v_lshlrev_b32_e32 v1, 4, v1
	v_xor_b32_e32 v247, v247, v1
	v_bfe_u32 v1, v0, 8, 1
	v_lshlrev_b32_e32 v1, 13, v1
	v_xor_b32_e32 v247, v247, v1
	v_mov_b32_e32 v246, 0x0
	v_bfe_u32 v1, v0, 0, 3
	v_lshlrev_b32_e32 v1, 4, v1
	v_add_u32_e32 v246, v246, v1
	v_bfe_u32 v1, v0, 3, 6
	v_lshlrev_b32_e32 v1, 11, v1
	v_add_u32_e32 v246, v246, v1
	v_mov_b32_e32 v245, 0x20000
	v_bfe_u32 v1, v0, 0, 3
	v_lshlrev_b32_e32 v1, 4, v1
	v_add_u32_e32 v245, v245, v1
	v_bfe_u32 v1, v0, 3, 6
	v_lshlrev_b32_e32 v1, 11, v1
	v_add_u32_e32 v245, v245, v1
	v_mov_b32_e32 v244, 0x10000
	v_bfe_u32 v1, v0, 0, 4
	v_lshlrev_b32_e32 v1, 4, v1
	v_xor_b32_e32 v244, v244, v1
	v_bfe_u32 v1, v0, 4, 4
	v_mul_u32_u24_e32 v1, 0x110, v1
	v_xor_b32_e32 v244, v244, v1
	v_bfe_u32 v1, v0, 8, 1
	v_lshlrev_b32_e32 v1, 12, v1
	v_xor_b32_e32 v244, v244, v1
	v_mov_b32_e32 v243, 0x18000
	v_bfe_u32 v1, v0, 0, 1
	v_lshlrev_b32_e32 v1, 7, v1
	v_xor_b32_e32 v243, v243, v1
	v_bfe_u32 v1, v0, 1, 3
	v_mul_u32_u24_e32 v1, 0x110, v1
	v_xor_b32_e32 v243, v243, v1
	v_bfe_u32 v1, v0, 4, 2
	v_lshlrev_b32_e32 v1, 4, v1
	v_xor_b32_e32 v243, v243, v1
	v_bfe_u32 v1, v0, 6, 2
	v_lshlrev_b32_e32 v1, 13, v1
	v_xor_b32_e32 v243, v243, v1
	v_mov_b32_e32 v1, v0
	s_mov_b32 s2, s10
	s_ashr_i32 s3, s2, 3
	s_abs_i32 s3, s3
	s_mul_hi_u32 s8, s3, s30
	s_mul_i32 s8, s8, s28
	s_sub_i32 s3, s3, s8
	s_ashr_i32 s2, s2, 31
	s_sub_i32 s8, s3, s28
	s_cmp_ge_u32 s3, s28
	s_cselect_b32 s3, s8, s3
	s_sub_i32 s8, s3, s28
	s_cmp_ge_u32 s3, s28
	s_cselect_b32 s3, s8, s3
	s_xor_b32 s3, s3, s2
	s_sub_i32 s22, s3, s2
	s_mov_b32 s2, s10
	s_lshl_b32 s8, s29, 1
	s_cmp_lt_i32 s22, s8
	s_cselect_b64 s[2:3], -1, 0
	s_cmp_ge_i32 s22, s8
	s_mov_b32 s23, 1
	s_cbranch_scc1 .LBB0_1189
	s_lshl_b32 s8, s22, 7
	s_and_b32 s27, s8, 0x80
	s_ashr_i32 s8, s22, 1
	s_sub_i32 s8, s8, s29
	s_add_i32 s29, s8, 0xb1
	s_add_i32 s22, s8, 0xb0
	s_branch .LBB0_1190

.LBB0_1203:
	s_add_i32 s2, s36, -1
	ds_read_b128 v[94:97], v255
	ds_read_b128 v[118:121], v255 offset:4096
	ds_read_b128 v[102:105], v254
	ds_read_b128 v[122:125], v254 offset:4096
	ds_read_b128 v[110:113], v253
	ds_read_b128 v[98:101], v252
	ds_read_b128 v[114:117], v252 offset:4096
	s_setprio 1
	s_waitcnt lgkmcnt(1)
	v_mfma_f32_16x16x32_bf16 v[58:61], v[94:97], v[98:101], v[58:61]
	s_cmp_lt_i32 s2, s35
	s_cselect_b64 s[8:9], -1, 0
	s_cmp_ge_i32 s2, s35
	v_mfma_f32_16x16x32_bf16 v[82:85], v[102:105], v[98:101], v[82:85]
	v_mfma_f32_16x16x32_bf16 v[90:93], v[118:121], v[98:101], v[86:89]
	v_mfma_f32_16x16x32_bf16 v[78:81], v[122:125], v[98:101], v[78:81]
	v_mfma_f32_16x16x32_bf16 v[98:101], v[102:105], v[110:113], v[66:69]
	s_nop 2
	ds_read_b128 v[66:69], v253 offset:4096
	v_mfma_f32_16x16x32_bf16 v[74:77], v[94:97], v[110:113], v[74:77]
	v_mfma_f32_16x16x32_bf16 v[106:109], v[118:121], v[110:113], v[70:73]
	v_mfma_f32_16x16x32_bf16 v[110:113], v[122:125], v[110:113], v[62:65]
	s_nop 2
	s_cbranch_scc1 .LBB0_1205
	s_waitcnt vmcnt(0)
	ds_write_b128 v244, v[22:25]
	ds_write_b128 v244, v[18:21] offset:8192
.LBB0_1205:
	s_lshl_b32 s2, s43, 8
	s_or_b32 s2, s2, s27
	s_ashr_i32 s3, s2, 31
	s_lshl_b64 s[12:13], s[2:3], 11
	s_lshl_b32 s2, s45, 6
	s_ashr_i32 s3, s2, 31
	s_add_u32 s14, s11, s12
	s_addc_u32 s15, s24, s13
	s_lshl_b64 s[20:21], s[2:3], 1
	s_waitcnt vmcnt(2)
	s_add_u32 s2, s14, s20
	s_addc_u32 s3, s15, s21
	s_waitcnt lgkmcnt(1)
	v_mfma_f32_16x16x32_bf16 v[126:129], v[94:97], v[114:117], v[54:57]
	s_nop 2
	v_mfma_f32_16x16x32_bf16 v[46:49], v[102:105], v[114:117], v[46:49]
	s_nop 0
	global_load_dwordx4 v[18:21], v246, s[2:3]
	global_load_dwordx4 v[22:25], v245, s[2:3]
	v_mfma_f32_16x16x32_bf16 v[130:133], v[118:121], v[114:117], v[50:53]
	v_mfma_f32_16x16x32_bf16 v[138:141], v[122:125], v[114:117], v[42:45]
	s_waitcnt lgkmcnt(0)
	v_mfma_f32_16x16x32_bf16 v[114:117], v[94:97], v[66:69], v[34:37]
	v_mfma_f32_16x16x32_bf16 v[102:105], v[102:105], v[66:69], v[30:33]
	v_mfma_f32_16x16x32_bf16 v[94:97], v[118:121], v[66:69], v[38:41]
	v_mfma_f32_16x16x32_bf16 v[86:89], v[122:125], v[66:69], v[26:29]
	s_setprio 0
	s_nop 1
	s_nop 0
	ds_read_b128 v[142:145], v250
	ds_read_b128 v[122:125], v250 offset:4096
	ds_read_b128 v[134:137], v249
	ds_read_b128 v[118:121], v249 offset:4096
	ds_read_b128 v[26:29], v248
	ds_read_b128 v[30:33], v247
	ds_read_b128 v[34:37], v247 offset:4096
	s_setprio 1
	s_waitcnt lgkmcnt(1)
	v_mfma_f32_16x16x32_bf16 v[66:69], v[122:125], v[30:33], v[90:93]
	s_nop 2
	ds_read_b128 v[90:93], v248 offset:4096
	v_mfma_f32_16x16x32_bf16 v[58:61], v[142:145], v[30:33], v[58:61]
	v_mfma_f32_16x16x32_bf16 v[62:65], v[134:137], v[30:33], v[82:85]
	v_mfma_f32_16x16x32_bf16 v[70:73], v[118:121], v[30:33], v[78:81]
	v_mfma_f32_16x16x32_bf16 v[50:53], v[142:145], v[26:29], v[74:77]
	v_mfma_f32_16x16x32_bf16 v[54:57], v[134:137], v[26:29], v[98:101]
	v_mfma_f32_16x16x32_bf16 v[30:33], v[122:125], v[26:29], v[106:109]
	v_mfma_f32_16x16x32_bf16 v[26:29], v[118:121], v[26:29], v[110:113]
	v_cndmask_b32_e64 v39, 0, 1, s[8:9]
	v_cmp_ne_u32_e64 s[2:3], 1, v39
	s_andn2_b64 vcc, exec, s[8:9]
	s_cbranch_vccnz .LBB0_1207
	s_waitcnt vmcnt(3)
	ds_write_b128 v244, v[14:17] offset:32768
	ds_write_b128 v244, v[10:13] offset:40960
.LBB0_1207:
	s_lshl_b32 s8, s42, 8
	s_ashr_i32 s9, s8, 31
	s_lshl_b64 s[14:15], s[8:9], 11
	s_add_u32 s8, s25, s14
	s_addc_u32 s9, s26, s15
	s_add_u32 s8, s8, s20
	s_addc_u32 s9, s9, s21
	s_waitcnt lgkmcnt(1)
	v_mfma_f32_16x16x32_bf16 v[38:41], v[142:145], v[34:37], v[126:129]
	global_load_dwordx4 v[10:13], v246, s[8:9]
	global_load_dwordx4 v[14:17], v245, s[8:9]
	v_mfma_f32_16x16x32_bf16 v[42:45], v[134:137], v[34:37], v[46:49]
	v_mfma_f32_16x16x32_bf16 v[46:49], v[122:125], v[34:37], v[130:133]
	v_mfma_f32_16x16x32_bf16 v[34:37], v[118:121], v[34:37], v[138:141]
	s_and_b64 vcc, exec, s[2:3]
	s_cbranch_vccnz .LBB0_1209
	s_waitcnt vmcnt(5)
	ds_write_b128 v244, v[6:9] offset:49152
	s_waitcnt vmcnt(4)
	ds_write_b128 v244, v[2:5] offset:57344
.LBB0_1209:
	s_waitcnt vmcnt(4)
	s_waitcnt lgkmcnt(0)
	v_mfma_f32_16x16x32_bf16 v[74:77], v[142:145], v[90:93], v[114:117]
	v_mfma_f32_16x16x32_bf16 v[78:81], v[134:137], v[90:93], v[102:105]
	s_nop 0
	v_add_u32_e32 v98, 0x40000, v246
	global_load_dwordx4 v[2:5], v98, s[8:9]
	v_add_u32_e32 v100, 0x60000, v246
	global_load_dwordx4 v[6:9], v100, s[8:9]
	v_mfma_f32_16x16x32_bf16 v[82:85], v[122:125], v[90:93], v[94:97]
	v_mfma_f32_16x16x32_bf16 v[86:89], v[118:121], v[90:93], v[86:89]
	s_setprio 0
	s_add_i32 s45, s45, 1
	s_cmp_lg_u32 s45, 16
	s_cbranch_scc1 .LBB0_1218
	s_add_i32 s22, s22, s23
	s_cmp_ge_i32 s22, s29
	s_cbranch_scc1 .LBB0_1217
	s_mov_b32 s8, s10
	s_cmpk_gt_i32 s22, 0xaf
	s_cbranch_scc1 .LBB0_1217
	s_cmpk_gt_i32 s22, 0x9f
	s_mov_b64 s[2:3], -1
	s_cbranch_scc0 .LBB0_1214
	s_lshl_b32 s2, s22, 2
	s_add_i32 s2, s2, 0x7ffffd80
	s_and_b32 s9, s2, 0x7ffffff8
	s_and_b32 s2, s22, 1
	s_or_b32 s42, s2, 20
	s_mov_b64 s[2:3], 0

.LBB0_1218:
	s_barrier
	s_nop 0
	v_add_u32_e32 v100, 0x10000, v254
	ds_read_b128 v[94:97], v243
	ds_read_b128 v[102:105], v100
	v_add_u32_e32 v99, 0x11000, v254
	ds_read_b128 v[114:117], v243 offset:4096
	ds_read_b128 v[122:125], v99
	v_add_u32_e32 v107, 0x10000, v253
	v_add_u32_e32 v106, 0x10000, v252
	ds_read_b128 v[98:101], v107
	ds_read_b128 v[90:93], v106
	ds_read_b128 v[118:121], v106 offset:4096
	s_setprio 1
	ds_read_b128 v[126:129], v107 offset:4096
	s_waitcnt lgkmcnt(2)
	v_mfma_f32_16x16x32_bf16 v[58:61], v[94:97], v[90:93], v[58:61]
	s_cmp_lt_i32 s36, s35
	s_cselect_b64 s[20:21], -1, 0
	s_cmp_ge_i32 s36, s35
	v_mfma_f32_16x16x32_bf16 v[62:65], v[102:105], v[90:93], v[62:65]
	s_cselect_b64 s[8:9], -1, 0
	v_mfma_f32_16x16x32_bf16 v[66:69], v[114:117], v[90:93], v[66:69]
	v_mfma_f32_16x16x32_bf16 v[70:73], v[122:125], v[90:93], v[70:73]
	v_mfma_f32_16x16x32_bf16 v[50:53], v[94:97], v[98:101], v[50:53]
	v_mfma_f32_16x16x32_bf16 v[54:57], v[102:105], v[98:101], v[54:57]
	v_mfma_f32_16x16x32_bf16 v[90:93], v[114:117], v[98:101], v[30:33]
	v_mfma_f32_16x16x32_bf16 v[98:101], v[122:125], v[98:101], v[26:29]
	s_nop 2
	s_and_b64 vcc, exec, s[8:9]
	s_cbranch_vccnz .LBB0_1220
	s_waitcnt vmcnt(5)
	ds_write_b128 v251, v[18:21]
	s_waitcnt vmcnt(4)
	ds_write_b128 v251, v[22:25] offset:8192
.LBB0_1220:
	s_lshl_b32 s2, s45, 6
	s_ashr_i32 s3, s2, 31
	s_add_u32 s46, s11, s12
	s_addc_u32 s47, s24, s13
	s_lshl_b64 s[12:13], s[2:3], 1
	s_waitcnt vmcnt(5)
	s_add_u32 s2, s46, s12
	s_addc_u32 s3, s47, s13
	s_waitcnt lgkmcnt(1)
	v_mfma_f32_16x16x32_bf16 v[106:109], v[94:97], v[118:121], v[38:41]
	global_load_dwordx4 v[22:25], v246, s[2:3]
	global_load_dwordx4 v[18:21], v245, s[2:3]
	v_mfma_f32_16x16x32_bf16 v[42:45], v[102:105], v[118:121], v[42:45]
	v_mfma_f32_16x16x32_bf16 v[110:113], v[114:117], v[118:121], v[46:49]
	v_mfma_f32_16x16x32_bf16 v[118:121], v[122:125], v[118:121], v[34:37]
	s_waitcnt lgkmcnt(0)
	v_mfma_f32_16x16x32_bf16 v[34:37], v[94:97], v[126:129], v[74:77]
	v_mfma_f32_16x16x32_bf16 v[30:33], v[102:105], v[126:129], v[78:81]
	v_mfma_f32_16x16x32_bf16 v[38:41], v[114:117], v[126:129], v[82:85]
	v_mfma_f32_16x16x32_bf16 v[26:29], v[122:125], v[126:129], v[86:89]
	s_setprio 0
	s_nop 0
	v_add_u32_e32 v49, 0x10000, v250
	v_add_u32_e32 v74, 0x10000, v249
	v_add_u32_e32 v46, 0x11000, v250
	v_add_u32_e32 v48, 0x11000, v249
	v_add_u32_e32 v130, 0x10000, v248
	ds_read_b128 v[122:125], v49
	ds_read_b128 v[102:105], v74
	ds_read_b128 v[114:117], v46
	ds_read_b128 v[94:97], v48
	v_add_u32_e32 v78, 0x10000, v247
	ds_read_b128 v[46:49], v130
	ds_read_b128 v[74:77], v78
	ds_read_b128 v[126:129], v78 offset:4096
	s_setprio 1
	s_waitcnt lgkmcnt(1)
	v_mfma_f32_16x16x32_bf16 v[78:81], v[94:97], v[74:77], v[70:73]
	v_mfma_f32_16x16x32_bf16 v[70:73], v[114:117], v[46:49], v[90:93]
	s_nop 2
	ds_read_b128 v[90:93], v130 offset:4096
	v_mfma_f32_16x16x32_bf16 v[58:61], v[122:125], v[74:77], v[58:61]
	v_mfma_f32_16x16x32_bf16 v[82:85], v[102:105], v[74:77], v[62:65]
	v_mfma_f32_16x16x32_bf16 v[86:89], v[114:117], v[74:77], v[66:69]
	v_mfma_f32_16x16x32_bf16 v[74:77], v[122:125], v[46:49], v[50:53]
	v_mfma_f32_16x16x32_bf16 v[66:69], v[102:105], v[46:49], v[54:57]
	v_mfma_f32_16x16x32_bf16 v[62:65], v[94:97], v[46:49], v[98:101]
	v_cndmask_b32_e64 v47, 0, 1, s[20:21]
	v_cmp_ne_u32_e64 s[2:3], 1, v47
	s_andn2_b64 vcc, exec, s[20:21]
	s_cbranch_vccnz .LBB0_1222
	s_waitcnt vmcnt(5)
	ds_write_b128 v251, v[10:13] offset:32768
	s_waitcnt vmcnt(4)
	ds_write_b128 v251, v[14:17] offset:40960
.LBB0_1222:
	s_add_u32 s14, s25, s14
	s_addc_u32 s15, s26, s15
	s_waitcnt vmcnt(5)
	s_add_u32 s12, s14, s12
	s_addc_u32 s13, s15, s13
	s_waitcnt lgkmcnt(1)
	v_mfma_f32_16x16x32_bf16 v[54:57], v[122:125], v[126:129], v[106:109]
	global_load_dwordx4 v[14:17], v246, s[12:13]
	global_load_dwordx4 v[10:13], v245, s[12:13]
	v_mfma_f32_16x16x32_bf16 v[46:49], v[102:105], v[126:129], v[42:45]
	v_mfma_f32_16x16x32_bf16 v[50:53], v[114:117], v[126:129], v[110:113]
	v_mfma_f32_16x16x32_bf16 v[42:45], v[94:97], v[126:129], v[118:121]
	s_and_b64 vcc, exec, s[2:3]
	s_cbranch_vccnz .LBB0_1224
	s_waitcnt vmcnt(5)
	ds_write_b128 v251, v[2:5] offset:49152
	s_waitcnt vmcnt(4)
	ds_write_b128 v251, v[6:9] offset:57344
.LBB0_1224:
	s_waitcnt vmcnt(5)
	s_waitcnt lgkmcnt(0)
	v_mfma_f32_16x16x32_bf16 v[34:37], v[122:125], v[90:93], v[34:37]
	v_mfma_f32_16x16x32_bf16 v[30:33], v[102:105], v[90:93], v[30:33]
	s_nop 0
	v_add_u32_e32 v98, 0x40000, v246
	global_load_dwordx4 v[6:9], v98, s[12:13]
	v_add_u32_e32 v100, 0x60000, v246
	global_load_dwordx4 v[2:5], v100, s[12:13]
	v_mfma_f32_16x16x32_bf16 v[38:41], v[114:117], v[90:93], v[38:41]
	v_mfma_f32_16x16x32_bf16 v[26:29], v[94:97], v[90:93], v[26:29]
	s_setprio 0
	s_add_i32 s45, s45, 1
	s_cmp_lg_u32 s45, 16
	s_cbranch_scc1 .LBB0_1233
	s_add_i32 s22, s22, s23
	s_cmp_ge_i32 s22, s29
	s_cbranch_scc1 .LBB0_1232
	s_mov_b32 s12, s10
	s_cmpk_gt_i32 s22, 0xaf
	s_cbranch_scc1 .LBB0_1232
	s_cmpk_gt_i32 s22, 0x9f
	s_mov_b64 s[2:3], -1
	s_cbranch_scc0 .LBB0_1229
	s_lshl_b32 s2, s22, 2
	s_add_i32 s2, s2, 0x7ffffd80
	s_and_b32 s13, s2, 0x7ffffff8
	s_and_b32 s2, s22, 1
	s_or_b32 s42, s2, 20
	s_mov_b64 s[2:3], 0

.LBB0_1298:
	v_mov_b32_e32 v255, 0x8000
	v_bfe_u32 v1, v0, 0, 1
	v_lshlrev_b32_e32 v1, 7, v1
	v_xor_b32_e32 v255, v255, v1
	v_bfe_u32 v1, v0, 1, 3
	v_mul_u32_u24_e32 v1, 0x110, v1
	v_xor_b32_e32 v255, v255, v1
	v_bfe_u32 v1, v0, 4, 2
	v_lshlrev_b32_e32 v1, 4, v1
	v_xor_b32_e32 v255, v255, v1
	v_bfe_u32 v1, v0, 6, 2
	v_lshlrev_b32_e32 v1, 13, v1
	v_xor_b32_e32 v255, v255, v1
	v_mov_b32_e32 v254, 0x8880
	v_bfe_u32 v1, v0, 0, 1
	v_lshlrev_b32_e32 v1, 7, v1
	v_xor_b32_e32 v254, v254, v1
	v_bfe_u32 v1, v0, 1, 3
	v_mul_u32_u24_e32 v1, 0x110, v1
	v_xor_b32_e32 v254, v254, v1
	v_bfe_u32 v1, v0, 4, 2
	v_lshlrev_b32_e32 v1, 4, v1
	v_xor_b32_e32 v254, v254, v1
	v_bfe_u32 v1, v0, 6, 2
	v_lshlrev_b32_e32 v1, 13, v1
	v_xor_b32_e32 v254, v254, v1
	v_mov_b32_e32 v253, 0x880
	v_bfe_u32 v1, v0, 0, 1
	v_lshlrev_b32_e32 v1, 7, v1
	v_xor_b32_e32 v253, v253, v1
	v_bfe_u32 v1, v0, 1, 3
	v_mul_u32_u24_e32 v1, 0x110, v1
	v_xor_b32_e32 v253, v253, v1
	v_bfe_u32 v1, v0, 4, 2
	v_lshlrev_b32_e32 v1, 4, v1
	v_xor_b32_e32 v253, v253, v1
	v_bfe_u32 v1, v0, 8, 1
	v_lshlrev_b32_e32 v1, 14, v1
	v_xor_b32_e32 v253, v253, v1
	v_mov_b32_e32 v252, 0x0
	v_bfe_u32 v1, v0, 0, 1
	v_lshlrev_b32_e32 v1, 7, v1
	v_xor_b32_e32 v252, v252, v1
	v_bfe_u32 v1, v0, 1, 3
	v_mul_u32_u24_e32 v1, 0x110, v1
	v_xor_b32_e32 v252, v252, v1
	v_bfe_u32 v1, v0, 4, 2
	v_lshlrev_b32_e32 v1, 4, v1
	v_xor_b32_e32 v252, v252, v1
	v_bfe_u32 v1, v0, 8, 1
	v_lshlrev_b32_e32 v1, 14, v1
	v_xor_b32_e32 v252, v252, v1
	v_mov_b32_e32 v251, 0x0
	v_bfe_u32 v1, v0, 0, 4
	v_lshlrev_b32_e32 v1, 4, v1
	v_xor_b32_e32 v251, v251, v1
	v_bfe_u32 v1, v0, 4, 4
	v_mul_u32_u24_e32 v1, 0x110, v1
	v_xor_b32_e32 v251, v251, v1
	v_bfe_u32 v1, v0, 8, 1
	v_lshlrev_b32_e32 v1, 12, v1
	v_xor_b32_e32 v251, v251, v1
	v_mov_b32_e32 v250, 0x88c0
	v_bfe_u32 v1, v0, 0, 1
	v_lshlrev_b32_e32 v1, 7, v1
	v_xor_b32_e32 v250, v250, v1
	v_bfe_u32 v1, v0, 1, 3
	v_mul_u32_u24_e32 v1, 0x110, v1
	v_xor_b32_e32 v250, v250, v1
	v_bfe_u32 v1, v0, 4, 2
	v_lshlrev_b32_e32 v1, 4, v1
	v_xor_b32_e32 v250, v250, v1
	v_bfe_u32 v1, v0, 6, 2
	v_lshlrev_b32_e32 v1, 13, v1
	v_xor_b32_e32 v250, v250, v1
	v_mov_b32_e32 v249, 0x8040
	v_bfe_u32 v1, v0, 0, 1
	v_lshlrev_b32_e32 v1, 7, v1
	v_xor_b32_e32 v249, v249, v1
	v_bfe_u32 v1, v0, 1, 3
	v_mul_u32_u24_e32 v1, 0x110, v1
	v_xor_b32_e32 v249, v249, v1
	v_bfe_u32 v1, v0, 4, 2
	v_lshlrev_b32_e32 v1, 4, v1
	v_xor_b32_e32 v249, v249, v1
	v_bfe_u32 v1, v0, 6, 2
	v_lshlrev_b32_e32 v1, 13, v1
	v_xor_b32_e32 v249, v249, v1
	v_mov_b32_e32 v248, 0x8c0
	v_bfe_u32 v1, v0, 0, 1
	v_lshlrev_b32_e32 v1, 7, v1
	v_xor_b32_e32 v248, v248, v1
	v_bfe_u32 v1, v0, 1, 3
	v_mul_u32_u24_e32 v1, 0x110, v1
	v_xor_b32_e32 v248, v248, v1
	v_bfe_u32 v1, v0, 4, 2
	v_lshlrev_b32_e32 v1, 4, v1
	v_xor_b32_e32 v248, v248, v1
	v_bfe_u32 v1, v0, 8, 1
	v_lshlrev_b32_e32 v1, 14, v1
	v_xor_b32_e32 v248, v248, v1
	v_mov_b32_e32 v247, 0x40
	v_bfe_u32 v1, v0, 0, 1
	v_lshlrev_b32_e32 v1, 7, v1
	v_xor_b32_e32 v247, v247, v1
	v_bfe_u32 v1, v0, 1, 3
	v_mul_u32_u24_e32 v1, 0x110, v1
	v_xor_b32_e32 v247, v247, v1
	v_bfe_u32 v1, v0, 4, 2
	v_lshlrev_b32_e32 v1, 4, v1
	v_xor_b32_e32 v247, v247, v1
	v_bfe_u32 v1, v0, 8, 1
	v_lshlrev_b32_e32 v1, 14, v1
	v_xor_b32_e32 v247, v247, v1
	v_mov_b32_e32 v246, 0x0
	v_bfe_u32 v1, v0, 0, 3
	v_lshlrev_b32_e32 v1, 4, v1
	v_add_u32_e32 v246, v246, v1
	v_bfe_u32 v1, v0, 3, 6
	v_mul_u32_u24_e32 v1, 0x1600, v1
	v_add_u32_e32 v246, v246, v1
	v_mov_b32_e32 v245, 0x10000
	v_bfe_u32 v1, v0, 0, 4
	v_lshlrev_b32_e32 v1, 4, v1
	v_xor_b32_e32 v245, v245, v1
	v_bfe_u32 v1, v0, 4, 4
	v_mul_u32_u24_e32 v1, 0x110, v1
	v_xor_b32_e32 v245, v245, v1
	v_bfe_u32 v1, v0, 8, 1
	v_lshlrev_b32_e32 v1, 12, v1
	v_xor_b32_e32 v245, v245, v1
	v_mov_b32_e32 v244, 0x58000
	v_bfe_u32 v1, v0, 0, 3
	v_lshlrev_b32_e32 v1, 4, v1
	v_add_u32_e32 v244, v244, v1
	v_bfe_u32 v1, v0, 3, 6
	v_mul_u32_u24_e32 v1, 0x1600, v1
	v_add_u32_e32 v244, v244, v1
	v_mov_b32_e32 v243, 0xb0000
	v_bfe_u32 v1, v0, 0, 3
	v_lshlrev_b32_e32 v1, 4, v1
	v_add_u32_e32 v243, v243, v1
	v_bfe_u32 v1, v0, 3, 6
	v_mul_u32_u24_e32 v1, 0x1600, v1
	v_add_u32_e32 v243, v243, v1
	v_mov_b32_e32 v1, v0
	s_load_dword s2, s[0:1], 0xe0
	s_mov_b32 s3, s10
	v_mov_b32_e32 v1, v0
	s_waitcnt lgkmcnt(0)
	s_lshr_b32 s11, s2, 3
	s_waitcnt vmcnt(0)
	v_cvt_f32_u32_e32 v2, s11
	s_mov_b32 s2, s10
	s_ashr_i32 s3, s2, 3
	v_rcp_iflag_f32_e32 v2, v2
	s_ashr_i32 s4, s2, 31
	s_sub_i32 s2, 0, s11
	s_abs_i32 s3, s3
	v_mul_f32_e32 v1, 0x4f7ffffe, v2
	v_cvt_u32_f32_e32 v1, v1
	s_mov_b32 s50, 0
	v_readfirstlane_b32 s5, v1
	s_mul_i32 s2, s2, s5
	s_mul_hi_u32 s2, s5, s2
	s_add_i32 s2, s5, s2
	s_mul_hi_u32 s5, s3, s2
	s_mul_i32 s5, s5, s11
	s_sub_i32 s3, s3, s5
	s_sub_i32 s5, s3, s11
	s_cmp_ge_u32 s3, s11
	s_cselect_b32 s3, s5, s3
	s_sub_i32 s5, s3, s11
	s_cmp_ge_u32 s3, s11
	s_cselect_b32 s3, s5, s3
	s_xor_b32 s3, s3, s4
	s_sub_i32 s28, s3, s4
	s_mov_b32 s3, s10
	s_cmp_gt_i32 s28, 31
	s_cbranch_scc1 .LBB0_1362
	s_load_dwordx4 s[4:7], s[16:17], 0xc8
	s_mov_b32 s3, s10
	v_mov_b32_e32 v82, 0
	v_mov_b32_e32 v1, v0
	s_waitcnt lgkmcnt(0)
	s_add_u32 s12, s4, 0x2000000
	s_addc_u32 s13, s5, 0
	s_add_u32 s14, s6, 0x9000
	s_addc_u32 s15, s7, 0
	s_add_u32 s29, s6, 0x37f0000
	s_addc_u32 s30, s7, 0
	s_add_u32 s31, s6, 0x1270000
	s_addc_u32 s33, s7, 0
	s_ashr_i32 s6, s28, 31
	s_lshr_b32 s6, s6, 27
	s_add_i32 s6, s28, s6
	s_ashr_i32 s6, s6, 5
	s_lshl_b32 s7, s28, 1
	s_lshl_b32 s20, s6, 6
	s_sub_i32 s7, s7, s20
	s_lshl_b32 s6, s6, 2
	s_and_b32 s20, s28, 3
	s_or_b32 s34, s6, s20
	s_sub_i32 s6, s11, s28
	s_add_i32 s6, s6, 31
	s_mul_hi_u32 s2, s6, s2
	s_mul_i32 s20, s2, s11
	s_sub_i32 s6, s6, s20
	s_add_i32 s20, s2, 1
	s_sub_i32 s21, s6, s11
	s_cmp_ge_u32 s6, s11
	s_cselect_b32 s2, s20, s2
	s_cselect_b32 s6, s21, s6
	s_add_i32 s20, s2, 1
	s_cmp_ge_u32 s6, s11
	s_cselect_b32 s41, s20, s2
	s_and_b32 s2, s3, 7
	s_and_b32 s3, s7, -8
	s_movk_i32 s35, 0xb00
	v_lshrrev_b32_e32 v2, 3, v1
	s_or_b32 s36, s2, s3
	s_lshl_b32 s2, s34, 8
	s_mul_i32 s3, s34, 0x160000
	v_mul_lo_u32 v2, v2, s35
	v_lshlrev_b32_e32 v1, 3, v1
	s_mul_hi_i32 s6, s2, 0x1600
	s_add_u32 s2, s31, s3
	v_and_or_b32 v1, v1, 56, v2
	v_mov_b32_e32 v239, 0
	s_addc_u32 s3, s33, s6
	v_lshlrev_b32_e32 v238, 1, v1
	v_lshl_add_u64 v[2:3], s[2:3], 0, v[238:239]
	s_mov_b32 s37, 0x108000
	v_add_co_u32_e32 v34, vcc, s37, v2
	s_mov_b32 s20, 0xb0000
	s_nop 0
	v_addc_co_u32_e32 v35, vcc, 0, v3, vcc
	v_add_co_u32_e32 v36, vcc, s20, v2
	s_lshl_b32 s6, s36, 8
	s_mul_i32 s7, s36, 0x160000
	v_addc_co_u32_e32 v37, vcc, 0, v3, vcc
	s_mov_b32 s38, 0x58000
	s_mul_hi_i32 s21, s6, 0x1600
	s_add_u32 s6, s29, s7
	v_add_co_u32_e32 v2, vcc, s38, v2
	s_addc_u32 s7, s30, s21
	s_nop 0
	v_addc_co_u32_e32 v3, vcc, 0, v3, vcc
	v_lshl_add_u64 v[22:23], s[6:7], 0, v[238:239]
	v_add_co_u32_e32 v24, vcc, s20, v22
	global_load_dwordx4 v[2:5], v[2:3], off
	s_nop 0
	v_addc_co_u32_e32 v25, vcc, 0, v23, vcc
	v_add_co_u32_e32 v26, vcc, s38, v22
	v_mov_b32_e32 v1, v0
	s_nop 0
	v_addc_co_u32_e32 v27, vcc, 0, v23, vcc
	v_add_co_u32_e32 v38, vcc, s37, v22
	global_load_dwordx4 v[6:9], v[24:25], off
	global_load_dwordx4 v[10:13], v[26:27], off
	global_load_dwordx4 v[14:17], v238, s[2:3]
	global_load_dwordx4 v[18:21], v238, s[6:7]
	v_addc_co_u32_e32 v39, vcc, 0, v23, vcc
	global_load_dwordx4 v[22:25], v[38:39], off
	global_load_dwordx4 v[26:29], v[36:37], off
	global_load_dwordx4 v[30:33], v[34:35], off
	s_movk_i32 s40, 0xf0
	v_ashrrev_i32_e32 v34, 4, v1
	v_xor_b32_e32 v1, v34, v1
	v_lshlrev_b32_e32 v34, 8, v34
	v_lshlrev_b32_e32 v1, 4, v1
	v_and_or_b32 v1, v1, s40, v34
	s_mov_b32 s39, 2
	s_mul_i32 s41, s41, 44
	s_movk_i32 s42, 0xff80
	s_mov_b32 s43, 0x10000
	s_mov_b32 s44, 0x11000
	s_movk_i32 s45, 0x1800
	s_movk_i32 s46, 0x1fff
	v_mov_b32_e32 v240, 0x8040
	s_mov_b32 s26, 2
	s_mov_b32 s47, s28
	s_mov_b32 s48, s34
	s_mov_b32 s49, s36
	v_mov_b32_e32 v83, v82
	v_mov_b32_e32 v84, v82
	v_mov_b32_e32 v85, v82
	v_mov_b32_e32 v102, v82
	v_mov_b32_e32 v103, v82
	v_mov_b32_e32 v104, v82
	v_mov_b32_e32 v105, v82
	v_mov_b32_e32 v106, v82
	v_mov_b32_e32 v107, v82
	v_mov_b32_e32 v108, v82
	v_mov_b32_e32 v109, v82
	v_mov_b32_e32 v110, v82
	v_mov_b32_e32 v111, v82
	v_mov_b32_e32 v112, v82
	v_mov_b32_e32 v113, v82
	s_waitcnt vmcnt(4)
	ds_write_b128 v1, v[14:17] offset:32768
	s_waitcnt vmcnt(3)
	ds_write_b128 v1, v[18:21]
	ds_write_b128 v1, v[2:5] offset:40960
	ds_write_b128 v1, v[10:13] offset:8192
	ds_write_b128 v1, v[6:9] offset:16384
	s_waitcnt vmcnt(2)
	ds_write_b128 v1, v[22:25] offset:24576
	s_waitcnt vmcnt(1)
	ds_write_b128 v1, v[26:29] offset:49152
	s_waitcnt vmcnt(0)
	ds_write_b128 v1, v[30:33] offset:57344
	v_mov_b32_e32 v1, v0
	v_mov_b32_e32 v114, v82
	v_lshrrev_b32_e32 v2, 3, v1
	v_mul_lo_u32 v2, v2, s35
	v_lshlrev_b32_e32 v1, 3, v1
	v_and_or_b32 v1, v1, 56, v2
	v_lshlrev_b32_e32 v238, 1, v1
	v_lshl_add_u64 v[10:11], s[2:3], 0, v[238:239]
	v_add_co_u32_e32 v12, vcc, s37, v10
	v_lshl_add_u64 v[16:17], s[6:7], 0, v[238:239]
	s_nop 0
	v_addc_co_u32_e32 v13, vcc, 0, v11, vcc
	v_add_co_u32_e32 v14, vcc, s20, v10
	v_mov_b32_e32 v1, 0x10000
	s_nop 0
	v_addc_co_u32_e32 v15, vcc, 0, v11, vcc
	global_load_dwordx4 v[2:5], v[12:13], off offset:128
	global_load_dwordx4 v[6:9], v[14:15], off offset:128
	v_add_co_u32_e32 v14, vcc, s38, v10
	v_mov_b32_e32 v115, v82
	s_nop 0
	v_addc_co_u32_e32 v15, vcc, 0, v11, vcc
	v_add_co_u32_e32 v22, vcc, s37, v16
	v_mov_b32_e32 v116, v82
	s_nop 0
	v_addc_co_u32_e32 v23, vcc, 0, v17, vcc
	v_add_co_u32_e32 v34, vcc, s20, v16
	global_load_dwordx4 v[10:13], v[14:15], off offset:128
	global_load_dwordx4 v[18:21], v[22:23], off offset:128
	v_addc_co_u32_e32 v35, vcc, 0, v17, vcc
	v_add_co_u32_e32 v36, vcc, s38, v16
	v_mov_b32_e32 v117, v82
	s_nop 0
	v_addc_co_u32_e32 v37, vcc, 0, v17, vcc
	global_load_dwordx4 v[22:25], v[34:35], off offset:128
	global_load_dwordx4 v[26:29], v[36:37], off offset:128
	global_load_dwordx4 v[14:17], v238, s[2:3] offset:128
	global_load_dwordx4 v[30:33], v238, s[6:7] offset:128
	v_mov_b32_e32 v118, v82
	v_mov_b32_e32 v119, v82
	v_mov_b32_e32 v120, v82
	v_mov_b32_e32 v121, v82
	v_mov_b32_e32 v122, v82
	v_mov_b32_e32 v123, v82
	v_mov_b32_e32 v124, v82
	v_mov_b32_e32 v125, v82
	v_mov_b32_e32 v126, v82
	v_mov_b32_e32 v127, v82
	v_mov_b32_e32 v128, v82
	v_mov_b32_e32 v129, v82
	v_mov_b32_e32 v130, v82
	v_mov_b32_e32 v131, v82
	v_mov_b32_e32 v132, v82
	v_mov_b32_e32 v133, v82
	v_mov_b32_e32 v134, v82
	v_mov_b32_e32 v135, v82
	v_mov_b32_e32 v136, v82
	v_mov_b32_e32 v137, v82
	v_mov_b32_e32 v138, v82
	v_mov_b32_e32 v139, v82
	v_mov_b32_e32 v140, v82
	v_mov_b32_e32 v141, v82
	v_mov_b32_e32 v142, v82
	v_mov_b32_e32 v143, v82
	v_mov_b32_e32 v144, v82
	v_mov_b32_e32 v145, v82
	v_mov_b32_e32 v146, v82
	v_mov_b32_e32 v147, v82
	v_mov_b32_e32 v148, v82
	v_mov_b32_e32 v149, v82
	v_mov_b32_e32 v150, v82
	v_mov_b32_e32 v151, v82
	v_mov_b32_e32 v152, v82
	v_mov_b32_e32 v153, v82
	v_mov_b32_e32 v154, v82
	v_mov_b32_e32 v155, v82
	v_mov_b32_e32 v156, v82
	v_mov_b32_e32 v157, v82
	v_mov_b32_e32 v158, v82
	v_mov_b32_e32 v159, v82
	v_mov_b32_e32 v160, v82
	v_mov_b32_e32 v161, v82
	v_mov_b32_e32 v98, v82
	v_mov_b32_e32 v99, v82
	v_mov_b32_e32 v100, v82
	v_mov_b32_e32 v101, v82
	v_mov_b32_e32 v94, v82
	v_mov_b32_e32 v95, v82
	v_mov_b32_e32 v96, v82
	v_mov_b32_e32 v97, v82
	v_mov_b32_e32 v90, v82
	v_mov_b32_e32 v91, v82
	v_mov_b32_e32 v92, v82
	v_mov_b32_e32 v93, v82
	v_mov_b32_e32 v86, v82
	v_mov_b32_e32 v87, v82
	v_mov_b32_e32 v88, v82
	v_mov_b32_e32 v89, v82
	v_mov_b32_e32 v78, v82
	v_mov_b32_e32 v79, v82
	v_mov_b32_e32 v80, v82
	v_mov_b32_e32 v81, v82
	v_mov_b32_e32 v74, v82
	v_mov_b32_e32 v75, v82
	v_mov_b32_e32 v76, v82
	v_mov_b32_e32 v77, v82
	v_mov_b32_e32 v70, v82
	v_mov_b32_e32 v71, v82
	v_mov_b32_e32 v72, v82
	v_mov_b32_e32 v73, v82
	v_mov_b32_e32 v66, v82
	v_mov_b32_e32 v67, v82
	v_mov_b32_e32 v68, v82
	v_mov_b32_e32 v69, v82
	v_mov_b32_e32 v62, v82
	v_mov_b32_e32 v63, v82
	v_mov_b32_e32 v64, v82
	v_mov_b32_e32 v65, v82
	v_mov_b32_e32 v58, v82
	v_mov_b32_e32 v59, v82
	v_mov_b32_e32 v60, v82
	v_mov_b32_e32 v61, v82
	v_mov_b32_e32 v54, v82
	v_mov_b32_e32 v55, v82
	v_mov_b32_e32 v56, v82
	v_mov_b32_e32 v57, v82
	v_mov_b32_e32 v50, v82
	v_mov_b32_e32 v51, v82
	v_mov_b32_e32 v52, v82
	v_mov_b32_e32 v53, v82
	v_mov_b32_e32 v46, v82
	v_mov_b32_e32 v47, v82
	v_mov_b32_e32 v48, v82
	v_mov_b32_e32 v49, v82
	v_mov_b32_e32 v42, v82
	v_mov_b32_e32 v43, v82
	v_mov_b32_e32 v44, v82
	v_mov_b32_e32 v45, v82
	v_mov_b32_e32 v38, v82
	v_mov_b32_e32 v39, v82
	v_mov_b32_e32 v40, v82
	v_mov_b32_e32 v41, v82
	v_mov_b32_e32 v34, v82
	v_mov_b32_e32 v35, v82
	v_mov_b32_e32 v36, v82
	v_mov_b32_e32 v37, v82
	s_waitcnt lgkmcnt(0)
	s_barrier
	s_branch .LBB0_1302

.LBB0_1302:
	s_add_i32 s2, s39, -1
	ds_read_b128 v[174:177], v255
	ds_read_b128 v[166:169], v255 offset:4096
	ds_read_b128 v[170:173], v254
	ds_read_b128 v[162:165], v254 offset:4096
	ds_read_b128 v[190:193], v253
	ds_read_b128 v[178:181], v252
	ds_read_b128 v[182:185], v252 offset:4096
	s_setprio 1
	s_waitcnt lgkmcnt(1)
	v_mfma_f32_16x16x32_bf16 v[158:161], v[174:177], v[178:181], v[158:161]
	s_cmp_lt_i32 s2, s41
	s_cselect_b64 s[22:23], -1, 0
	s_cmp_ge_i32 s2, s41
	v_mfma_f32_16x16x32_bf16 v[154:157], v[170:173], v[178:181], v[154:157]
	v_mfma_f32_16x16x32_bf16 v[150:153], v[166:169], v[178:181], v[150:153]
	v_mfma_f32_16x16x32_bf16 v[146:149], v[162:165], v[178:181], v[146:149]
	ds_read_b128 v[186:189], v253 offset:4096
	ds_read_b128 v[178:181], v252 offset:8192
	v_mfma_f32_16x16x32_bf16 v[142:145], v[174:177], v[190:193], v[142:145]
	v_mfma_f32_16x16x32_bf16 v[138:141], v[170:173], v[190:193], v[138:141]
	v_mfma_f32_16x16x32_bf16 v[134:137], v[166:169], v[190:193], v[134:137]
	v_mfma_f32_16x16x32_bf16 v[130:133], v[162:165], v[190:193], v[130:133]
	s_cbranch_scc1 .LBB0_1304
	s_waitcnt vmcnt(0)
	ds_write_b128 v245, v[30:33]
	ds_write_b128 v245, v[26:29] offset:8192
.LBB0_1304:
	s_lshl_b32 s2, s49, 8
	s_mul_i32 s20, s49, 0xb0000
	s_mul_hi_i32 s21, s2, 0xb00
	s_lshl_b32 s2, s26, 6
	s_ashr_i32 s3, s2, 31
	s_lshl_b64 s[6:7], s[20:21], 1
	s_add_u32 s24, s29, s6
	s_waitcnt vmcnt(2)
	s_addc_u32 s25, s30, s7
	s_lshl_b64 s[6:7], s[2:3], 1
	s_add_u32 s24, s24, s6
	s_addc_u32 s25, s25, s7
	s_waitcnt vmcnt(0)
	s_nop 0
	ds_read_b128 v[200:203], v253 offset:8192
	ds_read_b128 v[210:213], v253 offset:12288
	global_load_dwordx4 v[26:29], v246, s[24:25]
	s_waitcnt lgkmcnt(4)
	v_mfma_f32_16x16x32_bf16 v[126:129], v[174:177], v[182:185], v[126:129]
	global_load_dwordx4 v[30:33], v244, s[24:25]
	v_mfma_f32_16x16x32_bf16 v[122:125], v[170:173], v[182:185], v[122:125]
	v_mfma_f32_16x16x32_bf16 v[118:121], v[166:169], v[182:185], v[118:121]
	v_mfma_f32_16x16x32_bf16 v[114:117], v[162:165], v[182:185], v[114:117]
	s_waitcnt lgkmcnt(2)
	v_mfma_f32_16x16x32_bf16 v[182:185], v[174:177], v[178:181], v[98:101]
	s_waitcnt lgkmcnt(1)
	v_mfma_f32_16x16x32_bf16 v[98:101], v[166:169], v[200:203], v[70:73]
	s_nop 2
	ds_read_b128 v[70:73], v252 offset:12288
	v_mfma_f32_16x16x32_bf16 v[110:113], v[174:177], v[186:189], v[110:113]
	v_mfma_f32_16x16x32_bf16 v[106:109], v[170:173], v[186:189], v[106:109]
	v_mfma_f32_16x16x32_bf16 v[102:105], v[166:169], v[186:189], v[102:105]
	v_mfma_f32_16x16x32_bf16 v[82:85], v[162:165], v[186:189], v[82:85]
	v_mfma_f32_16x16x32_bf16 v[186:189], v[170:173], v[178:181], v[94:97]
	v_mfma_f32_16x16x32_bf16 v[190:193], v[166:169], v[178:181], v[90:93]
	v_mfma_f32_16x16x32_bf16 v[86:89], v[162:165], v[178:181], v[86:89]
	v_mfma_f32_16x16x32_bf16 v[90:93], v[174:177], v[200:203], v[78:81]
	v_mfma_f32_16x16x32_bf16 v[94:97], v[170:173], v[200:203], v[74:77]
	v_mfma_f32_16x16x32_bf16 v[178:181], v[162:165], v[200:203], v[66:69]
	s_nop 2
	v_cndmask_b32_e64 v67, 0, 1, s[22:23]
	v_cmp_ne_u32_e64 s[2:3], 1, v67
	s_andn2_b64 vcc, exec, s[22:23]
	s_cbranch_vccnz .LBB0_1306
	ds_write_b128 v245, v[22:25] offset:16384
	ds_write_b128 v245, v[18:21] offset:24576
.LBB0_1306:
	s_waitcnt lgkmcnt(0)
	v_mfma_f32_16x16x32_bf16 v[194:197], v[174:177], v[70:73], v[62:65]
	v_mfma_f32_16x16x32_bf16 v[198:201], v[170:173], v[70:73], v[58:61]
	s_nop 0
	global_load_dwordx4 v[18:21], v243, s[24:25]
	s_nop 0
	v_add_u32_e32 v22, 0x108000, v246
	global_load_dwordx4 v[22:25], v22, s[24:25]
	v_mfma_f32_16x16x32_bf16 v[202:205], v[166:169], v[70:73], v[54:57]
	v_mfma_f32_16x16x32_bf16 v[206:209], v[162:165], v[70:73], v[50:53]
	v_mfma_f32_16x16x32_bf16 v[174:177], v[174:177], v[210:213], v[46:49]
	v_mfma_f32_16x16x32_bf16 v[170:173], v[170:173], v[210:213], v[42:45]
	v_mfma_f32_16x16x32_bf16 v[166:169], v[166:169], v[210:213], v[38:41]
	v_mfma_f32_16x16x32_bf16 v[162:165], v[162:165], v[210:213], v[34:37]
	s_setprio 0
	s_nop 1
	s_nop 0
	ds_read_b128 v[218:221], v250
	ds_read_b128 v[214:217], v249 offset:4096
	ds_read_b128 v[210:213], v250 offset:4096
	ds_read_b128 v[222:225], v249
	ds_read_b128 v[34:37], v248
	ds_read_b128 v[38:41], v247
	ds_read_b128 v[54:57], v247 offset:4096
	s_setprio 1
	s_waitcnt lgkmcnt(1)
	v_mfma_f32_16x16x32_bf16 v[158:161], v[222:225], v[38:41], v[158:161]
	v_mfma_f32_16x16x32_bf16 v[154:157], v[218:221], v[38:41], v[154:157]
	v_mfma_f32_16x16x32_bf16 v[150:153], v[214:217], v[38:41], v[150:153]
	v_mfma_f32_16x16x32_bf16 v[146:149], v[210:213], v[38:41], v[146:149]
	v_mfma_f32_16x16x32_bf16 v[38:41], v[214:217], v[34:37], v[134:137]
	ds_read_b128 v[70:73], v248 offset:4096
	s_nop 1
	ds_read_b128 v[134:137], v247 offset:8192
	v_mfma_f32_16x16x32_bf16 v[142:145], v[222:225], v[34:37], v[142:145]
	v_mfma_f32_16x16x32_bf16 v[138:141], v[218:221], v[34:37], v[138:141]
	v_mfma_f32_16x16x32_bf16 v[34:37], v[210:213], v[34:37], v[130:133]
	s_nop 2
	s_and_b64 vcc, exec, s[2:3]
	s_cbranch_vccnz .LBB0_1308
	ds_write_b128 v245, v[14:17] offset:32768
	ds_write_b128 v245, v[10:13] offset:40960
.LBB0_1308:
	s_lshl_b32 s23, s48, 8
	s_mul_i32 s22, s48, 0xb0000
	s_mul_hi_i32 s23, s23, 0xb00
	s_lshl_b64 s[24:25], s[22:23], 1
	s_add_u32 s24, s31, s24
	s_addc_u32 s25, s33, s25
	s_add_u32 s6, s24, s6
	s_addc_u32 s7, s25, s7
	s_waitcnt lgkmcnt(2)
	v_mfma_f32_16x16x32_bf16 v[50:53], v[214:217], v[54:57], v[118:121]
	s_waitcnt lgkmcnt(1)
	v_mfma_f32_16x16x32_bf16 v[66:69], v[214:217], v[70:73], v[102:105]
	ds_read_b128 v[118:121], v247 offset:12288
	s_nop 1
	ds_read_b128 v[102:105], v248 offset:8192
	global_load_dwordx4 v[10:13], v246, s[6:7]
	s_nop 0
	global_load_dwordx4 v[14:17], v244, s[6:7]
	v_mfma_f32_16x16x32_bf16 v[58:61], v[222:225], v[70:73], v[110:113]
	v_mfma_f32_16x16x32_bf16 v[62:65], v[218:221], v[70:73], v[106:109]
	v_mfma_f32_16x16x32_bf16 v[70:73], v[210:213], v[70:73], v[82:85]
	s_waitcnt lgkmcnt(2)
	v_mfma_f32_16x16x32_bf16 v[74:77], v[222:225], v[134:137], v[182:185]
	v_mfma_f32_16x16x32_bf16 v[78:81], v[218:221], v[134:137], v[186:189]
	v_mfma_f32_16x16x32_bf16 v[82:85], v[214:217], v[134:137], v[190:193]
	v_mfma_f32_16x16x32_bf16 v[86:89], v[210:213], v[134:137], v[86:89]
	ds_read_b128 v[134:137], v248 offset:12288
	v_mfma_f32_16x16x32_bf16 v[42:45], v[222:225], v[54:57], v[126:129]
	v_mfma_f32_16x16x32_bf16 v[46:49], v[218:221], v[54:57], v[122:125]
	v_mfma_f32_16x16x32_bf16 v[54:57], v[210:213], v[54:57], v[114:117]
	s_waitcnt lgkmcnt(1)
	v_mfma_f32_16x16x32_bf16 v[90:93], v[222:225], v[102:105], v[90:93]
	v_mfma_f32_16x16x32_bf16 v[94:97], v[218:221], v[102:105], v[94:97]
	v_mfma_f32_16x16x32_bf16 v[98:101], v[214:217], v[102:105], v[98:101]
	v_mfma_f32_16x16x32_bf16 v[102:105], v[210:213], v[102:105], v[178:181]
	s_and_b64 vcc, exec, s[2:3]
	s_cbranch_vccnz .LBB0_1310
	ds_write_b128 v245, v[6:9] offset:49152
	ds_write_b128 v245, v[2:5] offset:57344
.LBB0_1310:
	v_mfma_f32_16x16x32_bf16 v[106:109], v[222:225], v[118:121], v[194:197]
	s_nop 0
	v_mfma_f32_16x16x32_bf16 v[110:113], v[218:221], v[118:121], v[198:201]
	s_nop 0
	global_load_dwordx4 v[2:5], v243, s[6:7]
	s_nop 0
	v_add_u32_e32 v6, 0x108000, v246
	global_load_dwordx4 v[6:9], v6, s[6:7]
	v_mfma_f32_16x16x32_bf16 v[114:117], v[214:217], v[118:121], v[202:205]
	v_mfma_f32_16x16x32_bf16 v[118:121], v[210:213], v[118:121], v[206:209]
	s_waitcnt lgkmcnt(0)
	v_mfma_f32_16x16x32_bf16 v[122:125], v[222:225], v[134:137], v[174:177]
	v_mfma_f32_16x16x32_bf16 v[126:129], v[218:221], v[134:137], v[170:173]
	v_mfma_f32_16x16x32_bf16 v[130:133], v[214:217], v[134:137], v[166:169]
	v_mfma_f32_16x16x32_bf16 v[134:137], v[210:213], v[134:137], v[162:165]
	s_setprio 0
	s_add_i32 s51, s26, 1
	s_cmp_lg_u32 s51, 44
	s_cbranch_scc1 .LBB0_1314
	s_add_i32 s28, s28, s11
	s_cmp_gt_i32 s28, 31
	s_cbranch_scc1 .LBB0_1313
	s_ashr_i32 s3, s28, 31
	s_lshr_b32 s3, s3, 27
	s_add_i32 s3, s28, s3
	s_ashr_i32 s3, s3, 5
	s_mov_b32 s2, s10
	s_lshl_b32 s6, s3, 6
	s_lshl_b32 s7, s28, 1
	s_sub_i32 s6, s7, s6
	s_and_b32 s2, s2, 7
	s_and_b32 s6, s6, -8
	s_lshl_b32 s3, s3, 2
	s_and_b32 s7, s28, 3
	s_or_b32 s49, s2, s6
	s_or_b32 s48, s3, s7
	s_lshl_b32 s2, s49, 8
	s_mul_hi_i32 s21, s2, 0xb00
	s_lshl_b32 s2, s48, 8
	s_mul_i32 s20, s49, 0xb0000
	s_mul_i32 s22, s48, 0xb0000
	s_mul_hi_i32 s23, s2, 0xb00

.LBB0_1314:
	s_barrier
	s_nop 0
	v_add_u32_e32 v170, 0x10000, v255
	v_add_u32_e32 v162, 0x11000, v255
	v_add_u32_e32 v171, 0x10000, v254
	ds_read_b128 v[206:209], v170
	ds_read_b128 v[210:213], v171
	v_add_u32_e32 v169, 0x11000, v254
	ds_read_b128 v[214:217], v162
	ds_read_b128 v[218:221], v169
	v_add_u32_e32 v186, 0x10000, v253
	v_add_u32_e32 v187, 0x10000, v252
	ds_read_b128 v[162:165], v186
	ds_read_b128 v[166:169], v187
	ds_read_b128 v[174:177], v187 offset:4096
	s_setprio 1
	ds_read_b128 v[182:185], v186 offset:4096
	ds_read_b128 v[178:181], v187 offset:8192
	s_waitcnt lgkmcnt(3)
	v_mfma_f32_16x16x32_bf16 v[158:161], v[206:209], v[166:169], v[158:161]
	s_cmp_lt_i32 s39, s41
	s_cselect_b64 s[24:25], -1, 0
	s_cmp_ge_i32 s39, s41
	v_mfma_f32_16x16x32_bf16 v[154:157], v[210:213], v[166:169], v[154:157]
	s_cselect_b64 s[6:7], -1, 0
	v_mfma_f32_16x16x32_bf16 v[150:153], v[214:217], v[166:169], v[150:153]
	v_mfma_f32_16x16x32_bf16 v[146:149], v[218:221], v[166:169], v[146:149]
	v_mfma_f32_16x16x32_bf16 v[142:145], v[206:209], v[162:165], v[142:145]
	v_mfma_f32_16x16x32_bf16 v[138:141], v[210:213], v[162:165], v[138:141]
	v_mfma_f32_16x16x32_bf16 v[38:41], v[214:217], v[162:165], v[38:41]
	v_mfma_f32_16x16x32_bf16 v[34:37], v[218:221], v[162:165], v[34:37]
	s_and_b64 vcc, exec, s[6:7]
	s_cbranch_vccnz .LBB0_1316
	s_waitcnt vmcnt(7)
	ds_write_b128 v251, v[26:29]
	s_waitcnt vmcnt(6)
	ds_write_b128 v251, v[30:33] offset:8192
.LBB0_1316:
	s_lshl_b32 s2, s51, 6
	s_ashr_i32 s3, s2, 31
	s_lshl_b64 s[20:21], s[20:21], 1
	s_add_u32 s26, s29, s20
	s_waitcnt vmcnt(7)
	s_addc_u32 s27, s30, s21
	s_lshl_b64 s[20:21], s[2:3], 1
	s_add_u32 s26, s26, s20
	s_addc_u32 s27, s27, s21
	s_waitcnt lgkmcnt(2)
	v_mfma_f32_16x16x32_bf16 v[170:173], v[214:217], v[174:177], v[50:53]
	ds_read_b128 v[190:193], v186 offset:8192
	s_waitcnt lgkmcnt(1)
	v_mfma_f32_16x16x32_bf16 v[50:53], v[214:217], v[178:181], v[82:85]
	s_nop 2
	ds_read_b128 v[82:85], v187 offset:12288
	global_load_dwordx4 v[30:33], v246, s[26:27]
	s_nop 0
	global_load_dwordx4 v[26:29], v244, s[26:27]
	v_mfma_f32_16x16x32_bf16 v[166:169], v[210:213], v[174:177], v[46:49]
	v_mfma_f32_16x16x32_bf16 v[46:49], v[210:213], v[178:181], v[78:81]
	s_nop 2
	ds_read_b128 v[78:81], v186 offset:12288
	v_mfma_f32_16x16x32_bf16 v[162:165], v[206:209], v[174:177], v[42:45]
	v_mfma_f32_16x16x32_bf16 v[174:177], v[218:221], v[174:177], v[54:57]
	v_mfma_f32_16x16x32_bf16 v[58:61], v[206:209], v[182:185], v[58:61]
	v_mfma_f32_16x16x32_bf16 v[62:65], v[210:213], v[182:185], v[62:65]
	v_mfma_f32_16x16x32_bf16 v[66:69], v[214:217], v[182:185], v[66:69]
	v_mfma_f32_16x16x32_bf16 v[70:73], v[218:221], v[182:185], v[70:73]
	v_mfma_f32_16x16x32_bf16 v[42:45], v[206:209], v[178:181], v[74:77]
	v_mfma_f32_16x16x32_bf16 v[54:57], v[218:221], v[178:181], v[86:89]
	s_waitcnt lgkmcnt(2)
	v_mfma_f32_16x16x32_bf16 v[74:77], v[206:209], v[190:193], v[90:93]
	v_mfma_f32_16x16x32_bf16 v[178:181], v[210:213], v[190:193], v[94:97]
	v_mfma_f32_16x16x32_bf16 v[182:185], v[214:217], v[190:193], v[98:101]
	v_mfma_f32_16x16x32_bf16 v[186:189], v[218:221], v[190:193], v[102:105]
	v_cndmask_b32_e64 v87, 0, 1, s[24:25]
	v_cmp_ne_u32_e64 s[2:3], 1, v87
	s_andn2_b64 vcc, exec, s[24:25]
	s_cbranch_vccnz .LBB0_1318
	s_waitcnt vmcnt(7)
	ds_write_b128 v251, v[18:21] offset:16384
	s_waitcnt vmcnt(6)
	ds_write_b128 v251, v[22:25] offset:24576
.LBB0_1318:
	s_waitcnt vmcnt(7)
	s_waitcnt lgkmcnt(1)
	v_mfma_f32_16x16x32_bf16 v[190:193], v[206:209], v[82:85], v[106:109]
	v_mfma_f32_16x16x32_bf16 v[194:197], v[210:213], v[82:85], v[110:113]
	s_nop 0
	global_load_dwordx4 v[22:25], v243, s[26:27]
	s_nop 0
	v_add_u32_e32 v18, 0x108000, v246
	global_load_dwordx4 v[18:21], v18, s[26:27]
	v_mfma_f32_16x16x32_bf16 v[198:201], v[214:217], v[82:85], v[114:117]
	v_mfma_f32_16x16x32_bf16 v[202:205], v[218:221], v[82:85], v[118:121]
	s_waitcnt lgkmcnt(0)
	v_mfma_f32_16x16x32_bf16 v[206:209], v[206:209], v[78:81], v[122:125]
	v_mfma_f32_16x16x32_bf16 v[210:213], v[210:213], v[78:81], v[126:129]
	v_mfma_f32_16x16x32_bf16 v[214:217], v[214:217], v[78:81], v[130:133]
	v_mfma_f32_16x16x32_bf16 v[218:221], v[218:221], v[78:81], v[134:137]
	s_setprio 0
	s_nop 0
	v_add_u32_e32 v81, 0x10000, v249
	v_add_u32_e32 v78, 0x11000, v249
	v_add_u32_e32 v85, 0x10000, v250
	ds_read_b128 v[234:237], v81
	ds_read_b128 v[226:229], v85
	v_add_u32_e32 v80, 0x11000, v250
	ds_read_b128 v[230:233], v78
	ds_read_b128 v[222:225], v80
	v_add_u32_e32 v242, 0x10000, v248
	v_add_u32_e32 v90, 0x10000, v247
	ds_read_b128 v[86:89], v242
	ds_read_b128 v[82:85], v90
	ds_read_b128 v[78:81], v90 offset:4096
	s_setprio 1
	s_waitcnt lgkmcnt(1)
	v_mfma_f32_16x16x32_bf16 v[158:161], v[234:237], v[82:85], v[158:161]
	v_mfma_f32_16x16x32_bf16 v[154:157], v[226:229], v[82:85], v[154:157]
	v_mfma_f32_16x16x32_bf16 v[150:153], v[230:233], v[82:85], v[150:153]
	v_mfma_f32_16x16x32_bf16 v[146:149], v[222:225], v[82:85], v[146:149]
	v_mfma_f32_16x16x32_bf16 v[134:137], v[230:233], v[86:89], v[38:41]
	ds_read_b128 v[82:85], v242 offset:4096
	s_nop 1
	ds_read_b128 v[38:41], v90 offset:8192
	v_mfma_f32_16x16x32_bf16 v[142:145], v[234:237], v[86:89], v[142:145]
	v_mfma_f32_16x16x32_bf16 v[138:141], v[226:229], v[86:89], v[138:141]
	v_mfma_f32_16x16x32_bf16 v[130:133], v[222:225], v[86:89], v[34:37]
	s_nop 2
	s_and_b64 vcc, exec, s[2:3]
	s_cbranch_vccnz .LBB0_1320
	s_waitcnt vmcnt(7)
	ds_write_b128 v251, v[10:13] offset:32768
	s_waitcnt vmcnt(6)
	ds_write_b128 v251, v[14:17] offset:40960
.LBB0_1320:
	s_lshl_b64 s[22:23], s[22:23], 1
	s_add_u32 s22, s31, s22
	s_waitcnt vmcnt(7)
	s_addc_u32 s23, s33, s23
	s_add_u32 s20, s22, s20
	s_addc_u32 s21, s23, s21
	global_load_dwordx4 v[14:17], v246, s[20:21]
	s_nop 0
	global_load_dwordx4 v[10:13], v244, s[20:21]
	s_waitcnt lgkmcnt(0)
	v_mfma_f32_16x16x32_bf16 v[98:101], v[234:237], v[38:41], v[42:45]
	ds_read_b128 v[34:37], v242 offset:12288
	s_nop 1
	ds_read_b128 v[42:45], v242 offset:8192
	v_mfma_f32_16x16x32_bf16 v[94:97], v[226:229], v[38:41], v[46:49]
	v_mfma_f32_16x16x32_bf16 v[90:93], v[230:233], v[38:41], v[50:53]
	v_mfma_f32_16x16x32_bf16 v[86:89], v[222:225], v[38:41], v[54:57]
	v_add_u32_e32 v38, 0x13000, v247
	ds_read_b128 v[38:41], v38
	v_mfma_f32_16x16x32_bf16 v[126:129], v[234:237], v[78:81], v[162:165]
	v_mfma_f32_16x16x32_bf16 v[122:125], v[226:229], v[78:81], v[166:169]
	v_mfma_f32_16x16x32_bf16 v[118:121], v[230:233], v[78:81], v[170:173]
	v_mfma_f32_16x16x32_bf16 v[114:117], v[222:225], v[78:81], v[174:177]
	v_mfma_f32_16x16x32_bf16 v[110:113], v[234:237], v[82:85], v[58:61]
	v_mfma_f32_16x16x32_bf16 v[106:109], v[226:229], v[82:85], v[62:65]
	v_mfma_f32_16x16x32_bf16 v[102:105], v[230:233], v[82:85], v[66:69]
	v_mfma_f32_16x16x32_bf16 v[82:85], v[222:225], v[82:85], v[70:73]
	s_waitcnt lgkmcnt(1)
	v_mfma_f32_16x16x32_bf16 v[78:81], v[234:237], v[42:45], v[74:77]
	v_mfma_f32_16x16x32_bf16 v[74:77], v[226:229], v[42:45], v[178:181]
	v_mfma_f32_16x16x32_bf16 v[70:73], v[230:233], v[42:45], v[182:185]
	v_mfma_f32_16x16x32_bf16 v[66:69], v[222:225], v[42:45], v[186:189]
	v_mov_b32_e32 v42, v0
	s_and_b64 vcc, exec, s[2:3]
	s_cbranch_vccnz .LBB0_1322
	s_waitcnt vmcnt(7)
	ds_write_b128 v251, v[2:5] offset:49152
	s_waitcnt vmcnt(6)
	ds_write_b128 v251, v[6:9] offset:57344
.LBB0_1322:
	s_waitcnt vmcnt(7)
	v_lshrrev_b32_e32 v2, 3, v42
	v_mul_lo_u32 v2, v2, s35
	v_lshlrev_b32_e32 v3, 3, v42
	v_and_or_b32 v2, v3, 56, v2
	v_lshlrev_b32_e32 v238, 1, v2
	s_waitcnt lgkmcnt(0)
	v_mfma_f32_16x16x32_bf16 v[62:65], v[234:237], v[38:41], v[190:193]
	v_mfma_f32_16x16x32_bf16 v[58:61], v[226:229], v[38:41], v[194:197]
	s_nop 0
	global_load_dwordx4 v[6:9], v243, s[20:21]
	s_nop 0
	v_add_u32_e32 v2, 0x108000, v246
	global_load_dwordx4 v[2:5], v2, s[20:21]
	v_mfma_f32_16x16x32_bf16 v[54:57], v[230:233], v[38:41], v[198:201]
	v_mfma_f32_16x16x32_bf16 v[50:53], v[222:225], v[38:41], v[202:205]
	v_mfma_f32_16x16x32_bf16 v[46:49], v[234:237], v[34:37], v[206:209]
	v_mfma_f32_16x16x32_bf16 v[42:45], v[226:229], v[34:37], v[210:213]
	v_mfma_f32_16x16x32_bf16 v[38:41], v[230:233], v[34:37], v[214:217]
	v_mfma_f32_16x16x32_bf16 v[34:37], v[222:225], v[34:37], v[218:221]
	s_setprio 0
	s_add_i32 s26, s51, 1
	s_cmp_lg_u32 s26, 44
	s_cbranch_scc1 .LBB0_1326
	s_add_i32 s28, s28, s11
	s_cmp_gt_i32 s28, 31
	s_cbranch_scc1 .LBB0_1325
	s_ashr_i32 s3, s28, 31
	s_lshr_b32 s3, s3, 27
	s_add_i32 s3, s28, s3
	s_ashr_i32 s3, s3, 5
	s_mov_b32 s2, s10
	s_lshl_b32 s20, s3, 6
	s_lshl_b32 s21, s28, 1
	s_sub_i32 s20, s21, s20
	s_and_b32 s2, s2, 7
	s_and_b32 s20, s20, -8
	s_lshl_b32 s3, s3, 2
	s_and_b32 s21, s28, 3
	s_or_b32 s48, s3, s21
	s_or_b32 s49, s2, s20

.LBB0_1524:
	v_mov_b32_e32 v255, 0x8000
	v_bfe_u32 v1, v0, 1, 3
	v_lshlrev_b32_e32 v1, 8, v1
	v_add_u32_e32 v255, v255, v1
	v_bfe_u32 v1, v0, 6, 2
	v_mul_u32_u24_e32 v1, 0x1800, v1
	v_add_u32_e32 v255, v255, v1
	v_mov_b32_e32 v2, 0x0
	v_bfe_u32 v1, v0, 0, 1
	v_lshlrev_b32_e32 v1, 7, v1
	v_xor_b32_e32 v2, v2, v1
	v_bfe_u32 v1, v0, 1, 3
	v_lshlrev_b32_e32 v1, 4, v1
	v_xor_b32_e32 v2, v2, v1
	v_bfe_u32 v1, v0, 4, 2
	v_lshlrev_b32_e32 v1, 4, v1
	v_xor_b32_e32 v2, v2, v1
	v_bfe_u32 v1, v0, 6, 1
	v_lshlrev_b32_e32 v1, 7, v1
	v_xor_b32_e32 v2, v2, v1
	v_add_u32_e32 v255, v255, v2
	v_mov_b32_e32 v254, 0x8800
	v_bfe_u32 v1, v0, 1, 3
	v_lshlrev_b32_e32 v1, 8, v1
	v_add_u32_e32 v254, v254, v1
	v_bfe_u32 v1, v0, 6, 2
	v_mul_u32_u24_e32 v1, 0x1800, v1
	v_add_u32_e32 v254, v254, v1
	v_mov_b32_e32 v2, 0x80
	v_bfe_u32 v1, v0, 0, 1
	v_lshlrev_b32_e32 v1, 7, v1
	v_xor_b32_e32 v2, v2, v1
	v_bfe_u32 v1, v0, 1, 3
	v_lshlrev_b32_e32 v1, 4, v1
	v_xor_b32_e32 v2, v2, v1
	v_bfe_u32 v1, v0, 4, 2
	v_lshlrev_b32_e32 v1, 4, v1
	v_xor_b32_e32 v2, v2, v1
	v_bfe_u32 v1, v0, 6, 1
	v_lshlrev_b32_e32 v1, 7, v1
	v_xor_b32_e32 v2, v2, v1
	v_add_u32_e32 v254, v254, v2
	v_mov_b32_e32 v253, 0x0
	v_bfe_u32 v1, v0, 0, 1
	v_lshlrev_b32_e32 v1, 7, v1
	v_xor_b32_e32 v253, v253, v1
	v_bfe_u32 v1, v0, 1, 3
	v_mul_u32_u24_e32 v1, 0x110, v1
	v_xor_b32_e32 v253, v253, v1
	v_bfe_u32 v1, v0, 4, 2
	v_lshlrev_b32_e32 v1, 4, v1
	v_xor_b32_e32 v253, v253, v1
	v_bfe_u32 v1, v0, 8, 1
	v_lshlrev_b32_e32 v1, 14, v1
	v_xor_b32_e32 v253, v253, v1
	v_mov_b32_e32 v252, 0x880
	v_bfe_u32 v1, v0, 0, 1
	v_lshlrev_b32_e32 v1, 7, v1
	v_xor_b32_e32 v252, v252, v1
	v_bfe_u32 v1, v0, 1, 3
	v_mul_u32_u24_e32 v1, 0x110, v1
	v_xor_b32_e32 v252, v252, v1
	v_bfe_u32 v1, v0, 4, 2
	v_lshlrev_b32_e32 v1, 4, v1
	v_xor_b32_e32 v252, v252, v1
	v_bfe_u32 v1, v0, 8, 1
	v_lshlrev_b32_e32 v1, 14, v1
	v_xor_b32_e32 v252, v252, v1
	v_mov_b32_e32 v251, 0x0
	v_bfe_u32 v1, v0, 0, 4
	v_lshlrev_b32_e32 v1, 4, v1
	v_xor_b32_e32 v251, v251, v1
	v_bfe_u32 v1, v0, 4, 4
	v_mul_u32_u24_e32 v1, 0x110, v1
	v_xor_b32_e32 v251, v251, v1
	v_bfe_u32 v1, v0, 8, 1
	v_lshlrev_b32_e32 v1, 12, v1
	v_xor_b32_e32 v251, v251, v1
	v_mov_b32_e32 v250, 0x8800
	v_bfe_u32 v1, v0, 1, 3
	v_lshlrev_b32_e32 v1, 8, v1
	v_add_u32_e32 v250, v250, v1
	v_bfe_u32 v1, v0, 6, 2
	v_mul_u32_u24_e32 v1, 0x1800, v1
	v_add_u32_e32 v250, v250, v1
	v_mov_b32_e32 v2, 0xc0
	v_bfe_u32 v1, v0, 0, 1
	v_lshlrev_b32_e32 v1, 7, v1
	v_xor_b32_e32 v2, v2, v1
	v_bfe_u32 v1, v0, 1, 3
	v_lshlrev_b32_e32 v1, 4, v1
	v_xor_b32_e32 v2, v2, v1
	v_bfe_u32 v1, v0, 4, 2
	v_lshlrev_b32_e32 v1, 4, v1
	v_xor_b32_e32 v2, v2, v1
	v_bfe_u32 v1, v0, 6, 1
	v_lshlrev_b32_e32 v1, 7, v1
	v_xor_b32_e32 v2, v2, v1
	v_add_u32_e32 v250, v250, v2
	v_mov_b32_e32 v249, 0x8000
	v_bfe_u32 v1, v0, 1, 3
	v_lshlrev_b32_e32 v1, 8, v1
	v_add_u32_e32 v249, v249, v1
	v_bfe_u32 v1, v0, 6, 2
	v_mul_u32_u24_e32 v1, 0x1800, v1
	v_add_u32_e32 v249, v249, v1
	v_mov_b32_e32 v2, 0x40
	v_bfe_u32 v1, v0, 0, 1
	v_lshlrev_b32_e32 v1, 7, v1
	v_xor_b32_e32 v2, v2, v1
	v_bfe_u32 v1, v0, 1, 3
	v_lshlrev_b32_e32 v1, 4, v1
	v_xor_b32_e32 v2, v2, v1
	v_bfe_u32 v1, v0, 4, 2
	v_lshlrev_b32_e32 v1, 4, v1
	v_xor_b32_e32 v2, v2, v1
	v_bfe_u32 v1, v0, 6, 1
	v_lshlrev_b32_e32 v1, 7, v1
	v_xor_b32_e32 v2, v2, v1
	v_add_u32_e32 v249, v249, v2
	v_mov_b32_e32 v248, 0x8c0
	v_bfe_u32 v1, v0, 0, 1
	v_lshlrev_b32_e32 v1, 7, v1
	v_xor_b32_e32 v248, v248, v1
	v_bfe_u32 v1, v0, 1, 3
	v_mul_u32_u24_e32 v1, 0x110, v1
	v_xor_b32_e32 v248, v248, v1
	v_bfe_u32 v1, v0, 4, 2
	v_lshlrev_b32_e32 v1, 4, v1
	v_xor_b32_e32 v248, v248, v1
	v_bfe_u32 v1, v0, 8, 1
	v_lshlrev_b32_e32 v1, 14, v1
	v_xor_b32_e32 v248, v248, v1
	v_mov_b32_e32 v247, 0x40
	v_bfe_u32 v1, v0, 0, 1
	v_lshlrev_b32_e32 v1, 7, v1
	v_xor_b32_e32 v247, v247, v1
	v_bfe_u32 v1, v0, 1, 3
	v_mul_u32_u24_e32 v1, 0x110, v1
	v_xor_b32_e32 v247, v247, v1
	v_bfe_u32 v1, v0, 4, 2
	v_lshlrev_b32_e32 v1, 4, v1
	v_xor_b32_e32 v247, v247, v1
	v_bfe_u32 v1, v0, 8, 1
	v_lshlrev_b32_e32 v1, 14, v1
	v_xor_b32_e32 v247, v247, v1
	v_mov_b32_e32 v246, 0x0
	v_bfe_u32 v1, v0, 0, 3
	v_lshlrev_b32_e32 v1, 4, v1
	v_add_u32_e32 v246, v246, v1
	v_bfe_u32 v1, v0, 3, 6
	v_lshlrev_b32_e32 v1, 11, v1
	v_add_u32_e32 v246, v246, v1
	v_mov_b32_e32 v245, 0x10000
	v_bfe_u32 v1, v0, 0, 4
	v_lshlrev_b32_e32 v1, 4, v1
	v_xor_b32_e32 v245, v245, v1
	v_bfe_u32 v1, v0, 4, 4
	v_mul_u32_u24_e32 v1, 0x110, v1
	v_xor_b32_e32 v245, v245, v1
	v_bfe_u32 v1, v0, 8, 1
	v_lshlrev_b32_e32 v1, 12, v1
	v_xor_b32_e32 v245, v245, v1
	v_mov_b32_e32 v244, 0x20000
	v_bfe_u32 v1, v0, 0, 3
	v_lshlrev_b32_e32 v1, 4, v1
	v_add_u32_e32 v244, v244, v1
	v_bfe_u32 v1, v0, 3, 6
	v_lshlrev_b32_e32 v1, 11, v1
	v_add_u32_e32 v244, v244, v1
	v_mov_b32_e32 v243, 0x40000
	v_bfe_u32 v1, v0, 0, 3
	v_lshlrev_b32_e32 v1, 4, v1
	v_add_u32_e32 v243, v243, v1
	v_bfe_u32 v1, v0, 3, 6
	v_lshlrev_b32_e32 v1, 11, v1
	v_add_u32_e32 v243, v243, v1
	v_mov_b32_e32 v242, 0x18000
	v_bfe_u32 v1, v0, 1, 3
	v_lshlrev_b32_e32 v1, 8, v1
	v_add_u32_e32 v242, v242, v1
	v_bfe_u32 v1, v0, 6, 2
	v_mul_u32_u24_e32 v1, 0x1800, v1
	v_add_u32_e32 v242, v242, v1
	v_mov_b32_e32 v2, 0x0
	v_bfe_u32 v1, v0, 0, 1
	v_lshlrev_b32_e32 v1, 7, v1
	v_xor_b32_e32 v2, v2, v1
	v_bfe_u32 v1, v0, 1, 3
	v_lshlrev_b32_e32 v1, 4, v1
	v_xor_b32_e32 v2, v2, v1
	v_bfe_u32 v1, v0, 4, 2
	v_lshlrev_b32_e32 v1, 4, v1
	v_xor_b32_e32 v2, v2, v1
	v_bfe_u32 v1, v0, 6, 1
	v_lshlrev_b32_e32 v1, 7, v1
	v_xor_b32_e32 v2, v2, v1
	v_add_u32_e32 v242, v242, v2
	v_mov_b32_e32 v241, 0x18000
	v_bfe_u32 v1, v0, 1, 3
	v_lshlrev_b32_e32 v1, 8, v1
	v_add_u32_e32 v241, v241, v1
	v_bfe_u32 v1, v0, 6, 2
	v_mul_u32_u24_e32 v1, 0x1800, v1
	v_add_u32_e32 v241, v241, v1
	v_mov_b32_e32 v2, 0x40
	v_bfe_u32 v1, v0, 0, 1
	v_lshlrev_b32_e32 v1, 7, v1
	v_xor_b32_e32 v2, v2, v1
	v_bfe_u32 v1, v0, 1, 3
	v_lshlrev_b32_e32 v1, 4, v1
	v_xor_b32_e32 v2, v2, v1
	v_bfe_u32 v1, v0, 4, 2
	v_lshlrev_b32_e32 v1, 4, v1
	v_xor_b32_e32 v2, v2, v1
	v_bfe_u32 v1, v0, 6, 1
	v_lshlrev_b32_e32 v1, 7, v1
	v_xor_b32_e32 v2, v2, v1
	v_add_u32_e32 v241, v241, v2
	v_mov_b32_e32 v240, 0x10040
	v_bfe_u32 v1, v0, 0, 1
	v_lshlrev_b32_e32 v1, 7, v1
	v_xor_b32_e32 v240, v240, v1
	v_bfe_u32 v1, v0, 1, 3
	v_mul_u32_u24_e32 v1, 0x110, v1
	v_xor_b32_e32 v240, v240, v1
	v_bfe_u32 v1, v0, 4, 2
	v_lshlrev_b32_e32 v1, 4, v1
	v_xor_b32_e32 v240, v240, v1
	v_bfe_u32 v1, v0, 8, 1
	v_lshlrev_b32_e32 v1, 14, v1
	v_xor_b32_e32 v240, v240, v1
	v_mov_b32_e32 v239, 0x60000
	v_bfe_u32 v1, v0, 0, 3
	v_lshlrev_b32_e32 v1, 4, v1
	v_add_u32_e32 v239, v239, v1
	v_bfe_u32 v1, v0, 3, 6
	v_lshlrev_b32_e32 v1, 11, v1
	v_add_u32_e32 v239, v239, v1
	v_mov_b32_e32 v238, 0x18800
	v_bfe_u32 v1, v0, 1, 3
	v_lshlrev_b32_e32 v1, 8, v1
	v_add_u32_e32 v238, v238, v1
	v_bfe_u32 v1, v0, 6, 2
	v_mul_u32_u24_e32 v1, 0x1800, v1
	v_add_u32_e32 v238, v238, v1
	v_mov_b32_e32 v2, 0x80
	v_bfe_u32 v1, v0, 0, 1
	v_lshlrev_b32_e32 v1, 7, v1
	v_xor_b32_e32 v2, v2, v1
	v_bfe_u32 v1, v0, 1, 3
	v_lshlrev_b32_e32 v1, 4, v1
	v_xor_b32_e32 v2, v2, v1
	v_bfe_u32 v1, v0, 4, 2
	v_lshlrev_b32_e32 v1, 4, v1
	v_xor_b32_e32 v2, v2, v1
	v_bfe_u32 v1, v0, 6, 1
	v_lshlrev_b32_e32 v1, 7, v1
	v_xor_b32_e32 v2, v2, v1
	v_add_u32_e32 v238, v238, v2
	v_mov_b32_e32 v237, 0x10000
	v_bfe_u32 v1, v0, 0, 1
	v_lshlrev_b32_e32 v1, 7, v1
	v_xor_b32_e32 v237, v237, v1
	v_bfe_u32 v1, v0, 1, 3
	v_mul_u32_u24_e32 v1, 0x110, v1
	v_xor_b32_e32 v237, v237, v1
	v_bfe_u32 v1, v0, 4, 2
	v_lshlrev_b32_e32 v1, 4, v1
	v_xor_b32_e32 v237, v237, v1
	v_bfe_u32 v1, v0, 8, 1
	v_lshlrev_b32_e32 v1, 14, v1
	v_xor_b32_e32 v237, v237, v1
	v_mov_b32_e32 v236, 0x10880
	v_bfe_u32 v1, v0, 0, 1
	v_lshlrev_b32_e32 v1, 7, v1
	v_xor_b32_e32 v236, v236, v1
	v_bfe_u32 v1, v0, 1, 3
	v_mul_u32_u24_e32 v1, 0x110, v1
	v_xor_b32_e32 v236, v236, v1
	v_bfe_u32 v1, v0, 4, 2
	v_lshlrev_b32_e32 v1, 4, v1
	v_xor_b32_e32 v236, v236, v1
	v_bfe_u32 v1, v0, 8, 1
	v_lshlrev_b32_e32 v1, 14, v1
	v_xor_b32_e32 v236, v236, v1
	v_mov_b32_e32 v235, 0x18800
	v_bfe_u32 v1, v0, 1, 3
	v_lshlrev_b32_e32 v1, 8, v1
	v_add_u32_e32 v235, v235, v1
	v_bfe_u32 v1, v0, 6, 2
	v_mul_u32_u24_e32 v1, 0x1800, v1
	v_add_u32_e32 v235, v235, v1
	v_mov_b32_e32 v2, 0xc0
	v_bfe_u32 v1, v0, 0, 1
	v_lshlrev_b32_e32 v1, 7, v1
	v_xor_b32_e32 v2, v2, v1
	v_bfe_u32 v1, v0, 1, 3
	v_lshlrev_b32_e32 v1, 4, v1
	v_xor_b32_e32 v2, v2, v1
	v_bfe_u32 v1, v0, 4, 2
	v_lshlrev_b32_e32 v1, 4, v1
	v_xor_b32_e32 v2, v2, v1
	v_bfe_u32 v1, v0, 6, 1
	v_lshlrev_b32_e32 v1, 7, v1
	v_xor_b32_e32 v2, v2, v1
	v_add_u32_e32 v235, v235, v2
	v_mov_b32_e32 v234, 0x108c0
	v_bfe_u32 v1, v0, 0, 1
	v_lshlrev_b32_e32 v1, 7, v1
	v_xor_b32_e32 v234, v234, v1
	v_bfe_u32 v1, v0, 1, 3
	v_mul_u32_u24_e32 v1, 0x110, v1
	v_xor_b32_e32 v234, v234, v1
	v_bfe_u32 v1, v0, 4, 2
	v_lshlrev_b32_e32 v1, 4, v1
	v_xor_b32_e32 v234, v234, v1
	v_bfe_u32 v1, v0, 8, 1
	v_lshlrev_b32_e32 v1, 14, v1
	v_xor_b32_e32 v234, v234, v1
	v_mov_b32_e32 v1, v0
	s_load_dword s2, s[0:1], 0xe0
	s_mov_b32 s3, s10
	v_mov_b32_e32 v1, v0
	s_waitcnt lgkmcnt(0)
	s_lshr_b32 s11, s2, 3
	s_waitcnt vmcnt(0)
	v_cvt_f32_u32_e32 v2, s11
	s_mov_b32 s2, s10
	s_ashr_i32 s3, s2, 3
	v_rcp_iflag_f32_e32 v2, v2
	s_ashr_i32 s4, s2, 31
	s_sub_i32 s2, 0, s11
	s_abs_i32 s3, s3
	v_mul_f32_e32 v1, 0x4f7ffffe, v2
	v_cvt_u32_f32_e32 v1, v1
	s_mov_b32 s45, 0
	v_readfirstlane_b32 s5, v1
	s_mul_i32 s2, s2, s5
	s_mul_hi_u32 s2, s5, s2
	s_add_i32 s2, s5, s2
	s_mul_hi_u32 s5, s3, s2
	s_mul_i32 s5, s5, s11
	s_sub_i32 s3, s3, s5
	s_sub_i32 s5, s3, s11
	s_cmp_ge_u32 s3, s11
	s_cselect_b32 s3, s5, s3
	s_sub_i32 s5, s3, s11
	s_cmp_ge_u32 s3, s11
	s_cselect_b32 s3, s5, s3
	s_xor_b32 s3, s3, s4
	s_sub_i32 s24, s3, s4
	s_mov_b32 s3, s10
	s_cmpk_gt_i32 s24, 0x5f
	s_cbranch_scc1 .LBB0_1604
	s_load_dwordx2 s[4:5], s[16:17], 0xd0
	s_mov_b32 s3, s10
	v_mov_b32_e32 v54, 0
	v_mov_b32_e32 v1, v0
	s_waitcnt lgkmcnt(0)
	s_add_u32 s25, s4, 0x17f0000
	s_addc_u32 s26, s5, 0
	s_add_u32 s8, s4, 0x37f0000
	s_addc_u32 s9, s5, 0
	s_add_u32 s27, s4, 0x50000
	s_addc_u32 s28, s5, 0
	s_ashr_i32 s4, s24, 31
	s_lshr_b32 s4, s4, 27
	s_add_i32 s4, s24, s4
	s_ashr_i32 s4, s4, 5
	s_lshl_b32 s5, s24, 1
	s_lshl_b32 s12, s4, 6
	s_sub_i32 s5, s5, s12
	s_lshl_b32 s4, s4, 2
	s_and_b32 s12, s24, 3
	s_or_b32 s29, s4, s12
	s_sub_i32 s4, s11, s24
	s_addk_i32 s4, 0x5f
	s_mul_hi_u32 s2, s4, s2
	s_mul_i32 s12, s2, s11
	s_sub_i32 s4, s4, s12
	s_add_i32 s12, s2, 1
	s_sub_i32 s13, s4, s11
	s_cmp_ge_u32 s4, s11
	s_cselect_b32 s2, s12, s2
	s_cselect_b32 s4, s13, s4
	s_add_i32 s12, s2, 1
	s_cmp_ge_u32 s4, s11
	s_cselect_b32 s2, s12, s2
	s_and_b32 s3, s3, 7
	s_and_b32 s4, s5, -8
	s_lshl_b32 s30, s2, 4
	s_mul_i32 s2, s29, 0xc0
	s_or_b32 s31, s3, s4
	s_ashr_i32 s3, s2, 31
	s_lshl_b64 s[2:3], s[2:3], 11
	v_lshlrev_b32_e32 v2, 8, v1
	v_lshlrev_b32_e32 v1, 4, v1
	s_add_u32 s2, s27, s2
	v_and_b32_e32 v1, 0x70, v1
	s_movk_i32 s33, 0xf800
	v_mov_b32_e32 v175, 0
	s_addc_u32 s3, s28, s3
	v_and_or_b32 v174, v2, s33, v1
	s_lshl_b32 s4, s31, 8
	v_lshl_add_u64 v[2:3], s[2:3], 0, v[174:175]
	s_mov_b32 s12, 0x40000
	s_ashr_i32 s5, s4, 31
	v_add_co_u32_e32 v14, vcc, s12, v2
	s_lshl_b64 s[4:5], s[4:5], 11
	s_nop 0
	v_addc_co_u32_e32 v15, vcc, 0, v3, vcc
	s_mov_b32 s34, 0x20000
	s_add_u32 s4, s25, s4
	v_add_co_u32_e32 v16, vcc, s34, v2
	s_addc_u32 s5, s26, s5
	s_nop 0
	v_addc_co_u32_e32 v17, vcc, 0, v3, vcc
	global_load_dwordx4 v[2:5], v[14:15], off
	global_load_dwordx4 v[6:9], v[16:17], off
	global_load_dwordx4 v[10:13], v174, s[2:3]
	v_lshl_add_u64 v[14:15], s[4:5], 0, v[174:175]
	s_mov_b32 s13, 0x60000
	v_add_co_u32_e32 v30, vcc, s13, v14
	v_mov_b32_e32 v1, v0
	s_nop 0
	v_addc_co_u32_e32 v31, vcc, 0, v15, vcc
	v_add_co_u32_e32 v32, vcc, s12, v14
	s_movk_i32 s36, 0xf0
	s_nop 0
	v_addc_co_u32_e32 v33, vcc, 0, v15, vcc
	v_add_co_u32_e32 v34, vcc, s34, v14
	s_mov_b32 s35, 2
	s_nop 0
	v_addc_co_u32_e32 v35, vcc, 0, v15, vcc
	global_load_dwordx4 v[14:17], v174, s[4:5]
	global_load_dwordx4 v[18:21], v[34:35], off
	global_load_dwordx4 v[22:25], v[32:33], off
	global_load_dwordx4 v[26:29], v[30:31], off
	v_mov_b32_e32 v30, v0
	v_ashrrev_i32_e32 v31, 4, v1
	v_xor_b32_e32 v1, v31, v1
	v_lshlrev_b32_e32 v31, 8, v31
	v_lshlrev_b32_e32 v1, 4, v1
	v_and_or_b32 v1, v1, s36, v31
	s_movk_i32 s37, 0xff80
	s_mov_b32 s38, 0x10000
	s_mov_b32 s39, 0x18000
	s_movk_i32 s40, 0x8a0
	s_movk_i32 s41, 0x1140
	v_mov_b32_e32 v176, 0x18000
	s_mov_b32 s22, 2
	s_mov_b32 s42, s24
	s_mov_b32 s43, s29
	s_mov_b32 s44, s31
	v_mov_b32_e32 v55, v54
	v_mov_b32_e32 v56, v54
	v_mov_b32_e32 v57, v54
	v_mov_b32_e32 v82, v54
	v_mov_b32_e32 v83, v54
	v_mov_b32_e32 v84, v54
	v_mov_b32_e32 v85, v54
	v_mov_b32_e32 v86, v54
	v_mov_b32_e32 v87, v54
	v_mov_b32_e32 v88, v54
	v_mov_b32_e32 v89, v54
	v_mov_b32_e32 v90, v54
	v_mov_b32_e32 v91, v54
	v_mov_b32_e32 v92, v54
	v_mov_b32_e32 v93, v54
	v_mov_b32_e32 v94, v54
	v_mov_b32_e32 v95, v54
	v_mov_b32_e32 v96, v54
	v_mov_b32_e32 v97, v54
	s_waitcnt vmcnt(4)
	ds_write_b128 v1, v[10:13] offset:32768
	ds_write_b128 v1, v[6:9] offset:40960
	ds_write_b128 v1, v[2:5] offset:49152
	s_waitcnt vmcnt(3)
	ds_write_b128 v1, v[14:17]
	s_waitcnt vmcnt(2)
	ds_write_b128 v1, v[18:21] offset:8192
	s_waitcnt vmcnt(1)
	ds_write_b128 v1, v[22:25] offset:16384
	s_waitcnt vmcnt(0)
	ds_write_b128 v1, v[26:29] offset:24576
	v_mov_b32_e32 v98, v54
	v_lshlrev_b32_e32 v2, 4, v30
	v_lshlrev_b32_e32 v1, 8, v30
	v_and_b32_e32 v2, 0x70, v2
	v_and_or_b32 v174, v1, s33, v2
	v_lshl_add_u64 v[2:3], s[2:3], 0, v[174:175]
	v_add_co_u32_e32 v10, vcc, s12, v2
	v_mov_b32_e32 v1, 0x10000
	s_nop 0
	v_addc_co_u32_e32 v11, vcc, 0, v3, vcc
	v_add_co_u32_e32 v12, vcc, s34, v2
	v_mov_b32_e32 v99, v54
	s_nop 0
	v_addc_co_u32_e32 v13, vcc, 0, v3, vcc
	global_load_dwordx4 v[2:5], v[10:11], off offset:128
	global_load_dwordx4 v[6:9], v[12:13], off offset:128
	v_lshl_add_u64 v[10:11], s[4:5], 0, v[174:175]
	v_add_co_u32_e32 v12, vcc, s13, v10
	v_mov_b32_e32 v100, v54
	s_nop 0
	v_addc_co_u32_e32 v13, vcc, 0, v11, vcc
	v_add_co_u32_e32 v22, vcc, s12, v10
	v_mov_b32_e32 v101, v54
	s_nop 0
	v_addc_co_u32_e32 v23, vcc, 0, v11, vcc
	v_add_co_u32_e32 v30, vcc, s34, v10
	global_load_dwordx4 v[14:17], v[12:13], off offset:128
	global_load_dwordx4 v[18:21], v[22:23], off offset:128
	v_addc_co_u32_e32 v31, vcc, 0, v11, vcc
	global_load_dwordx4 v[10:13], v174, s[2:3] offset:128
	global_load_dwordx4 v[22:25], v[30:31], off offset:128
	global_load_dwordx4 v[26:29], v174, s[4:5] offset:128
	v_mov_b32_e32 v102, v54
	v_mov_b32_e32 v103, v54
	v_mov_b32_e32 v104, v54
	v_mov_b32_e32 v105, v54
	v_mov_b32_e32 v106, v54
	v_mov_b32_e32 v107, v54
	v_mov_b32_e32 v108, v54
	v_mov_b32_e32 v109, v54
	v_mov_b32_e32 v110, v54
	v_mov_b32_e32 v111, v54
	v_mov_b32_e32 v112, v54
	v_mov_b32_e32 v113, v54
	v_mov_b32_e32 v114, v54
	v_mov_b32_e32 v115, v54
	v_mov_b32_e32 v116, v54
	v_mov_b32_e32 v117, v54
	v_mov_b32_e32 v118, v54
	v_mov_b32_e32 v119, v54
	v_mov_b32_e32 v120, v54
	v_mov_b32_e32 v121, v54
	v_mov_b32_e32 v122, v54
	v_mov_b32_e32 v123, v54
	v_mov_b32_e32 v124, v54
	v_mov_b32_e32 v125, v54
	v_mov_b32_e32 v78, v54
	v_mov_b32_e32 v79, v54
	v_mov_b32_e32 v80, v54
	v_mov_b32_e32 v81, v54
	v_mov_b32_e32 v74, v54
	v_mov_b32_e32 v75, v54
	v_mov_b32_e32 v76, v54
	v_mov_b32_e32 v77, v54
	v_mov_b32_e32 v70, v54
	v_mov_b32_e32 v71, v54
	v_mov_b32_e32 v72, v54
	v_mov_b32_e32 v73, v54
	v_mov_b32_e32 v66, v54
	v_mov_b32_e32 v67, v54
	v_mov_b32_e32 v68, v54
	v_mov_b32_e32 v69, v54
	v_mov_b32_e32 v62, v54
	v_mov_b32_e32 v63, v54
	v_mov_b32_e32 v64, v54
	v_mov_b32_e32 v65, v54
	v_mov_b32_e32 v58, v54
	v_mov_b32_e32 v59, v54
	v_mov_b32_e32 v60, v54
	v_mov_b32_e32 v61, v54
	v_mov_b32_e32 v50, v54
	v_mov_b32_e32 v51, v54
	v_mov_b32_e32 v52, v54
	v_mov_b32_e32 v53, v54
	v_mov_b32_e32 v46, v54
	v_mov_b32_e32 v47, v54
	v_mov_b32_e32 v48, v54
	v_mov_b32_e32 v49, v54
	v_mov_b32_e32 v42, v54
	v_mov_b32_e32 v43, v54
	v_mov_b32_e32 v44, v54
	v_mov_b32_e32 v45, v54
	v_mov_b32_e32 v38, v54
	v_mov_b32_e32 v39, v54
	v_mov_b32_e32 v40, v54
	v_mov_b32_e32 v41, v54
	v_mov_b32_e32 v34, v54
	v_mov_b32_e32 v35, v54
	v_mov_b32_e32 v36, v54
	v_mov_b32_e32 v37, v54
	v_mov_b32_e32 v30, v54
	v_mov_b32_e32 v31, v54
	v_mov_b32_e32 v32, v54
	v_mov_b32_e32 v33, v54
	s_waitcnt lgkmcnt(0)
	s_barrier
	s_branch .LBB0_1528

.LBB0_2199:
	v_mov_b32_e32 v255, 0x8000
	v_bfe_u32 v1, v0, 0, 1
	v_lshlrev_b32_e32 v1, 7, v1
	v_xor_b32_e32 v255, v255, v1
	v_bfe_u32 v1, v0, 1, 3
	v_mul_u32_u24_e32 v1, 0x110, v1
	v_xor_b32_e32 v255, v255, v1
	v_bfe_u32 v1, v0, 4, 2
	v_lshlrev_b32_e32 v1, 4, v1
	v_xor_b32_e32 v255, v255, v1
	v_bfe_u32 v1, v0, 6, 2
	v_lshlrev_b32_e32 v1, 13, v1
	v_xor_b32_e32 v255, v255, v1
	v_mov_b32_e32 v254, 0x8880
	v_bfe_u32 v1, v0, 0, 1
	v_lshlrev_b32_e32 v1, 7, v1
	v_xor_b32_e32 v254, v254, v1
	v_bfe_u32 v1, v0, 1, 3
	v_mul_u32_u24_e32 v1, 0x110, v1
	v_xor_b32_e32 v254, v254, v1
	v_bfe_u32 v1, v0, 4, 2
	v_lshlrev_b32_e32 v1, 4, v1
	v_xor_b32_e32 v254, v254, v1
	v_bfe_u32 v1, v0, 6, 2
	v_lshlrev_b32_e32 v1, 13, v1
	v_xor_b32_e32 v254, v254, v1
	v_mov_b32_e32 v253, 0x880
	v_bfe_u32 v1, v0, 0, 1
	v_lshlrev_b32_e32 v1, 7, v1
	v_xor_b32_e32 v253, v253, v1
	v_bfe_u32 v1, v0, 1, 3
	v_mul_u32_u24_e32 v1, 0x110, v1
	v_xor_b32_e32 v253, v253, v1
	v_bfe_u32 v1, v0, 4, 2
	v_lshlrev_b32_e32 v1, 4, v1
	v_xor_b32_e32 v253, v253, v1
	v_bfe_u32 v1, v0, 8, 1
	v_lshlrev_b32_e32 v1, 14, v1
	v_xor_b32_e32 v253, v253, v1
	v_mov_b32_e32 v252, 0x0
	v_bfe_u32 v1, v0, 0, 1
	v_lshlrev_b32_e32 v1, 7, v1
	v_xor_b32_e32 v252, v252, v1
	v_bfe_u32 v1, v0, 1, 3
	v_mul_u32_u24_e32 v1, 0x110, v1
	v_xor_b32_e32 v252, v252, v1
	v_bfe_u32 v1, v0, 4, 2
	v_lshlrev_b32_e32 v1, 4, v1
	v_xor_b32_e32 v252, v252, v1
	v_bfe_u32 v1, v0, 8, 1
	v_lshlrev_b32_e32 v1, 14, v1
	v_xor_b32_e32 v252, v252, v1
	v_mov_b32_e32 v251, 0x0
	v_bfe_u32 v1, v0, 0, 4
	v_lshlrev_b32_e32 v1, 4, v1
	v_xor_b32_e32 v251, v251, v1
	v_bfe_u32 v1, v0, 4, 4
	v_mul_u32_u24_e32 v1, 0x110, v1
	v_xor_b32_e32 v251, v251, v1
	v_bfe_u32 v1, v0, 8, 1
	v_lshlrev_b32_e32 v1, 12, v1
	v_xor_b32_e32 v251, v251, v1
	v_mov_b32_e32 v250, 0x88c0
	v_bfe_u32 v1, v0, 0, 1
	v_lshlrev_b32_e32 v1, 7, v1
	v_xor_b32_e32 v250, v250, v1
	v_bfe_u32 v1, v0, 1, 3
	v_mul_u32_u24_e32 v1, 0x110, v1
	v_xor_b32_e32 v250, v250, v1
	v_bfe_u32 v1, v0, 4, 2
	v_lshlrev_b32_e32 v1, 4, v1
	v_xor_b32_e32 v250, v250, v1
	v_bfe_u32 v1, v0, 6, 2
	v_lshlrev_b32_e32 v1, 13, v1
	v_xor_b32_e32 v250, v250, v1
	v_mov_b32_e32 v249, 0x8040
	v_bfe_u32 v1, v0, 0, 1
	v_lshlrev_b32_e32 v1, 7, v1
	v_xor_b32_e32 v249, v249, v1
	v_bfe_u32 v1, v0, 1, 3
	v_mul_u32_u24_e32 v1, 0x110, v1
	v_xor_b32_e32 v249, v249, v1
	v_bfe_u32 v1, v0, 4, 2
	v_lshlrev_b32_e32 v1, 4, v1
	v_xor_b32_e32 v249, v249, v1
	v_bfe_u32 v1, v0, 6, 2
	v_lshlrev_b32_e32 v1, 13, v1
	v_xor_b32_e32 v249, v249, v1
	v_mov_b32_e32 v248, 0x8c0
	v_bfe_u32 v1, v0, 0, 1
	v_lshlrev_b32_e32 v1, 7, v1
	v_xor_b32_e32 v248, v248, v1
	v_bfe_u32 v1, v0, 1, 3
	v_mul_u32_u24_e32 v1, 0x110, v1
	v_xor_b32_e32 v248, v248, v1
	v_bfe_u32 v1, v0, 4, 2
	v_lshlrev_b32_e32 v1, 4, v1
	v_xor_b32_e32 v248, v248, v1
	v_bfe_u32 v1, v0, 8, 1
	v_lshlrev_b32_e32 v1, 14, v1
	v_xor_b32_e32 v248, v248, v1
	v_mov_b32_e32 v247, 0x40
	v_bfe_u32 v1, v0, 0, 1
	v_lshlrev_b32_e32 v1, 7, v1
	v_xor_b32_e32 v247, v247, v1
	v_bfe_u32 v1, v0, 1, 3
	v_mul_u32_u24_e32 v1, 0x110, v1
	v_xor_b32_e32 v247, v247, v1
	v_bfe_u32 v1, v0, 4, 2
	v_lshlrev_b32_e32 v1, 4, v1
	v_xor_b32_e32 v247, v247, v1
	v_bfe_u32 v1, v0, 8, 1
	v_lshlrev_b32_e32 v1, 14, v1
	v_xor_b32_e32 v247, v247, v1
	v_mov_b32_e32 v246, 0x0
	v_bfe_u32 v1, v0, 0, 3
	v_lshlrev_b32_e32 v1, 4, v1
	v_add_u32_e32 v246, v246, v1
	v_bfe_u32 v1, v0, 3, 6
	v_lshlrev_b32_e32 v1, 11, v1
	v_add_u32_e32 v246, v246, v1
	v_mov_b32_e32 v245, 0x10000
	v_bfe_u32 v1, v0, 0, 4
	v_lshlrev_b32_e32 v1, 4, v1
	v_xor_b32_e32 v245, v245, v1
	v_bfe_u32 v1, v0, 4, 4
	v_mul_u32_u24_e32 v1, 0x110, v1
	v_xor_b32_e32 v245, v245, v1
	v_bfe_u32 v1, v0, 8, 1
	v_lshlrev_b32_e32 v1, 12, v1
	v_xor_b32_e32 v245, v245, v1
	v_mov_b32_e32 v244, 0x20000
	v_bfe_u32 v1, v0, 0, 3
	v_lshlrev_b32_e32 v1, 4, v1
	v_add_u32_e32 v244, v244, v1
	v_bfe_u32 v1, v0, 3, 6
	v_lshlrev_b32_e32 v1, 11, v1
	v_add_u32_e32 v244, v244, v1
	v_mov_b32_e32 v243, 0x40000
	v_bfe_u32 v1, v0, 0, 3
	v_lshlrev_b32_e32 v1, 4, v1
	v_add_u32_e32 v243, v243, v1
	v_bfe_u32 v1, v0, 3, 6
	v_lshlrev_b32_e32 v1, 11, v1
	v_add_u32_e32 v243, v243, v1
	v_mov_b32_e32 v1, v0
	s_load_dword s2, s[0:1], 0xe0
	s_mov_b32 s3, s10
	v_mov_b32_e32 v1, v0
	s_waitcnt lgkmcnt(0)
	s_lshr_b32 s11, s2, 3
	s_waitcnt vmcnt(0)
	v_cvt_f32_u32_e32 v2, s11
	s_mov_b32 s2, s10
	s_ashr_i32 s3, s2, 3
	v_rcp_iflag_f32_e32 v2, v2
	s_ashr_i32 s4, s2, 31
	s_sub_i32 s2, 0, s11
	s_abs_i32 s3, s3
	v_mul_f32_e32 v1, 0x4f7ffffe, v2
	v_cvt_u32_f32_e32 v1, v1
	s_mov_b32 s50, 0
	v_readfirstlane_b32 s5, v1
	s_mul_i32 s2, s2, s5
	s_mul_hi_u32 s2, s5, s2
	s_add_i32 s2, s5, s2
	s_mul_hi_u32 s5, s3, s2
	s_mul_i32 s5, s5, s11
	s_sub_i32 s3, s3, s5
	s_sub_i32 s5, s3, s11
	s_cmp_ge_u32 s3, s11
	s_cselect_b32 s3, s5, s3
	s_sub_i32 s5, s3, s11
	s_cmp_ge_u32 s3, s11
	s_cselect_b32 s3, s5, s3
	s_xor_b32 s3, s3, s4
	s_sub_i32 s28, s3, s4
	s_mov_b32 s3, s10
	s_cmp_gt_i32 s28, 31
	s_cbranch_scc1 .LBB0_2263
	s_load_dwordx4 s[4:7], s[16:17], 0xc8
	s_mov_b32 s3, s10
	v_mov_b32_e32 v82, 0
	v_mov_b32_e32 v1, v0
	s_waitcnt lgkmcnt(0)
	s_add_u32 s29, s6, 0x17f0000
	s_addc_u32 s30, s7, 0
	s_add_u32 s12, s4, 0x2000000
	s_addc_u32 s13, s5, 0
	s_add_u32 s14, s6, 0x24000
	s_addc_u32 s15, s7, 0
	s_add_u32 s31, s6, 0x570000
	s_addc_u32 s33, s7, 0
	s_ashr_i32 s6, s28, 31
	s_lshr_b32 s6, s6, 27
	s_add_i32 s6, s28, s6
	s_ashr_i32 s6, s6, 5
	s_lshl_b32 s7, s28, 1
	s_lshl_b32 s20, s6, 6
	s_sub_i32 s7, s7, s20
	s_lshl_b32 s6, s6, 2
	s_and_b32 s20, s28, 3
	s_or_b32 s34, s6, s20
	s_sub_i32 s6, s11, s28
	s_add_i32 s6, s6, 31
	s_mul_hi_u32 s2, s6, s2
	s_mul_i32 s20, s2, s11
	s_sub_i32 s6, s6, s20
	s_add_i32 s20, s2, 1
	s_sub_i32 s21, s6, s11
	s_cmp_ge_u32 s6, s11
	s_cselect_b32 s2, s20, s2
	s_cselect_b32 s6, s21, s6
	s_add_i32 s20, s2, 1
	s_cmp_ge_u32 s6, s11
	s_cselect_b32 s2, s20, s2
	s_and_b32 s3, s3, 7
	s_and_b32 s6, s7, -8
	s_lshl_b32 s35, s2, 4
	s_lshl_b32 s2, s34, 8
	s_or_b32 s36, s3, s6
	s_ashr_i32 s3, s2, 31
	s_lshl_b64 s[2:3], s[2:3], 11
	v_lshlrev_b32_e32 v2, 8, v1
	v_lshlrev_b32_e32 v1, 4, v1
	s_add_u32 s2, s31, s2
	v_and_b32_e32 v1, 0x70, v1
	s_movk_i32 s37, 0xf800
	v_mov_b32_e32 v239, 0
	s_addc_u32 s3, s33, s3
	v_and_or_b32 v238, v2, s37, v1
	v_lshl_add_u64 v[10:11], s[2:3], 0, v[238:239]
	s_mov_b32 s38, 0x60000
	v_add_co_u32_e32 v12, vcc, s38, v10
	s_lshl_b32 s6, s36, 8
	s_nop 0
	v_addc_co_u32_e32 v13, vcc, 0, v11, vcc
	s_mov_b32 s20, 0x40000
	s_ashr_i32 s7, s6, 31
	v_add_co_u32_e32 v14, vcc, s20, v10
	s_lshl_b64 s[6:7], s[6:7], 11
	s_nop 0
	v_addc_co_u32_e32 v15, vcc, 0, v11, vcc
	s_mov_b32 s39, 0x20000
	s_add_u32 s6, s29, s6
	v_add_co_u32_e32 v18, vcc, s39, v10
	s_addc_u32 s7, s30, s7
	s_nop 0
	v_addc_co_u32_e32 v19, vcc, 0, v11, vcc
	v_lshl_add_u64 v[30:31], s[6:7], 0, v[238:239]
	v_add_co_u32_e32 v32, vcc, s20, v30
	global_load_dwordx4 v[2:5], v[12:13], off
	global_load_dwordx4 v[6:9], v[14:15], off
	v_addc_co_u32_e32 v33, vcc, 0, v31, vcc
	v_add_co_u32_e32 v34, vcc, s39, v30
	global_load_dwordx4 v[10:13], v[18:19], off
	global_load_dwordx4 v[14:17], v238, s[2:3]
	v_addc_co_u32_e32 v35, vcc, 0, v31, vcc
	global_load_dwordx4 v[18:21], v[32:33], off
	global_load_dwordx4 v[22:25], v[34:35], off
	global_load_dwordx4 v[26:29], v238, s[6:7]
	v_add_co_u32_e32 v30, vcc, s38, v30
	v_mov_b32_e32 v1, v0
	s_nop 0
	v_addc_co_u32_e32 v31, vcc, 0, v31, vcc
	global_load_dwordx4 v[30:33], v[30:31], off
	s_movk_i32 s41, 0xf0
	v_ashrrev_i32_e32 v35, 4, v1
	v_xor_b32_e32 v1, v35, v1
	v_lshlrev_b32_e32 v35, 8, v35
	v_lshlrev_b32_e32 v1, 4, v1
	v_mov_b32_e32 v34, v0
	v_and_or_b32 v1, v1, s41, v35
	s_mov_b32 s40, 2
	s_movk_i32 s42, 0xff80
	s_mov_b32 s43, 0x10000
	s_mov_b32 s44, 0x11000
	s_movk_i32 s45, 0x1800
	s_movk_i32 s46, 0x1fff
	v_mov_b32_e32 v240, 0x8040
	s_mov_b32 s26, 2
	s_mov_b32 s47, s28
	s_mov_b32 s48, s34
	s_mov_b32 s49, s36
	v_mov_b32_e32 v83, v82
	v_mov_b32_e32 v84, v82
	v_mov_b32_e32 v85, v82
	v_mov_b32_e32 v102, v82
	v_mov_b32_e32 v103, v82
	v_mov_b32_e32 v104, v82
	v_mov_b32_e32 v105, v82
	v_mov_b32_e32 v106, v82
	v_mov_b32_e32 v107, v82
	v_mov_b32_e32 v108, v82
	v_mov_b32_e32 v109, v82
	v_mov_b32_e32 v110, v82
	v_mov_b32_e32 v111, v82
	s_waitcnt vmcnt(4)
	ds_write_b128 v1, v[14:17] offset:32768
	ds_write_b128 v1, v[10:13] offset:40960
	ds_write_b128 v1, v[6:9] offset:49152
	ds_write_b128 v1, v[2:5] offset:57344
	s_waitcnt vmcnt(1)
	ds_write_b128 v1, v[26:29]
	ds_write_b128 v1, v[22:25] offset:8192
	ds_write_b128 v1, v[18:21] offset:16384
	s_waitcnt vmcnt(0)
	ds_write_b128 v1, v[30:33] offset:24576
	v_mov_b32_e32 v112, v82
	v_lshlrev_b32_e32 v2, 4, v34
	v_lshlrev_b32_e32 v1, 8, v34
	v_and_b32_e32 v2, 0x70, v2
	v_and_or_b32 v238, v1, s37, v2
	v_lshl_add_u64 v[10:11], s[2:3], 0, v[238:239]
	v_add_co_u32_e32 v12, vcc, s38, v10
	v_lshl_add_u64 v[16:17], s[6:7], 0, v[238:239]
	s_nop 0
	v_addc_co_u32_e32 v13, vcc, 0, v11, vcc
	v_add_co_u32_e32 v14, vcc, s20, v10
	v_mov_b32_e32 v1, 0x10000
	s_nop 0
	v_addc_co_u32_e32 v15, vcc, 0, v11, vcc
	global_load_dwordx4 v[2:5], v[12:13], off offset:128
	global_load_dwordx4 v[6:9], v[14:15], off offset:128
	v_add_co_u32_e32 v14, vcc, s39, v10
	v_mov_b32_e32 v113, v82
	s_nop 0
	v_addc_co_u32_e32 v15, vcc, 0, v11, vcc
	v_add_co_u32_e32 v22, vcc, s38, v16
	v_mov_b32_e32 v114, v82
	s_nop 0
	v_addc_co_u32_e32 v23, vcc, 0, v17, vcc
	v_add_co_u32_e32 v34, vcc, s20, v16
	global_load_dwordx4 v[10:13], v[14:15], off offset:128
	global_load_dwordx4 v[18:21], v[22:23], off offset:128
	v_addc_co_u32_e32 v35, vcc, 0, v17, vcc
	v_add_co_u32_e32 v36, vcc, s39, v16
	v_mov_b32_e32 v115, v82
	s_nop 0
	v_addc_co_u32_e32 v37, vcc, 0, v17, vcc
	global_load_dwordx4 v[22:25], v[34:35], off offset:128
	global_load_dwordx4 v[26:29], v[36:37], off offset:128
	global_load_dwordx4 v[14:17], v238, s[2:3] offset:128
	global_load_dwordx4 v[30:33], v238, s[6:7] offset:128
	v_mov_b32_e32 v116, v82
	v_mov_b32_e32 v117, v82
	v_mov_b32_e32 v118, v82
	v_mov_b32_e32 v119, v82
	v_mov_b32_e32 v120, v82
	v_mov_b32_e32 v121, v82
	v_mov_b32_e32 v122, v82
	v_mov_b32_e32 v123, v82
	v_mov_b32_e32 v124, v82
	v_mov_b32_e32 v125, v82
	v_mov_b32_e32 v126, v82
	v_mov_b32_e32 v127, v82
	v_mov_b32_e32 v128, v82
	v_mov_b32_e32 v129, v82
	v_mov_b32_e32 v130, v82
	v_mov_b32_e32 v131, v82
	v_mov_b32_e32 v132, v82
	v_mov_b32_e32 v133, v82
	v_mov_b32_e32 v134, v82
	v_mov_b32_e32 v135, v82
	v_mov_b32_e32 v136, v82
	v_mov_b32_e32 v137, v82
	v_mov_b32_e32 v138, v82
	v_mov_b32_e32 v139, v82
	v_mov_b32_e32 v140, v82
	v_mov_b32_e32 v141, v82
	v_mov_b32_e32 v142, v82
	v_mov_b32_e32 v143, v82
	v_mov_b32_e32 v144, v82
	v_mov_b32_e32 v145, v82
	v_mov_b32_e32 v146, v82
	v_mov_b32_e32 v147, v82
	v_mov_b32_e32 v148, v82
	v_mov_b32_e32 v149, v82
	v_mov_b32_e32 v150, v82
	v_mov_b32_e32 v151, v82
	v_mov_b32_e32 v152, v82
	v_mov_b32_e32 v153, v82
	v_mov_b32_e32 v154, v82
	v_mov_b32_e32 v155, v82
	v_mov_b32_e32 v156, v82
	v_mov_b32_e32 v157, v82
	v_mov_b32_e32 v158, v82
	v_mov_b32_e32 v159, v82
	v_mov_b32_e32 v160, v82
	v_mov_b32_e32 v161, v82
	v_mov_b32_e32 v98, v82
	v_mov_b32_e32 v99, v82
	v_mov_b32_e32 v100, v82
	v_mov_b32_e32 v101, v82
	v_mov_b32_e32 v94, v82
	v_mov_b32_e32 v95, v82
	v_mov_b32_e32 v96, v82
	v_mov_b32_e32 v97, v82
	v_mov_b32_e32 v90, v82
	v_mov_b32_e32 v91, v82
	v_mov_b32_e32 v92, v82
	v_mov_b32_e32 v93, v82
	v_mov_b32_e32 v86, v82
	v_mov_b32_e32 v87, v82
	v_mov_b32_e32 v88, v82
	v_mov_b32_e32 v89, v82
	v_mov_b32_e32 v78, v82
	v_mov_b32_e32 v79, v82
	v_mov_b32_e32 v80, v82
	v_mov_b32_e32 v81, v82
	v_mov_b32_e32 v74, v82
	v_mov_b32_e32 v75, v82
	v_mov_b32_e32 v76, v82
	v_mov_b32_e32 v77, v82
	v_mov_b32_e32 v70, v82
	v_mov_b32_e32 v71, v82
	v_mov_b32_e32 v72, v82
	v_mov_b32_e32 v73, v82
	v_mov_b32_e32 v66, v82
	v_mov_b32_e32 v67, v82
	v_mov_b32_e32 v68, v82
	v_mov_b32_e32 v69, v82
	v_mov_b32_e32 v62, v82
	v_mov_b32_e32 v63, v82
	v_mov_b32_e32 v64, v82
	v_mov_b32_e32 v65, v82
	v_mov_b32_e32 v58, v82
	v_mov_b32_e32 v59, v82
	v_mov_b32_e32 v60, v82
	v_mov_b32_e32 v61, v82
	v_mov_b32_e32 v54, v82
	v_mov_b32_e32 v55, v82
	v_mov_b32_e32 v56, v82
	v_mov_b32_e32 v57, v82
	v_mov_b32_e32 v50, v82
	v_mov_b32_e32 v51, v82
	v_mov_b32_e32 v52, v82
	v_mov_b32_e32 v53, v82
	v_mov_b32_e32 v46, v82
	v_mov_b32_e32 v47, v82
	v_mov_b32_e32 v48, v82
	v_mov_b32_e32 v49, v82
	v_mov_b32_e32 v42, v82
	v_mov_b32_e32 v43, v82
	v_mov_b32_e32 v44, v82
	v_mov_b32_e32 v45, v82
	v_mov_b32_e32 v38, v82
	v_mov_b32_e32 v39, v82
	v_mov_b32_e32 v40, v82
	v_mov_b32_e32 v41, v82
	v_mov_b32_e32 v34, v82
	v_mov_b32_e32 v35, v82
	v_mov_b32_e32 v36, v82
	v_mov_b32_e32 v37, v82
	s_waitcnt lgkmcnt(0)
	s_barrier
	s_branch .LBB0_2203

.LBB0_2203:
	s_add_i32 s2, s40, -1
	ds_read_b128 v[174:177], v255
	ds_read_b128 v[166:169], v255 offset:4096
	ds_read_b128 v[170:173], v254
	ds_read_b128 v[162:165], v254 offset:4096
	ds_read_b128 v[194:197], v253
	ds_read_b128 v[182:185], v252
	ds_read_b128 v[178:181], v252 offset:4096
	s_setprio 1
	s_waitcnt lgkmcnt(1)
	v_mfma_f32_16x16x32_bf16 v[158:161], v[174:177], v[182:185], v[158:161]
	s_cmp_lt_i32 s2, s35
	s_cselect_b64 s[22:23], -1, 0
	s_cmp_ge_i32 s2, s35
	v_mfma_f32_16x16x32_bf16 v[154:157], v[170:173], v[182:185], v[154:157]
	v_mfma_f32_16x16x32_bf16 v[150:153], v[166:169], v[182:185], v[150:153]
	v_mfma_f32_16x16x32_bf16 v[146:149], v[162:165], v[182:185], v[146:149]
	ds_read_b128 v[186:189], v253 offset:4096
	ds_read_b128 v[182:185], v252 offset:8192
	v_mfma_f32_16x16x32_bf16 v[142:145], v[174:177], v[194:197], v[142:145]
	v_mfma_f32_16x16x32_bf16 v[138:141], v[170:173], v[194:197], v[138:141]
	v_mfma_f32_16x16x32_bf16 v[134:137], v[166:169], v[194:197], v[134:137]
	v_mfma_f32_16x16x32_bf16 v[130:133], v[162:165], v[194:197], v[130:133]
	s_cbranch_scc1 .LBB0_2205
	s_waitcnt vmcnt(0)
	ds_write_b128 v245, v[30:33]
	ds_write_b128 v245, v[26:29] offset:8192
.LBB0_2205:
	s_lshl_b32 s6, s49, 8
	s_ashr_i32 s7, s6, 31
	s_lshl_b32 s2, s26, 6
	s_ashr_i32 s3, s2, 31
	s_lshl_b64 s[20:21], s[6:7], 11
	s_add_u32 s24, s29, s20
	s_addc_u32 s25, s30, s21
	s_lshl_b64 s[20:21], s[2:3], 1
	s_waitcnt vmcnt(2)
	s_add_u32 s24, s24, s20
	s_addc_u32 s25, s25, s21
	s_waitcnt vmcnt(0)
	s_nop 0
	s_waitcnt lgkmcnt(2)
	v_mfma_f32_16x16x32_bf16 v[126:129], v[174:177], v[178:181], v[126:129]
	global_load_dwordx4 v[30:33], v244, s[24:25]
	v_mfma_f32_16x16x32_bf16 v[122:125], v[170:173], v[178:181], v[122:125]
	v_mfma_f32_16x16x32_bf16 v[118:121], v[166:169], v[178:181], v[118:121]
	v_mfma_f32_16x16x32_bf16 v[114:117], v[162:165], v[178:181], v[114:117]
	s_waitcnt lgkmcnt(0)
	v_mfma_f32_16x16x32_bf16 v[98:101], v[174:177], v[182:185], v[98:101]
	v_mfma_f32_16x16x32_bf16 v[94:97], v[170:173], v[182:185], v[94:97]
	v_mfma_f32_16x16x32_bf16 v[178:181], v[166:169], v[182:185], v[90:93]
	s_nop 2
	ds_read_b128 v[90:93], v253 offset:8192
	v_mfma_f32_16x16x32_bf16 v[182:185], v[162:165], v[182:185], v[86:89]
	s_nop 2
	ds_read_b128 v[86:89], v253 offset:12288
	global_load_dwordx4 v[26:29], v246, s[24:25]
	v_mfma_f32_16x16x32_bf16 v[110:113], v[174:177], v[186:189], v[110:113]
	v_mfma_f32_16x16x32_bf16 v[106:109], v[170:173], v[186:189], v[106:109]
	v_mfma_f32_16x16x32_bf16 v[102:105], v[166:169], v[186:189], v[102:105]
	v_mfma_f32_16x16x32_bf16 v[82:85], v[162:165], v[186:189], v[82:85]
	s_waitcnt lgkmcnt(1)
	v_mfma_f32_16x16x32_bf16 v[186:189], v[166:169], v[90:93], v[70:73]
	s_nop 2
	ds_read_b128 v[70:73], v252 offset:12288
	v_mfma_f32_16x16x32_bf16 v[78:81], v[174:177], v[90:93], v[78:81]
	v_mfma_f32_16x16x32_bf16 v[74:77], v[170:173], v[90:93], v[74:77]
	v_mfma_f32_16x16x32_bf16 v[190:193], v[162:165], v[90:93], v[66:69]
	s_nop 2
	v_cndmask_b32_e64 v67, 0, 1, s[22:23]
	v_cmp_ne_u32_e64 s[2:3], 1, v67
	s_andn2_b64 vcc, exec, s[22:23]
	s_cbranch_vccnz .LBB0_2207
	ds_write_b128 v245, v[22:25] offset:16384
	ds_write_b128 v245, v[18:21] offset:24576
.LBB0_2207:
	s_waitcnt lgkmcnt(0)
	v_mfma_f32_16x16x32_bf16 v[194:197], v[174:177], v[70:73], v[62:65]
	v_mfma_f32_16x16x32_bf16 v[198:201], v[170:173], v[70:73], v[58:61]
	s_nop 0
	global_load_dwordx4 v[18:21], v243, s[24:25]
	s_nop 0
	v_add_u32_e32 v22, 0x60000, v246
	global_load_dwordx4 v[22:25], v22, s[24:25]
	v_mfma_f32_16x16x32_bf16 v[202:205], v[166:169], v[70:73], v[54:57]
	v_mfma_f32_16x16x32_bf16 v[206:209], v[162:165], v[70:73], v[50:53]
	v_mfma_f32_16x16x32_bf16 v[174:177], v[174:177], v[86:89], v[46:49]
	v_mfma_f32_16x16x32_bf16 v[170:173], v[170:173], v[86:89], v[42:45]
	v_mfma_f32_16x16x32_bf16 v[166:169], v[166:169], v[86:89], v[38:41]
	v_mfma_f32_16x16x32_bf16 v[162:165], v[162:165], v[86:89], v[34:37]
	s_setprio 0
	s_nop 1
	s_nop 0
	ds_read_b128 v[218:221], v250
	ds_read_b128 v[214:217], v249 offset:4096
	ds_read_b128 v[210:213], v250 offset:4096
	ds_read_b128 v[222:225], v249
	ds_read_b128 v[34:37], v248
	ds_read_b128 v[38:41], v247
	ds_read_b128 v[54:57], v247 offset:4096
	s_setprio 1
	s_waitcnt lgkmcnt(1)
	v_mfma_f32_16x16x32_bf16 v[158:161], v[222:225], v[38:41], v[158:161]
	v_mfma_f32_16x16x32_bf16 v[154:157], v[218:221], v[38:41], v[154:157]
	v_mfma_f32_16x16x32_bf16 v[150:153], v[214:217], v[38:41], v[150:153]
	v_mfma_f32_16x16x32_bf16 v[146:149], v[210:213], v[38:41], v[146:149]
	v_mfma_f32_16x16x32_bf16 v[38:41], v[214:217], v[34:37], v[134:137]
	ds_read_b128 v[70:73], v248 offset:4096
	s_nop 1
	ds_read_b128 v[134:137], v247 offset:8192
	v_mfma_f32_16x16x32_bf16 v[142:145], v[222:225], v[34:37], v[142:145]
	v_mfma_f32_16x16x32_bf16 v[138:141], v[218:221], v[34:37], v[138:141]
	v_mfma_f32_16x16x32_bf16 v[34:37], v[210:213], v[34:37], v[130:133]
	s_nop 2
	s_and_b64 vcc, exec, s[2:3]
	s_cbranch_vccnz .LBB0_2209
	ds_write_b128 v245, v[14:17] offset:32768
	ds_write_b128 v245, v[10:13] offset:40960
.LBB0_2209:
	s_lshl_b32 s22, s48, 8
	s_ashr_i32 s23, s22, 31
	s_lshl_b64 s[24:25], s[22:23], 11
	s_add_u32 s24, s31, s24
	s_addc_u32 s25, s33, s25
	s_add_u32 s20, s24, s20
	s_addc_u32 s21, s25, s21
	s_waitcnt lgkmcnt(2)
	v_mfma_f32_16x16x32_bf16 v[50:53], v[214:217], v[54:57], v[118:121]
	s_waitcnt lgkmcnt(1)
	v_mfma_f32_16x16x32_bf16 v[58:61], v[222:225], v[70:73], v[110:113]
	ds_read_b128 v[118:121], v247 offset:12288
	v_mfma_f32_16x16x32_bf16 v[62:65], v[218:221], v[70:73], v[106:109]
	v_mfma_f32_16x16x32_bf16 v[66:69], v[214:217], v[70:73], v[102:105]
	v_mfma_f32_16x16x32_bf16 v[70:73], v[210:213], v[70:73], v[82:85]
	s_nop 2
	ds_read_b128 v[82:85], v248 offset:8192
	global_load_dwordx4 v[10:13], v246, s[20:21]
	s_nop 0
	global_load_dwordx4 v[14:17], v244, s[20:21]
	s_waitcnt lgkmcnt(2)
	v_mfma_f32_16x16x32_bf16 v[86:89], v[222:225], v[134:137], v[98:101]
	v_mfma_f32_16x16x32_bf16 v[90:93], v[218:221], v[134:137], v[94:97]
	v_mfma_f32_16x16x32_bf16 v[94:97], v[214:217], v[134:137], v[178:181]
	v_mfma_f32_16x16x32_bf16 v[98:101], v[210:213], v[134:137], v[182:185]
	ds_read_b128 v[134:137], v248 offset:12288
	v_mfma_f32_16x16x32_bf16 v[42:45], v[222:225], v[54:57], v[126:129]
	v_mfma_f32_16x16x32_bf16 v[46:49], v[218:221], v[54:57], v[122:125]
	v_mfma_f32_16x16x32_bf16 v[54:57], v[210:213], v[54:57], v[114:117]
	s_waitcnt lgkmcnt(1)
	v_mfma_f32_16x16x32_bf16 v[102:105], v[222:225], v[82:85], v[78:81]
	v_mfma_f32_16x16x32_bf16 v[74:77], v[218:221], v[82:85], v[74:77]
	v_mfma_f32_16x16x32_bf16 v[78:81], v[214:217], v[82:85], v[186:189]
	v_mfma_f32_16x16x32_bf16 v[82:85], v[210:213], v[82:85], v[190:193]
	s_and_b64 vcc, exec, s[2:3]
	s_cbranch_vccnz .LBB0_2211
	ds_write_b128 v245, v[6:9] offset:49152
	ds_write_b128 v245, v[2:5] offset:57344
.LBB0_2211:
	v_mfma_f32_16x16x32_bf16 v[106:109], v[222:225], v[118:121], v[194:197]
	s_nop 0
	v_mfma_f32_16x16x32_bf16 v[110:113], v[218:221], v[118:121], v[198:201]
	s_nop 0
	global_load_dwordx4 v[2:5], v243, s[20:21]
	s_nop 0
	v_add_u32_e32 v6, 0x60000, v246
	global_load_dwordx4 v[6:9], v6, s[20:21]
	v_mfma_f32_16x16x32_bf16 v[114:117], v[214:217], v[118:121], v[202:205]
	s_lshl_b64 s[2:3], s[6:7], 10
	s_lshl_b64 s[20:21], s[22:23], 10
	v_mfma_f32_16x16x32_bf16 v[118:121], v[210:213], v[118:121], v[206:209]
	s_waitcnt lgkmcnt(0)
	v_mfma_f32_16x16x32_bf16 v[122:125], v[222:225], v[134:137], v[174:177]
	v_mfma_f32_16x16x32_bf16 v[126:129], v[218:221], v[134:137], v[170:173]
	v_mfma_f32_16x16x32_bf16 v[130:133], v[214:217], v[134:137], v[166:169]
	v_mfma_f32_16x16x32_bf16 v[134:137], v[210:213], v[134:137], v[162:165]
	s_setprio 0
	s_add_i32 s51, s26, 1
	s_cmp_lg_u32 s51, 16
	s_cbranch_scc1 .LBB0_2215
	s_add_i32 s28, s28, s11
	s_cmp_gt_i32 s28, 31
	s_cbranch_scc1 .LBB0_2214
	s_ashr_i32 s3, s28, 31
	s_lshr_b32 s3, s3, 27
	s_add_i32 s3, s28, s3
	s_ashr_i32 s3, s3, 5
	s_mov_b32 s2, s10
	s_lshl_b32 s6, s3, 6
	s_lshl_b32 s7, s28, 1
	s_sub_i32 s6, s7, s6
	s_and_b32 s2, s2, 7
	s_and_b32 s6, s6, -8
	s_lshl_b32 s3, s3, 2
	s_and_b32 s7, s28, 3
	s_or_b32 s48, s3, s7
	s_or_b32 s49, s2, s6
	s_lshl_b32 s2, s49, 8
	s_lshl_b32 s6, s48, 8
	s_ashr_i32 s3, s2, 31
	s_ashr_i32 s7, s6, 31
	s_lshl_b64 s[2:3], s[2:3], 10
	s_lshl_b64 s[20:21], s[6:7], 10

.LBB0_2215:
	s_barrier
	s_nop 0
	v_add_u32_e32 v170, 0x10000, v255
	v_add_u32_e32 v162, 0x11000, v255
	v_add_u32_e32 v171, 0x10000, v254
	ds_read_b128 v[206:209], v170
	ds_read_b128 v[210:213], v171
	v_add_u32_e32 v169, 0x11000, v254
	ds_read_b128 v[214:217], v162
	ds_read_b128 v[218:221], v169
	v_add_u32_e32 v186, 0x10000, v253
	v_add_u32_e32 v187, 0x10000, v252
	ds_read_b128 v[162:165], v186
	ds_read_b128 v[166:169], v187
	ds_read_b128 v[174:177], v187 offset:4096
	s_setprio 1
	ds_read_b128 v[182:185], v186 offset:4096
	ds_read_b128 v[178:181], v187 offset:8192
	s_waitcnt lgkmcnt(3)
	v_mfma_f32_16x16x32_bf16 v[158:161], v[206:209], v[166:169], v[158:161]
	s_cmp_lt_i32 s40, s35
	s_cselect_b64 s[24:25], -1, 0
	s_cmp_ge_i32 s40, s35
	v_mfma_f32_16x16x32_bf16 v[154:157], v[210:213], v[166:169], v[154:157]
	s_cselect_b64 s[6:7], -1, 0
	v_mfma_f32_16x16x32_bf16 v[150:153], v[214:217], v[166:169], v[150:153]
	v_mfma_f32_16x16x32_bf16 v[146:149], v[218:221], v[166:169], v[146:149]
	v_mfma_f32_16x16x32_bf16 v[142:145], v[206:209], v[162:165], v[142:145]
	v_mfma_f32_16x16x32_bf16 v[138:141], v[210:213], v[162:165], v[138:141]
	v_mfma_f32_16x16x32_bf16 v[38:41], v[214:217], v[162:165], v[38:41]
	v_mfma_f32_16x16x32_bf16 v[34:37], v[218:221], v[162:165], v[34:37]
	s_and_b64 vcc, exec, s[6:7]
	s_cbranch_vccnz .LBB0_2217
	s_waitcnt vmcnt(6)
	ds_write_b128 v251, v[26:29]
	ds_write_b128 v251, v[30:33] offset:8192
.LBB0_2217:
	s_lshl_b32 s22, s51, 6
	s_ashr_i32 s23, s22, 31
	s_lshl_b64 s[2:3], s[2:3], 1
	s_add_u32 s2, s29, s2
	s_addc_u32 s3, s30, s3
	s_lshl_b64 s[22:23], s[22:23], 1
	s_waitcnt vmcnt(6)
	s_add_u32 s26, s2, s22
	s_addc_u32 s27, s3, s23
	s_waitcnt lgkmcnt(2)
	v_mfma_f32_16x16x32_bf16 v[162:165], v[206:209], v[174:177], v[42:45]
	v_mfma_f32_16x16x32_bf16 v[166:169], v[210:213], v[174:177], v[46:49]
	s_waitcnt lgkmcnt(0)
	v_mfma_f32_16x16x32_bf16 v[42:45], v[206:209], v[178:181], v[86:89]
	v_mfma_f32_16x16x32_bf16 v[46:49], v[210:213], v[178:181], v[90:93]
	s_nop 1
	ds_read_b128 v[86:89], v187 offset:12288
	ds_read_b128 v[90:93], v186 offset:8192
	global_load_dwordx4 v[30:33], v246, s[26:27]
	s_nop 0
	global_load_dwordx4 v[26:29], v244, s[26:27]
	v_mfma_f32_16x16x32_bf16 v[58:61], v[206:209], v[182:185], v[58:61]
	v_mfma_f32_16x16x32_bf16 v[62:65], v[210:213], v[182:185], v[62:65]
	v_mfma_f32_16x16x32_bf16 v[66:69], v[214:217], v[182:185], v[66:69]
	v_mfma_f32_16x16x32_bf16 v[70:73], v[218:221], v[182:185], v[70:73]
	s_waitcnt lgkmcnt(0)
	v_mfma_f32_16x16x32_bf16 v[182:185], v[214:217], v[90:93], v[78:81]
	s_nop 2
	ds_read_b128 v[78:81], v186 offset:12288
	v_mfma_f32_16x16x32_bf16 v[170:173], v[214:217], v[174:177], v[50:53]
	v_mfma_f32_16x16x32_bf16 v[174:177], v[218:221], v[174:177], v[54:57]
	v_mfma_f32_16x16x32_bf16 v[50:53], v[214:217], v[178:181], v[94:97]
	v_mfma_f32_16x16x32_bf16 v[54:57], v[218:221], v[178:181], v[98:101]
	v_mfma_f32_16x16x32_bf16 v[178:181], v[206:209], v[90:93], v[102:105]
	v_mfma_f32_16x16x32_bf16 v[74:77], v[210:213], v[90:93], v[74:77]
	v_mfma_f32_16x16x32_bf16 v[186:189], v[218:221], v[90:93], v[82:85]
	s_nop 2
	v_cndmask_b32_e64 v83, 0, 1, s[24:25]
	v_cmp_ne_u32_e64 s[2:3], 1, v83
	s_andn2_b64 vcc, exec, s[24:25]
	s_cbranch_vccnz .LBB0_2219
	s_waitcnt vmcnt(7)
	ds_write_b128 v251, v[18:21] offset:16384
	s_waitcnt vmcnt(6)
	ds_write_b128 v251, v[22:25] offset:24576
.LBB0_2219:
	s_waitcnt vmcnt(7)
	v_mfma_f32_16x16x32_bf16 v[190:193], v[206:209], v[86:89], v[106:109]
	s_nop 0
	v_mfma_f32_16x16x32_bf16 v[194:197], v[210:213], v[86:89], v[110:113]
	s_nop 0
	global_load_dwordx4 v[22:25], v243, s[26:27]
	s_nop 0
	v_add_u32_e32 v18, 0x60000, v246
	global_load_dwordx4 v[18:21], v18, s[26:27]
	v_mfma_f32_16x16x32_bf16 v[198:201], v[214:217], v[86:89], v[114:117]
	v_mfma_f32_16x16x32_bf16 v[202:205], v[218:221], v[86:89], v[118:121]
	s_waitcnt lgkmcnt(0)
	v_mfma_f32_16x16x32_bf16 v[206:209], v[206:209], v[78:81], v[122:125]
	v_mfma_f32_16x16x32_bf16 v[210:213], v[210:213], v[78:81], v[126:129]
	v_mfma_f32_16x16x32_bf16 v[214:217], v[214:217], v[78:81], v[130:133]
	v_mfma_f32_16x16x32_bf16 v[218:221], v[218:221], v[78:81], v[134:137]
	s_setprio 0
	s_nop 0
	v_add_u32_e32 v81, 0x10000, v249
	v_add_u32_e32 v78, 0x11000, v249
	v_add_u32_e32 v85, 0x10000, v250
	ds_read_b128 v[234:237], v81
	ds_read_b128 v[226:229], v85
	v_add_u32_e32 v80, 0x11000, v250
	ds_read_b128 v[230:233], v78
	ds_read_b128 v[222:225], v80
	v_add_u32_e32 v242, 0x10000, v248
	v_add_u32_e32 v90, 0x10000, v247
	ds_read_b128 v[86:89], v242
	ds_read_b128 v[82:85], v90
	ds_read_b128 v[78:81], v90 offset:4096
	s_setprio 1
	s_waitcnt lgkmcnt(1)
	v_mfma_f32_16x16x32_bf16 v[158:161], v[234:237], v[82:85], v[158:161]
	v_mfma_f32_16x16x32_bf16 v[154:157], v[226:229], v[82:85], v[154:157]
	v_mfma_f32_16x16x32_bf16 v[150:153], v[230:233], v[82:85], v[150:153]
	v_mfma_f32_16x16x32_bf16 v[146:149], v[222:225], v[82:85], v[146:149]
	v_mfma_f32_16x16x32_bf16 v[134:137], v[230:233], v[86:89], v[38:41]
	ds_read_b128 v[82:85], v242 offset:4096
	s_nop 1
	ds_read_b128 v[38:41], v90 offset:8192
	v_mfma_f32_16x16x32_bf16 v[142:145], v[234:237], v[86:89], v[142:145]
	v_mfma_f32_16x16x32_bf16 v[138:141], v[226:229], v[86:89], v[138:141]
	v_mfma_f32_16x16x32_bf16 v[130:133], v[222:225], v[86:89], v[34:37]
	s_nop 2
	s_and_b64 vcc, exec, s[2:3]
	s_cbranch_vccnz .LBB0_2221
	s_waitcnt vmcnt(7)
	ds_write_b128 v251, v[10:13] offset:32768
	s_waitcnt vmcnt(6)
	ds_write_b128 v251, v[14:17] offset:40960
.LBB0_2221:
	s_lshl_b64 s[20:21], s[20:21], 1
	s_add_u32 s20, s31, s20
	s_addc_u32 s21, s33, s21
	s_waitcnt vmcnt(7)
	s_add_u32 s20, s20, s22
	s_addc_u32 s21, s21, s23
	global_load_dwordx4 v[14:17], v246, s[20:21]
	s_nop 0
	global_load_dwordx4 v[10:13], v244, s[20:21]
	s_waitcnt lgkmcnt(0)
	v_mfma_f32_16x16x32_bf16 v[98:101], v[234:237], v[38:41], v[42:45]
	ds_read_b128 v[34:37], v242 offset:12288
	s_nop 1
	ds_read_b128 v[42:45], v242 offset:8192
	v_mfma_f32_16x16x32_bf16 v[94:97], v[226:229], v[38:41], v[46:49]
	v_mfma_f32_16x16x32_bf16 v[90:93], v[230:233], v[38:41], v[50:53]
	v_mfma_f32_16x16x32_bf16 v[86:89], v[222:225], v[38:41], v[54:57]
	v_add_u32_e32 v38, 0x13000, v247
	ds_read_b128 v[38:41], v38
	v_mfma_f32_16x16x32_bf16 v[126:129], v[234:237], v[78:81], v[162:165]
	v_mfma_f32_16x16x32_bf16 v[122:125], v[226:229], v[78:81], v[166:169]
	v_mfma_f32_16x16x32_bf16 v[118:121], v[230:233], v[78:81], v[170:173]
	v_mfma_f32_16x16x32_bf16 v[114:117], v[222:225], v[78:81], v[174:177]
	v_mfma_f32_16x16x32_bf16 v[110:113], v[234:237], v[82:85], v[58:61]
	v_mfma_f32_16x16x32_bf16 v[106:109], v[226:229], v[82:85], v[62:65]
	v_mfma_f32_16x16x32_bf16 v[102:105], v[230:233], v[82:85], v[66:69]
	v_mfma_f32_16x16x32_bf16 v[82:85], v[222:225], v[82:85], v[70:73]
	s_waitcnt lgkmcnt(1)
	v_mfma_f32_16x16x32_bf16 v[78:81], v[234:237], v[42:45], v[178:181]
	v_mfma_f32_16x16x32_bf16 v[74:77], v[226:229], v[42:45], v[74:77]
	v_mfma_f32_16x16x32_bf16 v[70:73], v[230:233], v[42:45], v[182:185]
	v_mfma_f32_16x16x32_bf16 v[66:69], v[222:225], v[42:45], v[186:189]
	v_mov_b32_e32 v42, v0
	s_and_b64 vcc, exec, s[2:3]
	s_cbranch_vccnz .LBB0_2223
	s_waitcnt vmcnt(7)
	ds_write_b128 v251, v[2:5] offset:49152
	s_waitcnt vmcnt(6)
	ds_write_b128 v251, v[6:9] offset:57344
.LBB0_2223:
	s_waitcnt vmcnt(7)
	v_lshlrev_b32_e32 v3, 4, v42
	v_lshlrev_b32_e32 v2, 8, v42
	v_and_b32_e32 v3, 0x70, v3
	v_and_or_b32 v238, v2, s37, v3
	s_waitcnt lgkmcnt(0)
	v_mfma_f32_16x16x32_bf16 v[62:65], v[234:237], v[38:41], v[190:193]
	v_mfma_f32_16x16x32_bf16 v[58:61], v[226:229], v[38:41], v[194:197]
	s_nop 0
	global_load_dwordx4 v[6:9], v243, s[20:21]
	s_nop 0
	v_add_u32_e32 v2, 0x60000, v246
	global_load_dwordx4 v[2:5], v2, s[20:21]
	v_mfma_f32_16x16x32_bf16 v[54:57], v[230:233], v[38:41], v[198:201]
	v_mfma_f32_16x16x32_bf16 v[50:53], v[222:225], v[38:41], v[202:205]
	v_mfma_f32_16x16x32_bf16 v[46:49], v[234:237], v[34:37], v[206:209]
	v_mfma_f32_16x16x32_bf16 v[42:45], v[226:229], v[34:37], v[210:213]
	v_mfma_f32_16x16x32_bf16 v[38:41], v[230:233], v[34:37], v[214:217]
	v_mfma_f32_16x16x32_bf16 v[34:37], v[222:225], v[34:37], v[218:221]
	s_setprio 0
	s_add_i32 s26, s51, 1
	s_cmp_lg_u32 s26, 16
	s_cbranch_scc1 .LBB0_2227
	s_add_i32 s28, s28, s11
	s_cmp_gt_i32 s28, 31
	s_cbranch_scc1 .LBB0_2226
	s_ashr_i32 s3, s28, 31
	s_lshr_b32 s3, s3, 27
	s_add_i32 s3, s28, s3
	s_ashr_i32 s3, s3, 5
	s_mov_b32 s2, s10
	s_lshl_b32 s20, s3, 6
	s_lshl_b32 s21, s28, 1
	s_sub_i32 s20, s21, s20
	s_and_b32 s2, s2, 7
	s_and_b32 s20, s20, -8
	s_lshl_b32 s3, s3, 2
	s_and_b32 s21, s28, 3
	s_or_b32 s48, s3, s21
	s_or_b32 s49, s2, s20

.LBB0_2541:
	v_mov_b32_e32 v255, 0x8000
	v_bfe_u32 v1, v0, 0, 1
	v_lshlrev_b32_e32 v1, 7, v1
	v_xor_b32_e32 v255, v255, v1
	v_bfe_u32 v1, v0, 1, 3
	v_mul_u32_u24_e32 v1, 0x110, v1
	v_xor_b32_e32 v255, v255, v1
	v_bfe_u32 v1, v0, 4, 2
	v_lshlrev_b32_e32 v1, 4, v1
	v_xor_b32_e32 v255, v255, v1
	v_bfe_u32 v1, v0, 6, 2
	v_lshlrev_b32_e32 v1, 13, v1
	v_xor_b32_e32 v255, v255, v1
	v_mov_b32_e32 v254, 0x8880
	v_bfe_u32 v1, v0, 0, 1
	v_lshlrev_b32_e32 v1, 7, v1
	v_xor_b32_e32 v254, v254, v1
	v_bfe_u32 v1, v0, 1, 3
	v_mul_u32_u24_e32 v1, 0x110, v1
	v_xor_b32_e32 v254, v254, v1
	v_bfe_u32 v1, v0, 4, 2
	v_lshlrev_b32_e32 v1, 4, v1
	v_xor_b32_e32 v254, v254, v1
	v_bfe_u32 v1, v0, 6, 2
	v_lshlrev_b32_e32 v1, 13, v1
	v_xor_b32_e32 v254, v254, v1
	v_mov_b32_e32 v253, 0x880
	v_bfe_u32 v1, v0, 0, 1
	v_lshlrev_b32_e32 v1, 7, v1
	v_xor_b32_e32 v253, v253, v1
	v_bfe_u32 v1, v0, 1, 3
	v_mul_u32_u24_e32 v1, 0x110, v1
	v_xor_b32_e32 v253, v253, v1
	v_bfe_u32 v1, v0, 4, 2
	v_lshlrev_b32_e32 v1, 4, v1
	v_xor_b32_e32 v253, v253, v1
	v_bfe_u32 v1, v0, 8, 1
	v_lshlrev_b32_e32 v1, 14, v1
	v_xor_b32_e32 v253, v253, v1
	v_mov_b32_e32 v252, 0x0
	v_bfe_u32 v1, v0, 0, 1
	v_lshlrev_b32_e32 v1, 7, v1
	v_xor_b32_e32 v252, v252, v1
	v_bfe_u32 v1, v0, 1, 3
	v_mul_u32_u24_e32 v1, 0x110, v1
	v_xor_b32_e32 v252, v252, v1
	v_bfe_u32 v1, v0, 4, 2
	v_lshlrev_b32_e32 v1, 4, v1
	v_xor_b32_e32 v252, v252, v1
	v_bfe_u32 v1, v0, 8, 1
	v_lshlrev_b32_e32 v1, 14, v1
	v_xor_b32_e32 v252, v252, v1
	v_mov_b32_e32 v251, 0x0
	v_bfe_u32 v1, v0, 0, 4
	v_lshlrev_b32_e32 v1, 4, v1
	v_xor_b32_e32 v251, v251, v1
	v_bfe_u32 v1, v0, 4, 4
	v_mul_u32_u24_e32 v1, 0x110, v1
	v_xor_b32_e32 v251, v251, v1
	v_bfe_u32 v1, v0, 8, 1
	v_lshlrev_b32_e32 v1, 12, v1
	v_xor_b32_e32 v251, v251, v1
	v_mov_b32_e32 v250, 0x88c0
	v_bfe_u32 v1, v0, 0, 1
	v_lshlrev_b32_e32 v1, 7, v1
	v_xor_b32_e32 v250, v250, v1
	v_bfe_u32 v1, v0, 1, 3
	v_mul_u32_u24_e32 v1, 0x110, v1
	v_xor_b32_e32 v250, v250, v1
	v_bfe_u32 v1, v0, 4, 2
	v_lshlrev_b32_e32 v1, 4, v1
	v_xor_b32_e32 v250, v250, v1
	v_bfe_u32 v1, v0, 6, 2
	v_lshlrev_b32_e32 v1, 13, v1
	v_xor_b32_e32 v250, v250, v1
	v_mov_b32_e32 v249, 0x8040
	v_bfe_u32 v1, v0, 0, 1
	v_lshlrev_b32_e32 v1, 7, v1
	v_xor_b32_e32 v249, v249, v1
	v_bfe_u32 v1, v0, 1, 3
	v_mul_u32_u24_e32 v1, 0x110, v1
	v_xor_b32_e32 v249, v249, v1
	v_bfe_u32 v1, v0, 4, 2
	v_lshlrev_b32_e32 v1, 4, v1
	v_xor_b32_e32 v249, v249, v1
	v_bfe_u32 v1, v0, 6, 2
	v_lshlrev_b32_e32 v1, 13, v1
	v_xor_b32_e32 v249, v249, v1
	v_mov_b32_e32 v248, 0x8c0
	v_bfe_u32 v1, v0, 0, 1
	v_lshlrev_b32_e32 v1, 7, v1
	v_xor_b32_e32 v248, v248, v1
	v_bfe_u32 v1, v0, 1, 3
	v_mul_u32_u24_e32 v1, 0x110, v1
	v_xor_b32_e32 v248, v248, v1
	v_bfe_u32 v1, v0, 4, 2
	v_lshlrev_b32_e32 v1, 4, v1
	v_xor_b32_e32 v248, v248, v1
	v_bfe_u32 v1, v0, 8, 1
	v_lshlrev_b32_e32 v1, 14, v1
	v_xor_b32_e32 v248, v248, v1
	v_mov_b32_e32 v247, 0x40
	v_bfe_u32 v1, v0, 0, 1
	v_lshlrev_b32_e32 v1, 7, v1
	v_xor_b32_e32 v247, v247, v1
	v_bfe_u32 v1, v0, 1, 3
	v_mul_u32_u24_e32 v1, 0x110, v1
	v_xor_b32_e32 v247, v247, v1
	v_bfe_u32 v1, v0, 4, 2
	v_lshlrev_b32_e32 v1, 4, v1
	v_xor_b32_e32 v247, v247, v1
	v_bfe_u32 v1, v0, 8, 1
	v_lshlrev_b32_e32 v1, 14, v1
	v_xor_b32_e32 v247, v247, v1
	v_mov_b32_e32 v246, 0x0
	v_bfe_u32 v1, v0, 0, 3
	v_lshlrev_b32_e32 v1, 4, v1
	v_add_u32_e32 v246, v246, v1
	v_bfe_u32 v1, v0, 3, 6
	v_mul_u32_u24_e32 v1, 0x1600, v1
	v_add_u32_e32 v246, v246, v1
	v_mov_b32_e32 v245, 0x10000
	v_bfe_u32 v1, v0, 0, 4
	v_lshlrev_b32_e32 v1, 4, v1
	v_xor_b32_e32 v245, v245, v1
	v_bfe_u32 v1, v0, 4, 4
	v_mul_u32_u24_e32 v1, 0x110, v1
	v_xor_b32_e32 v245, v245, v1
	v_bfe_u32 v1, v0, 8, 1
	v_lshlrev_b32_e32 v1, 12, v1
	v_xor_b32_e32 v245, v245, v1
	v_mov_b32_e32 v244, 0x58000
	v_bfe_u32 v1, v0, 0, 3
	v_lshlrev_b32_e32 v1, 4, v1
	v_add_u32_e32 v244, v244, v1
	v_bfe_u32 v1, v0, 3, 6
	v_mul_u32_u24_e32 v1, 0x1600, v1
	v_add_u32_e32 v244, v244, v1
	v_mov_b32_e32 v243, 0xb0000
	v_bfe_u32 v1, v0, 0, 3
	v_lshlrev_b32_e32 v1, 4, v1
	v_add_u32_e32 v243, v243, v1
	v_bfe_u32 v1, v0, 3, 6
	v_mul_u32_u24_e32 v1, 0x1600, v1
	v_add_u32_e32 v243, v243, v1
	v_mov_b32_e32 v1, v0
	s_load_dword s0, s[0:1], 0xe0
	s_mov_b32 s1, s10
	v_mov_b32_e32 v1, v0
	s_waitcnt lgkmcnt(0)
	s_lshr_b32 s11, s0, 3
	s_waitcnt vmcnt(0)
	v_cvt_f32_u32_e32 v2, s11
	s_mov_b32 s0, s10
	s_ashr_i32 s1, s0, 3
	v_rcp_iflag_f32_e32 v2, v2
	s_ashr_i32 s2, s0, 31
	s_sub_i32 s0, 0, s11
	s_abs_i32 s1, s1
	v_mul_f32_e32 v1, 0x4f7ffffe, v2
	v_cvt_u32_f32_e32 v1, v1
	s_mov_b32 s42, 0
	v_readfirstlane_b32 s3, v1
	s_mul_i32 s0, s0, s3
	s_mul_hi_u32 s0, s3, s0
	s_add_i32 s0, s3, s0
	s_mul_hi_u32 s3, s1, s0
	s_mul_i32 s3, s3, s11
	s_sub_i32 s1, s1, s3
	s_sub_i32 s3, s1, s11
	s_cmp_ge_u32 s1, s11
	s_cselect_b32 s1, s3, s1
	s_sub_i32 s3, s1, s11
	s_cmp_ge_u32 s1, s11
	s_cselect_b32 s1, s3, s1
	s_xor_b32 s1, s1, s2
	s_sub_i32 s20, s1, s2
	s_mov_b32 s1, s10
	s_cmp_gt_i32 s20, 31
	s_cbranch_scc1 .LBB0_2605
	s_load_dwordx4 s[4:7], s[16:17], 0xc8
	s_mov_b32 s1, s10
	v_mov_b32_e32 v82, 0
	v_mov_b32_e32 v1, v0
	s_waitcnt lgkmcnt(0)
	s_add_u32 s2, s4, 0x2000000
	s_addc_u32 s3, s5, 0
	s_add_u32 s8, s6, 0x27000
	s_addc_u32 s9, s7, 0
	s_add_u32 s21, s6, 0x37f0000
	s_addc_u32 s22, s7, 0
	s_add_u32 s23, s6, 0x1270000
	s_addc_u32 s24, s7, 0
	s_ashr_i32 s6, s20, 31
	s_lshr_b32 s6, s6, 27
	s_add_i32 s6, s20, s6
	s_ashr_i32 s6, s6, 5
	s_lshl_b32 s7, s20, 1
	s_lshl_b32 s12, s6, 6
	s_sub_i32 s7, s7, s12
	s_lshl_b32 s6, s6, 2
	s_and_b32 s12, s20, 3
	s_or_b32 s25, s6, s12
	s_sub_i32 s6, s11, s20
	s_add_i32 s6, s6, 31
	s_mul_hi_u32 s0, s6, s0
	s_mul_i32 s12, s0, s11
	s_sub_i32 s6, s6, s12
	s_add_i32 s12, s0, 1
	s_sub_i32 s13, s6, s11
	s_cmp_ge_u32 s6, s11
	s_cselect_b32 s0, s12, s0
	s_cselect_b32 s6, s13, s6
	s_add_i32 s12, s0, 1
	s_cmp_ge_u32 s6, s11
	s_cselect_b32 s33, s12, s0
	s_and_b32 s0, s1, 7
	s_and_b32 s1, s7, -8
	s_movk_i32 s26, 0xb00
	v_lshrrev_b32_e32 v2, 3, v1
	s_or_b32 s27, s0, s1
	s_lshl_b32 s0, s25, 8
	s_mul_i32 s1, s25, 0x160000
	v_mul_lo_u32 v2, v2, s26
	v_lshlrev_b32_e32 v1, 3, v1
	s_mul_hi_i32 s6, s0, 0x1600
	s_add_u32 s0, s23, s1
	v_and_or_b32 v1, v1, 56, v2
	v_mov_b32_e32 v239, 0
	s_addc_u32 s1, s24, s6
	v_lshlrev_b32_e32 v238, 1, v1
	v_lshl_add_u64 v[2:3], s[0:1], 0, v[238:239]
	s_mov_b32 s28, 0x108000
	v_add_co_u32_e32 v34, vcc, s28, v2
	s_mov_b32 s12, 0xb0000
	s_nop 0
	v_addc_co_u32_e32 v35, vcc, 0, v3, vcc
	v_add_co_u32_e32 v36, vcc, s12, v2
	s_lshl_b32 s6, s27, 8
	s_mul_i32 s7, s27, 0x160000
	v_addc_co_u32_e32 v37, vcc, 0, v3, vcc
	s_mov_b32 s29, 0x58000
	s_mul_hi_i32 s13, s6, 0x1600
	s_add_u32 s6, s21, s7
	v_add_co_u32_e32 v2, vcc, s29, v2
	s_addc_u32 s7, s22, s13
	s_nop 0
	v_addc_co_u32_e32 v3, vcc, 0, v3, vcc
	v_lshl_add_u64 v[22:23], s[6:7], 0, v[238:239]
	v_add_co_u32_e32 v24, vcc, s12, v22
	global_load_dwordx4 v[2:5], v[2:3], off
	s_nop 0
	v_addc_co_u32_e32 v25, vcc, 0, v23, vcc
	v_add_co_u32_e32 v26, vcc, s29, v22
	v_mov_b32_e32 v1, v0
	s_nop 0
	v_addc_co_u32_e32 v27, vcc, 0, v23, vcc
	v_add_co_u32_e32 v38, vcc, s28, v22
	global_load_dwordx4 v[6:9], v[24:25], off
	global_load_dwordx4 v[10:13], v[26:27], off
	global_load_dwordx4 v[14:17], v238, s[0:1]
	global_load_dwordx4 v[18:21], v238, s[6:7]
	v_addc_co_u32_e32 v39, vcc, 0, v23, vcc
	global_load_dwordx4 v[22:25], v[38:39], off
	global_load_dwordx4 v[26:29], v[36:37], off
	global_load_dwordx4 v[30:33], v[34:35], off
	s_movk_i32 s31, 0xf0
	v_ashrrev_i32_e32 v34, 4, v1
	v_xor_b32_e32 v1, v34, v1
	v_lshlrev_b32_e32 v34, 8, v34
	v_lshlrev_b32_e32 v1, 4, v1
	v_and_or_b32 v1, v1, s31, v34
	s_mov_b32 s30, 2
	s_mul_i32 s33, s33, 44
	s_movk_i32 s34, 0xff80
	s_mov_b32 s35, 0x10000
	s_mov_b32 s36, 0x11000
	s_movk_i32 s37, 0x1800
	s_movk_i32 s38, 0x1fff
	v_mov_b32_e32 v240, 0x8040
	s_mov_b32 s18, 2
	s_mov_b32 s39, s20
	s_mov_b32 s40, s25
	s_mov_b32 s41, s27
	v_mov_b32_e32 v83, v82
	v_mov_b32_e32 v84, v82
	v_mov_b32_e32 v85, v82
	v_mov_b32_e32 v102, v82
	v_mov_b32_e32 v103, v82
	v_mov_b32_e32 v104, v82
	v_mov_b32_e32 v105, v82
	v_mov_b32_e32 v106, v82
	v_mov_b32_e32 v107, v82
	v_mov_b32_e32 v108, v82
	v_mov_b32_e32 v109, v82
	v_mov_b32_e32 v110, v82
	v_mov_b32_e32 v111, v82
	v_mov_b32_e32 v112, v82
	v_mov_b32_e32 v113, v82
	s_waitcnt vmcnt(4)
	ds_write_b128 v1, v[14:17] offset:32768
	s_waitcnt vmcnt(3)
	ds_write_b128 v1, v[18:21]
	ds_write_b128 v1, v[2:5] offset:40960
	ds_write_b128 v1, v[10:13] offset:8192
	ds_write_b128 v1, v[6:9] offset:16384
	s_waitcnt vmcnt(2)
	ds_write_b128 v1, v[22:25] offset:24576
	s_waitcnt vmcnt(1)
	ds_write_b128 v1, v[26:29] offset:49152
	s_waitcnt vmcnt(0)
	ds_write_b128 v1, v[30:33] offset:57344
	v_mov_b32_e32 v1, v0
	v_mov_b32_e32 v114, v82
	v_lshrrev_b32_e32 v2, 3, v1
	v_mul_lo_u32 v2, v2, s26
	v_lshlrev_b32_e32 v1, 3, v1
	v_and_or_b32 v1, v1, 56, v2
	v_lshlrev_b32_e32 v238, 1, v1
	v_lshl_add_u64 v[10:11], s[0:1], 0, v[238:239]
	v_add_co_u32_e32 v12, vcc, s28, v10
	v_lshl_add_u64 v[16:17], s[6:7], 0, v[238:239]
	s_nop 0
	v_addc_co_u32_e32 v13, vcc, 0, v11, vcc
	v_add_co_u32_e32 v14, vcc, s12, v10
	v_mov_b32_e32 v1, 0x10000
	s_nop 0
	v_addc_co_u32_e32 v15, vcc, 0, v11, vcc
	global_load_dwordx4 v[2:5], v[12:13], off offset:128
	global_load_dwordx4 v[6:9], v[14:15], off offset:128
	v_add_co_u32_e32 v14, vcc, s29, v10
	v_mov_b32_e32 v115, v82
	s_nop 0
	v_addc_co_u32_e32 v15, vcc, 0, v11, vcc
	v_add_co_u32_e32 v22, vcc, s28, v16
	v_mov_b32_e32 v116, v82
	s_nop 0
	v_addc_co_u32_e32 v23, vcc, 0, v17, vcc
	v_add_co_u32_e32 v34, vcc, s12, v16
	global_load_dwordx4 v[10:13], v[14:15], off offset:128
	global_load_dwordx4 v[18:21], v[22:23], off offset:128
	v_addc_co_u32_e32 v35, vcc, 0, v17, vcc
	v_add_co_u32_e32 v36, vcc, s29, v16
	v_mov_b32_e32 v117, v82
	s_nop 0
	v_addc_co_u32_e32 v37, vcc, 0, v17, vcc
	global_load_dwordx4 v[22:25], v[34:35], off offset:128
	global_load_dwordx4 v[26:29], v[36:37], off offset:128
	global_load_dwordx4 v[14:17], v238, s[0:1] offset:128
	global_load_dwordx4 v[30:33], v238, s[6:7] offset:128
	v_mov_b32_e32 v118, v82
	v_mov_b32_e32 v119, v82
	v_mov_b32_e32 v120, v82
	v_mov_b32_e32 v121, v82
	v_mov_b32_e32 v122, v82
	v_mov_b32_e32 v123, v82
	v_mov_b32_e32 v124, v82
	v_mov_b32_e32 v125, v82
	v_mov_b32_e32 v126, v82
	v_mov_b32_e32 v127, v82
	v_mov_b32_e32 v128, v82
	v_mov_b32_e32 v129, v82
	v_mov_b32_e32 v130, v82
	v_mov_b32_e32 v131, v82
	v_mov_b32_e32 v132, v82
	v_mov_b32_e32 v133, v82
	v_mov_b32_e32 v134, v82
	v_mov_b32_e32 v135, v82
	v_mov_b32_e32 v136, v82
	v_mov_b32_e32 v137, v82
	v_mov_b32_e32 v138, v82
	v_mov_b32_e32 v139, v82
	v_mov_b32_e32 v140, v82
	v_mov_b32_e32 v141, v82
	v_mov_b32_e32 v142, v82
	v_mov_b32_e32 v143, v82
	v_mov_b32_e32 v144, v82
	v_mov_b32_e32 v145, v82
	v_mov_b32_e32 v146, v82
	v_mov_b32_e32 v147, v82
	v_mov_b32_e32 v148, v82
	v_mov_b32_e32 v149, v82
	v_mov_b32_e32 v150, v82
	v_mov_b32_e32 v151, v82
	v_mov_b32_e32 v152, v82
	v_mov_b32_e32 v153, v82
	v_mov_b32_e32 v154, v82
	v_mov_b32_e32 v155, v82
	v_mov_b32_e32 v156, v82
	v_mov_b32_e32 v157, v82
	v_mov_b32_e32 v158, v82
	v_mov_b32_e32 v159, v82
	v_mov_b32_e32 v160, v82
	v_mov_b32_e32 v161, v82
	v_mov_b32_e32 v98, v82
	v_mov_b32_e32 v99, v82
	v_mov_b32_e32 v100, v82
	v_mov_b32_e32 v101, v82
	v_mov_b32_e32 v94, v82
	v_mov_b32_e32 v95, v82
	v_mov_b32_e32 v96, v82
	v_mov_b32_e32 v97, v82
	v_mov_b32_e32 v90, v82
	v_mov_b32_e32 v91, v82
	v_mov_b32_e32 v92, v82
	v_mov_b32_e32 v93, v82
	v_mov_b32_e32 v86, v82
	v_mov_b32_e32 v87, v82
	v_mov_b32_e32 v88, v82
	v_mov_b32_e32 v89, v82
	v_mov_b32_e32 v78, v82
	v_mov_b32_e32 v79, v82
	v_mov_b32_e32 v80, v82
	v_mov_b32_e32 v81, v82
	v_mov_b32_e32 v74, v82
	v_mov_b32_e32 v75, v82
	v_mov_b32_e32 v76, v82
	v_mov_b32_e32 v77, v82
	v_mov_b32_e32 v70, v82
	v_mov_b32_e32 v71, v82
	v_mov_b32_e32 v72, v82
	v_mov_b32_e32 v73, v82
	v_mov_b32_e32 v66, v82
	v_mov_b32_e32 v67, v82
	v_mov_b32_e32 v68, v82
	v_mov_b32_e32 v69, v82
	v_mov_b32_e32 v62, v82
	v_mov_b32_e32 v63, v82
	v_mov_b32_e32 v64, v82
	v_mov_b32_e32 v65, v82
	v_mov_b32_e32 v58, v82
	v_mov_b32_e32 v59, v82
	v_mov_b32_e32 v60, v82
	v_mov_b32_e32 v61, v82
	v_mov_b32_e32 v54, v82
	v_mov_b32_e32 v55, v82
	v_mov_b32_e32 v56, v82
	v_mov_b32_e32 v57, v82
	v_mov_b32_e32 v50, v82
	v_mov_b32_e32 v51, v82
	v_mov_b32_e32 v52, v82
	v_mov_b32_e32 v53, v82
	v_mov_b32_e32 v46, v82
	v_mov_b32_e32 v47, v82
	v_mov_b32_e32 v48, v82
	v_mov_b32_e32 v49, v82
	v_mov_b32_e32 v42, v82
	v_mov_b32_e32 v43, v82
	v_mov_b32_e32 v44, v82
	v_mov_b32_e32 v45, v82
	v_mov_b32_e32 v38, v82
	v_mov_b32_e32 v39, v82
	v_mov_b32_e32 v40, v82
	v_mov_b32_e32 v41, v82
	v_mov_b32_e32 v34, v82
	v_mov_b32_e32 v35, v82
	v_mov_b32_e32 v36, v82
	v_mov_b32_e32 v37, v82
	s_waitcnt lgkmcnt(0)
	s_barrier
	s_branch .LBB0_2545

.LBB0_2545:
	s_add_i32 s0, s30, -1
	ds_read_b128 v[174:177], v255
	ds_read_b128 v[166:169], v255 offset:4096
	ds_read_b128 v[170:173], v254
	ds_read_b128 v[162:165], v254 offset:4096
	ds_read_b128 v[190:193], v253
	ds_read_b128 v[178:181], v252
	ds_read_b128 v[182:185], v252 offset:4096
	s_setprio 1
	s_waitcnt lgkmcnt(1)
	v_mfma_f32_16x16x32_bf16 v[158:161], v[174:177], v[178:181], v[158:161]
	s_cmp_lt_i32 s0, s33
	s_cselect_b64 s[14:15], -1, 0
	s_cmp_ge_i32 s0, s33
	v_mfma_f32_16x16x32_bf16 v[154:157], v[170:173], v[178:181], v[154:157]
	v_mfma_f32_16x16x32_bf16 v[150:153], v[166:169], v[178:181], v[150:153]
	v_mfma_f32_16x16x32_bf16 v[146:149], v[162:165], v[178:181], v[146:149]
	ds_read_b128 v[186:189], v253 offset:4096
	ds_read_b128 v[178:181], v252 offset:8192
	v_mfma_f32_16x16x32_bf16 v[142:145], v[174:177], v[190:193], v[142:145]
	v_mfma_f32_16x16x32_bf16 v[138:141], v[170:173], v[190:193], v[138:141]
	v_mfma_f32_16x16x32_bf16 v[134:137], v[166:169], v[190:193], v[134:137]
	v_mfma_f32_16x16x32_bf16 v[130:133], v[162:165], v[190:193], v[130:133]
	s_cbranch_scc1 .LBB0_2547
	s_waitcnt vmcnt(0)
	ds_write_b128 v245, v[30:33]
	ds_write_b128 v245, v[26:29] offset:8192
.LBB0_2547:
	s_lshl_b32 s0, s41, 8
	s_mul_i32 s12, s41, 0xb0000
	s_mul_hi_i32 s13, s0, 0xb00
	s_lshl_b32 s0, s18, 6
	s_ashr_i32 s1, s0, 31
	s_lshl_b64 s[6:7], s[12:13], 1
	s_add_u32 s16, s21, s6
	s_waitcnt vmcnt(2)
	s_addc_u32 s17, s22, s7
	s_lshl_b64 s[6:7], s[0:1], 1
	s_add_u32 s16, s16, s6
	s_addc_u32 s17, s17, s7
	s_waitcnt vmcnt(0)
	s_nop 0
	ds_read_b128 v[200:203], v253 offset:8192
	ds_read_b128 v[210:213], v253 offset:12288
	global_load_dwordx4 v[26:29], v246, s[16:17]
	s_waitcnt lgkmcnt(4)
	v_mfma_f32_16x16x32_bf16 v[126:129], v[174:177], v[182:185], v[126:129]
	global_load_dwordx4 v[30:33], v244, s[16:17]
	v_mfma_f32_16x16x32_bf16 v[122:125], v[170:173], v[182:185], v[122:125]
	v_mfma_f32_16x16x32_bf16 v[118:121], v[166:169], v[182:185], v[118:121]
	v_mfma_f32_16x16x32_bf16 v[114:117], v[162:165], v[182:185], v[114:117]
	s_waitcnt lgkmcnt(2)
	v_mfma_f32_16x16x32_bf16 v[182:185], v[174:177], v[178:181], v[98:101]
	s_waitcnt lgkmcnt(1)
	v_mfma_f32_16x16x32_bf16 v[98:101], v[166:169], v[200:203], v[70:73]
	s_nop 2
	ds_read_b128 v[70:73], v252 offset:12288
	v_mfma_f32_16x16x32_bf16 v[110:113], v[174:177], v[186:189], v[110:113]
	v_mfma_f32_16x16x32_bf16 v[106:109], v[170:173], v[186:189], v[106:109]
	v_mfma_f32_16x16x32_bf16 v[102:105], v[166:169], v[186:189], v[102:105]
	v_mfma_f32_16x16x32_bf16 v[82:85], v[162:165], v[186:189], v[82:85]
	v_mfma_f32_16x16x32_bf16 v[186:189], v[170:173], v[178:181], v[94:97]
	v_mfma_f32_16x16x32_bf16 v[190:193], v[166:169], v[178:181], v[90:93]
	v_mfma_f32_16x16x32_bf16 v[86:89], v[162:165], v[178:181], v[86:89]
	v_mfma_f32_16x16x32_bf16 v[90:93], v[174:177], v[200:203], v[78:81]
	v_mfma_f32_16x16x32_bf16 v[94:97], v[170:173], v[200:203], v[74:77]
	v_mfma_f32_16x16x32_bf16 v[178:181], v[162:165], v[200:203], v[66:69]
	s_nop 2
	v_cndmask_b32_e64 v67, 0, 1, s[14:15]
	v_cmp_ne_u32_e64 s[0:1], 1, v67
	s_andn2_b64 vcc, exec, s[14:15]
	s_cbranch_vccnz .LBB0_2549
	ds_write_b128 v245, v[22:25] offset:16384
	ds_write_b128 v245, v[18:21] offset:24576
.LBB0_2549:
	s_waitcnt lgkmcnt(0)
	v_mfma_f32_16x16x32_bf16 v[194:197], v[174:177], v[70:73], v[62:65]
	v_mfma_f32_16x16x32_bf16 v[198:201], v[170:173], v[70:73], v[58:61]
	s_nop 0
	global_load_dwordx4 v[18:21], v243, s[16:17]
	s_nop 0
	v_add_u32_e32 v22, 0x108000, v246
	global_load_dwordx4 v[22:25], v22, s[16:17]
	v_mfma_f32_16x16x32_bf16 v[202:205], v[166:169], v[70:73], v[54:57]
	v_mfma_f32_16x16x32_bf16 v[206:209], v[162:165], v[70:73], v[50:53]
	v_mfma_f32_16x16x32_bf16 v[174:177], v[174:177], v[210:213], v[46:49]
	v_mfma_f32_16x16x32_bf16 v[170:173], v[170:173], v[210:213], v[42:45]
	v_mfma_f32_16x16x32_bf16 v[166:169], v[166:169], v[210:213], v[38:41]
	v_mfma_f32_16x16x32_bf16 v[162:165], v[162:165], v[210:213], v[34:37]
	s_setprio 0
	s_nop 1
	s_nop 0
	ds_read_b128 v[218:221], v250
	ds_read_b128 v[214:217], v249 offset:4096
	ds_read_b128 v[210:213], v250 offset:4096
	ds_read_b128 v[222:225], v249
	ds_read_b128 v[34:37], v248
	ds_read_b128 v[38:41], v247
	ds_read_b128 v[54:57], v247 offset:4096
	s_setprio 1
	s_waitcnt lgkmcnt(1)
	v_mfma_f32_16x16x32_bf16 v[158:161], v[222:225], v[38:41], v[158:161]
	v_mfma_f32_16x16x32_bf16 v[154:157], v[218:221], v[38:41], v[154:157]
	v_mfma_f32_16x16x32_bf16 v[150:153], v[214:217], v[38:41], v[150:153]
	v_mfma_f32_16x16x32_bf16 v[146:149], v[210:213], v[38:41], v[146:149]
	v_mfma_f32_16x16x32_bf16 v[38:41], v[214:217], v[34:37], v[134:137]
	ds_read_b128 v[70:73], v248 offset:4096
	s_nop 1
	ds_read_b128 v[134:137], v247 offset:8192
	v_mfma_f32_16x16x32_bf16 v[142:145], v[222:225], v[34:37], v[142:145]
	v_mfma_f32_16x16x32_bf16 v[138:141], v[218:221], v[34:37], v[138:141]
	v_mfma_f32_16x16x32_bf16 v[34:37], v[210:213], v[34:37], v[130:133]
	s_nop 2
	s_and_b64 vcc, exec, s[0:1]
	s_cbranch_vccnz .LBB0_2551
	ds_write_b128 v245, v[14:17] offset:32768
	ds_write_b128 v245, v[10:13] offset:40960
.LBB0_2551:
	s_lshl_b32 s15, s40, 8
	s_mul_i32 s14, s40, 0xb0000
	s_mul_hi_i32 s15, s15, 0xb00
	s_lshl_b64 s[16:17], s[14:15], 1
	s_add_u32 s16, s23, s16
	s_addc_u32 s17, s24, s17
	s_add_u32 s6, s16, s6
	s_addc_u32 s7, s17, s7
	s_waitcnt lgkmcnt(2)
	v_mfma_f32_16x16x32_bf16 v[50:53], v[214:217], v[54:57], v[118:121]
	s_waitcnt lgkmcnt(1)
	v_mfma_f32_16x16x32_bf16 v[66:69], v[214:217], v[70:73], v[102:105]
	ds_read_b128 v[118:121], v247 offset:12288
	s_nop 1
	ds_read_b128 v[102:105], v248 offset:8192
	global_load_dwordx4 v[10:13], v246, s[6:7]
	s_nop 0
	global_load_dwordx4 v[14:17], v244, s[6:7]
	v_mfma_f32_16x16x32_bf16 v[58:61], v[222:225], v[70:73], v[110:113]
	v_mfma_f32_16x16x32_bf16 v[62:65], v[218:221], v[70:73], v[106:109]
	v_mfma_f32_16x16x32_bf16 v[70:73], v[210:213], v[70:73], v[82:85]
	s_waitcnt lgkmcnt(2)
	v_mfma_f32_16x16x32_bf16 v[74:77], v[222:225], v[134:137], v[182:185]
	v_mfma_f32_16x16x32_bf16 v[78:81], v[218:221], v[134:137], v[186:189]
	v_mfma_f32_16x16x32_bf16 v[82:85], v[214:217], v[134:137], v[190:193]
	v_mfma_f32_16x16x32_bf16 v[86:89], v[210:213], v[134:137], v[86:89]
	ds_read_b128 v[134:137], v248 offset:12288
	v_mfma_f32_16x16x32_bf16 v[42:45], v[222:225], v[54:57], v[126:129]
	v_mfma_f32_16x16x32_bf16 v[46:49], v[218:221], v[54:57], v[122:125]
	v_mfma_f32_16x16x32_bf16 v[54:57], v[210:213], v[54:57], v[114:117]
	s_waitcnt lgkmcnt(1)
	v_mfma_f32_16x16x32_bf16 v[90:93], v[222:225], v[102:105], v[90:93]
	v_mfma_f32_16x16x32_bf16 v[94:97], v[218:221], v[102:105], v[94:97]
	v_mfma_f32_16x16x32_bf16 v[98:101], v[214:217], v[102:105], v[98:101]
	v_mfma_f32_16x16x32_bf16 v[102:105], v[210:213], v[102:105], v[178:181]
	s_and_b64 vcc, exec, s[0:1]
	s_cbranch_vccnz .LBB0_2553
	ds_write_b128 v245, v[6:9] offset:49152
	ds_write_b128 v245, v[2:5] offset:57344
.LBB0_2553:
	v_mfma_f32_16x16x32_bf16 v[106:109], v[222:225], v[118:121], v[194:197]
	s_nop 0
	v_mfma_f32_16x16x32_bf16 v[110:113], v[218:221], v[118:121], v[198:201]
	s_nop 0
	global_load_dwordx4 v[2:5], v243, s[6:7]
	s_nop 0
	v_add_u32_e32 v6, 0x108000, v246
	global_load_dwordx4 v[6:9], v6, s[6:7]
	v_mfma_f32_16x16x32_bf16 v[114:117], v[214:217], v[118:121], v[202:205]
	v_mfma_f32_16x16x32_bf16 v[118:121], v[210:213], v[118:121], v[206:209]
	s_waitcnt lgkmcnt(0)
	v_mfma_f32_16x16x32_bf16 v[122:125], v[222:225], v[134:137], v[174:177]
	v_mfma_f32_16x16x32_bf16 v[126:129], v[218:221], v[134:137], v[170:173]
	v_mfma_f32_16x16x32_bf16 v[130:133], v[214:217], v[134:137], v[166:169]
	v_mfma_f32_16x16x32_bf16 v[134:137], v[210:213], v[134:137], v[162:165]
	s_setprio 0
	s_add_i32 s43, s18, 1
	s_cmp_lg_u32 s43, 44
	s_cbranch_scc1 .LBB0_2557
	s_add_i32 s20, s20, s11
	s_cmp_gt_i32 s20, 31
	s_cbranch_scc1 .LBB0_2556
	s_ashr_i32 s1, s20, 31
	s_lshr_b32 s1, s1, 27
	s_add_i32 s1, s20, s1
	s_ashr_i32 s1, s1, 5
	s_mov_b32 s0, s10
	s_lshl_b32 s6, s1, 6
	s_lshl_b32 s7, s20, 1
	s_sub_i32 s6, s7, s6
	s_and_b32 s0, s0, 7
	s_and_b32 s6, s6, -8
	s_lshl_b32 s1, s1, 2
	s_and_b32 s7, s20, 3
	s_or_b32 s41, s0, s6
	s_or_b32 s40, s1, s7
	s_lshl_b32 s0, s41, 8
	s_mul_hi_i32 s13, s0, 0xb00
	s_lshl_b32 s0, s40, 8
	s_mul_i32 s12, s41, 0xb0000
	s_mul_i32 s14, s40, 0xb0000
	s_mul_hi_i32 s15, s0, 0xb00

.LBB0_2557:
	s_barrier
	s_nop 0
	v_add_u32_e32 v170, 0x10000, v255
	v_add_u32_e32 v162, 0x11000, v255
	v_add_u32_e32 v171, 0x10000, v254
	ds_read_b128 v[206:209], v170
	ds_read_b128 v[210:213], v171
	v_add_u32_e32 v169, 0x11000, v254
	ds_read_b128 v[214:217], v162
	ds_read_b128 v[218:221], v169
	v_add_u32_e32 v186, 0x10000, v253
	v_add_u32_e32 v187, 0x10000, v252
	ds_read_b128 v[162:165], v186
	ds_read_b128 v[166:169], v187
	ds_read_b128 v[174:177], v187 offset:4096
	s_setprio 1
	ds_read_b128 v[182:185], v186 offset:4096
	ds_read_b128 v[178:181], v187 offset:8192
	s_waitcnt lgkmcnt(3)
	v_mfma_f32_16x16x32_bf16 v[158:161], v[206:209], v[166:169], v[158:161]
	s_cmp_lt_i32 s30, s33
	s_cselect_b64 s[16:17], -1, 0
	s_cmp_ge_i32 s30, s33
	v_mfma_f32_16x16x32_bf16 v[154:157], v[210:213], v[166:169], v[154:157]
	s_cselect_b64 s[6:7], -1, 0
	v_mfma_f32_16x16x32_bf16 v[150:153], v[214:217], v[166:169], v[150:153]
	v_mfma_f32_16x16x32_bf16 v[146:149], v[218:221], v[166:169], v[146:149]
	v_mfma_f32_16x16x32_bf16 v[142:145], v[206:209], v[162:165], v[142:145]
	v_mfma_f32_16x16x32_bf16 v[138:141], v[210:213], v[162:165], v[138:141]
	v_mfma_f32_16x16x32_bf16 v[38:41], v[214:217], v[162:165], v[38:41]
	v_mfma_f32_16x16x32_bf16 v[34:37], v[218:221], v[162:165], v[34:37]
	s_and_b64 vcc, exec, s[6:7]
	s_cbranch_vccnz .LBB0_2559
	s_waitcnt vmcnt(7)
	ds_write_b128 v251, v[26:29]
	s_waitcnt vmcnt(6)
	ds_write_b128 v251, v[30:33] offset:8192
.LBB0_2559:
	s_lshl_b32 s0, s43, 6
	s_ashr_i32 s1, s0, 31
	s_lshl_b64 s[12:13], s[12:13], 1
	s_add_u32 s18, s21, s12
	s_waitcnt vmcnt(7)
	s_addc_u32 s19, s22, s13
	s_lshl_b64 s[12:13], s[0:1], 1
	s_add_u32 s18, s18, s12
	s_addc_u32 s19, s19, s13
	s_waitcnt lgkmcnt(2)
	v_mfma_f32_16x16x32_bf16 v[170:173], v[214:217], v[174:177], v[50:53]
	ds_read_b128 v[190:193], v186 offset:8192
	s_waitcnt lgkmcnt(1)
	v_mfma_f32_16x16x32_bf16 v[50:53], v[214:217], v[178:181], v[82:85]
	s_nop 2
	ds_read_b128 v[82:85], v187 offset:12288
	global_load_dwordx4 v[30:33], v246, s[18:19]
	s_nop 0
	global_load_dwordx4 v[26:29], v244, s[18:19]
	v_mfma_f32_16x16x32_bf16 v[166:169], v[210:213], v[174:177], v[46:49]
	v_mfma_f32_16x16x32_bf16 v[46:49], v[210:213], v[178:181], v[78:81]
	s_nop 2
	ds_read_b128 v[78:81], v186 offset:12288
	v_mfma_f32_16x16x32_bf16 v[162:165], v[206:209], v[174:177], v[42:45]
	v_mfma_f32_16x16x32_bf16 v[174:177], v[218:221], v[174:177], v[54:57]
	v_mfma_f32_16x16x32_bf16 v[58:61], v[206:209], v[182:185], v[58:61]
	v_mfma_f32_16x16x32_bf16 v[62:65], v[210:213], v[182:185], v[62:65]
	v_mfma_f32_16x16x32_bf16 v[66:69], v[214:217], v[182:185], v[66:69]
	v_mfma_f32_16x16x32_bf16 v[70:73], v[218:221], v[182:185], v[70:73]
	v_mfma_f32_16x16x32_bf16 v[42:45], v[206:209], v[178:181], v[74:77]
	v_mfma_f32_16x16x32_bf16 v[54:57], v[218:221], v[178:181], v[86:89]
	s_waitcnt lgkmcnt(2)
	v_mfma_f32_16x16x32_bf16 v[74:77], v[206:209], v[190:193], v[90:93]
	v_mfma_f32_16x16x32_bf16 v[178:181], v[210:213], v[190:193], v[94:97]
	v_mfma_f32_16x16x32_bf16 v[182:185], v[214:217], v[190:193], v[98:101]
	v_mfma_f32_16x16x32_bf16 v[186:189], v[218:221], v[190:193], v[102:105]
	v_cndmask_b32_e64 v87, 0, 1, s[16:17]
	v_cmp_ne_u32_e64 s[0:1], 1, v87
	s_andn2_b64 vcc, exec, s[16:17]
	s_cbranch_vccnz .LBB0_2561
	s_waitcnt vmcnt(7)
	ds_write_b128 v251, v[18:21] offset:16384
	s_waitcnt vmcnt(6)
	ds_write_b128 v251, v[22:25] offset:24576
.LBB0_2561:
	s_waitcnt vmcnt(7)
	s_waitcnt lgkmcnt(1)
	v_mfma_f32_16x16x32_bf16 v[190:193], v[206:209], v[82:85], v[106:109]
	v_mfma_f32_16x16x32_bf16 v[194:197], v[210:213], v[82:85], v[110:113]
	s_nop 0
	global_load_dwordx4 v[22:25], v243, s[18:19]
	s_nop 0
	v_add_u32_e32 v18, 0x108000, v246
	global_load_dwordx4 v[18:21], v18, s[18:19]
	v_mfma_f32_16x16x32_bf16 v[198:201], v[214:217], v[82:85], v[114:117]
	v_mfma_f32_16x16x32_bf16 v[202:205], v[218:221], v[82:85], v[118:121]
	s_waitcnt lgkmcnt(0)
	v_mfma_f32_16x16x32_bf16 v[206:209], v[206:209], v[78:81], v[122:125]
	v_mfma_f32_16x16x32_bf16 v[210:213], v[210:213], v[78:81], v[126:129]
	v_mfma_f32_16x16x32_bf16 v[214:217], v[214:217], v[78:81], v[130:133]
	v_mfma_f32_16x16x32_bf16 v[218:221], v[218:221], v[78:81], v[134:137]
	s_setprio 0
	s_nop 0
	v_add_u32_e32 v81, 0x10000, v249
	v_add_u32_e32 v78, 0x11000, v249
	v_add_u32_e32 v85, 0x10000, v250
	ds_read_b128 v[234:237], v81
	ds_read_b128 v[226:229], v85
	v_add_u32_e32 v80, 0x11000, v250
	ds_read_b128 v[230:233], v78
	ds_read_b128 v[222:225], v80
	v_add_u32_e32 v242, 0x10000, v248
	v_add_u32_e32 v90, 0x10000, v247
	ds_read_b128 v[86:89], v242
	ds_read_b128 v[82:85], v90
	ds_read_b128 v[78:81], v90 offset:4096
	s_setprio 1
	s_waitcnt lgkmcnt(1)
	v_mfma_f32_16x16x32_bf16 v[158:161], v[234:237], v[82:85], v[158:161]
	v_mfma_f32_16x16x32_bf16 v[154:157], v[226:229], v[82:85], v[154:157]
	v_mfma_f32_16x16x32_bf16 v[150:153], v[230:233], v[82:85], v[150:153]
	v_mfma_f32_16x16x32_bf16 v[146:149], v[222:225], v[82:85], v[146:149]
	v_mfma_f32_16x16x32_bf16 v[134:137], v[230:233], v[86:89], v[38:41]
	ds_read_b128 v[82:85], v242 offset:4096
	s_nop 1
	ds_read_b128 v[38:41], v90 offset:8192
	v_mfma_f32_16x16x32_bf16 v[142:145], v[234:237], v[86:89], v[142:145]
	v_mfma_f32_16x16x32_bf16 v[138:141], v[226:229], v[86:89], v[138:141]
	v_mfma_f32_16x16x32_bf16 v[130:133], v[222:225], v[86:89], v[34:37]
	s_nop 2
	s_and_b64 vcc, exec, s[0:1]
	s_cbranch_vccnz .LBB0_2563
	s_waitcnt vmcnt(7)
	ds_write_b128 v251, v[10:13] offset:32768
	s_waitcnt vmcnt(6)
	ds_write_b128 v251, v[14:17] offset:40960
.LBB0_2563:
	s_lshl_b64 s[14:15], s[14:15], 1
	s_add_u32 s14, s23, s14
	s_waitcnt vmcnt(7)
	s_addc_u32 s15, s24, s15
	s_add_u32 s12, s14, s12
	s_addc_u32 s13, s15, s13
	global_load_dwordx4 v[14:17], v246, s[12:13]
	s_nop 0
	global_load_dwordx4 v[10:13], v244, s[12:13]
	s_waitcnt lgkmcnt(0)
	v_mfma_f32_16x16x32_bf16 v[98:101], v[234:237], v[38:41], v[42:45]
	ds_read_b128 v[34:37], v242 offset:12288
	s_nop 1
	ds_read_b128 v[42:45], v242 offset:8192
	v_mfma_f32_16x16x32_bf16 v[94:97], v[226:229], v[38:41], v[46:49]
	v_mfma_f32_16x16x32_bf16 v[90:93], v[230:233], v[38:41], v[50:53]
	v_mfma_f32_16x16x32_bf16 v[86:89], v[222:225], v[38:41], v[54:57]
	v_add_u32_e32 v38, 0x13000, v247
	ds_read_b128 v[38:41], v38
	v_mfma_f32_16x16x32_bf16 v[126:129], v[234:237], v[78:81], v[162:165]
	v_mfma_f32_16x16x32_bf16 v[122:125], v[226:229], v[78:81], v[166:169]
	v_mfma_f32_16x16x32_bf16 v[118:121], v[230:233], v[78:81], v[170:173]
	v_mfma_f32_16x16x32_bf16 v[114:117], v[222:225], v[78:81], v[174:177]
	v_mfma_f32_16x16x32_bf16 v[110:113], v[234:237], v[82:85], v[58:61]
	v_mfma_f32_16x16x32_bf16 v[106:109], v[226:229], v[82:85], v[62:65]
	v_mfma_f32_16x16x32_bf16 v[102:105], v[230:233], v[82:85], v[66:69]
	v_mfma_f32_16x16x32_bf16 v[82:85], v[222:225], v[82:85], v[70:73]
	s_waitcnt lgkmcnt(1)
	v_mfma_f32_16x16x32_bf16 v[78:81], v[234:237], v[42:45], v[74:77]
	v_mfma_f32_16x16x32_bf16 v[74:77], v[226:229], v[42:45], v[178:181]
	v_mfma_f32_16x16x32_bf16 v[70:73], v[230:233], v[42:45], v[182:185]
	v_mfma_f32_16x16x32_bf16 v[66:69], v[222:225], v[42:45], v[186:189]
	v_mov_b32_e32 v42, v0
	s_and_b64 vcc, exec, s[0:1]
	s_cbranch_vccnz .LBB0_2565
	s_waitcnt vmcnt(7)
	ds_write_b128 v251, v[2:5] offset:49152
	s_waitcnt vmcnt(6)
	ds_write_b128 v251, v[6:9] offset:57344
.LBB0_2565:
	s_waitcnt vmcnt(7)
	v_lshrrev_b32_e32 v2, 3, v42
	v_mul_lo_u32 v2, v2, s26
	v_lshlrev_b32_e32 v3, 3, v42
	v_and_or_b32 v2, v3, 56, v2
	v_lshlrev_b32_e32 v238, 1, v2
	s_waitcnt lgkmcnt(0)
	v_mfma_f32_16x16x32_bf16 v[62:65], v[234:237], v[38:41], v[190:193]
	v_mfma_f32_16x16x32_bf16 v[58:61], v[226:229], v[38:41], v[194:197]
	s_nop 0
	global_load_dwordx4 v[6:9], v243, s[12:13]
	s_nop 0
	v_add_u32_e32 v2, 0x108000, v246
	global_load_dwordx4 v[2:5], v2, s[12:13]
	v_mfma_f32_16x16x32_bf16 v[54:57], v[230:233], v[38:41], v[198:201]
	v_mfma_f32_16x16x32_bf16 v[50:53], v[222:225], v[38:41], v[202:205]
	v_mfma_f32_16x16x32_bf16 v[46:49], v[234:237], v[34:37], v[206:209]
	v_mfma_f32_16x16x32_bf16 v[42:45], v[226:229], v[34:37], v[210:213]
	v_mfma_f32_16x16x32_bf16 v[38:41], v[230:233], v[34:37], v[214:217]
	v_mfma_f32_16x16x32_bf16 v[34:37], v[222:225], v[34:37], v[218:221]
	s_setprio 0
	s_add_i32 s18, s43, 1
	s_cmp_lg_u32 s18, 44
	s_cbranch_scc1 .LBB0_2569
	s_add_i32 s20, s20, s11
	s_cmp_gt_i32 s20, 31
	s_cbranch_scc1 .LBB0_2568
	s_ashr_i32 s1, s20, 31
	s_lshr_b32 s1, s1, 27
	s_add_i32 s1, s20, s1
	s_ashr_i32 s1, s1, 5
	s_mov_b32 s0, s10
	s_lshl_b32 s12, s1, 6
	s_lshl_b32 s13, s20, 1
	s_sub_i32 s12, s13, s12
	s_and_b32 s0, s0, 7
	s_and_b32 s12, s12, -8
	s_lshl_b32 s1, s1, 2
	s_and_b32 s13, s20, 3
	s_or_b32 s40, s1, s13
	s_or_b32 s41, s0, s12

	.amdhsa_kernel _Z10mk_forward6Paramsii
		.amdhsa_group_segment_fixed_size 135168
		.amdhsa_private_segment_fixed_size 0
		.amdhsa_kernarg_size 480
		.amdhsa_user_sgpr_count 2
		.amdhsa_user_sgpr_dispatch_ptr 0
		.amdhsa_user_sgpr_queue_ptr 0
		.amdhsa_user_sgpr_kernarg_segment_ptr 1
		.amdhsa_user_sgpr_dispatch_id 0
		.amdhsa_user_sgpr_kernarg_preload_length 0
		.amdhsa_user_sgpr_kernarg_preload_offset 0
		.amdhsa_user_sgpr_private_segment_size 0
		.amdhsa_uses_dynamic_stack 0
		.amdhsa_enable_private_segment 0
		.amdhsa_system_sgpr_workgroup_id_x 1
		.amdhsa_system_sgpr_workgroup_id_y 0
		.amdhsa_system_sgpr_workgroup_id_z 0
		.amdhsa_system_sgpr_workgroup_info 0
		.amdhsa_system_vgpr_workitem_id 0
		.amdhsa_next_free_vgpr 256
		.amdhsa_next_free_sgpr 98
		.amdhsa_accum_offset 256
		.amdhsa_reserve_vcc 1
		.amdhsa_float_round_mode_32 0
		.amdhsa_float_round_mode_16_64 0
		.amdhsa_float_denorm_mode_32 3
		.amdhsa_float_denorm_mode_16_64 3
		.amdhsa_dx10_clamp 1
		.amdhsa_ieee_mode 1
		.amdhsa_fp16_overflow 0
		.amdhsa_tg_split 0
		.amdhsa_exception_fp_ieee_invalid_op 0
		.amdhsa_exception_fp_denorm_src 0
		.amdhsa_exception_fp_ieee_div_zero 0
		.amdhsa_exception_fp_ieee_overflow 0
		.amdhsa_exception_fp_ieee_underflow 0
		.amdhsa_exception_fp_ieee_inexact 0
		.amdhsa_exception_int_div_zero 0
	.end_amdhsa_kernel

amdhsa.kernels:
  - .agpr_count:     0
    .args:
      - .offset:         0
        .size:           216
        .value_kind:     by_value
      - .offset:         216
        .size:           4
        .value_kind:     by_value
      - .offset:         220
        .size:           4
        .value_kind:     by_value
      - .offset:         224
        .size:           4
        .value_kind:     hidden_block_count_x
      - .offset:         228
        .size:           4
        .value_kind:     hidden_block_count_y
      - .offset:         232
        .size:           4
        .value_kind:     hidden_block_count_z
      - .offset:         236
        .size:           2
        .value_kind:     hidden_group_size_x
      - .offset:         238
        .size:           2
        .value_kind:     hidden_group_size_y
      - .offset:         240
        .size:           2
        .value_kind:     hidden_group_size_z
      - .offset:         242
        .size:           2
        .value_kind:     hidden_remainder_x
      - .offset:         244
        .size:           2
        .value_kind:     hidden_remainder_y
      - .offset:         246
        .size:           2
        .value_kind:     hidden_remainder_z
      - .offset:         264
        .size:           8
        .value_kind:     hidden_global_offset_x
      - .offset:         272
        .size:           8
        .value_kind:     hidden_global_offset_y
      - .offset:         280
        .size:           8
        .value_kind:     hidden_global_offset_z
      - .offset:         288
        .size:           2
        .value_kind:     hidden_grid_dims
    .group_segment_fixed_size: 135168
    .kernarg_segment_align: 8
    .kernarg_segment_size: 480
    .language:       OpenCL C
    .language_version:
      - 2
      - 0
    .max_flat_workgroup_size: 512
    .name:           _Z10mk_forward6Paramsii
    .private_segment_fixed_size: 0
    .sgpr_count:     104
    .sgpr_spill_count: 0
    .symbol:         _Z10mk_forward6Paramsii.kd
    .uniform_work_group_size: 1
    .uses_dynamic_stack: false
    .vgpr_count:     256
    .vgpr_spill_count: 0
    .wavefront_size: 64
